# + m18 back-edge rotation: K-loop scalar pointer/counter updates + exit compare moved in front of the last load segment's waits; LDS fragment reads issued before the scalar address selects in the loop
# speedup vs baseline: 1.0140x; 1.0003x over previous
; #define PG8_STAGE(bufoff, gbase, voff) do { _Pragma("unroll") for (int _i = 0; _i < 2; ++_i) \
;         __builtin_amdgcn_global_load_lds((const unsigned*)((const char*)(gbase) + (voff)[_i]), (PG8_LAS unsigned*)(lds + (bufoff) + ldsw + _i * 8192), 16, 0, 0); } while (0)
; #define PG8_LDA(dst, b, h) do { _Pragma("unroll") for (int m = 0; m < 4; ++m) _Pragma("unroll") for (int k = 0; k < 2; ++k) dst[m][k] = *(const PG8_LAS bf16x8*)(lds + PG8_SA(b, h) + aoff + m * 2048 + k * 1024); } while (0)
; #define PG8_LDB(dst, b, h) do { _Pragma("unroll") for (int n = 0; n < 2; ++n) _Pragma("unroll") for (int k = 0; k < 2; ++k) dst[n][k] = *(const PG8_LAS bf16x8*)(lds + PG8_SB(b, h) + boff + n * 2048 + k * 1024); } while (0)
; #define PG8_MMA(ai, bj, At, Bt) do { __builtin_amdgcn_s_setprio(1); _Pragma("unroll") for (int m = 0; m < 4; ++m) _Pragma("unroll") for (int n = 0; n < 2; ++n) _Pragma("unroll") for (int k = 0; k < 2; ++k) \
;         acc[ai][bj][m][n] = __builtin_amdgcn_mfma_f32_16x16x32_bf16(Bt[n][k], At[m][k], acc[ai][bj][m][n], 0, 0, 0); __builtin_amdgcn_s_setprio(0); } while (0)
; #define PG8_WAIT_V(n) asm volatile("s_waitcnt vmcnt(" #n ")" ::: "memory")
; #define PG8_WAIT_L(n) asm volatile("s_waitcnt lgkmcnt(" #n ")" ::: "memory")
; #define PG8_BAR __builtin_amdgcn_s_barrier()
; #define PG8_SCHED __builtin_amdgcn_sched_barrier(0)
; template <class Epi, class Sched, bool ALIGN_EPI = false, bool SP2 = false>
; __device__ __forceinline__ void gemm_phase(PG8_LAS unsigned char* lds, const Gemm g, const Sched& S, const Epi& E, const int tid) {
;     ...
;             const bool last = (t == nt - 2);
;             const char* a1 = cA + (size_t)(t + 1) * kstep;
;             const char* a2 = last ? nA : cA + (size_t)(t + 2) * kstep; const char* b2 = last ? nB : cB + (size_t)(t + 2) * kstep;
;             const char* a3 = a2 + kstep; const char* b3 = b2 + kstep;
;             if (last && has_next) S.a_ready(nxt);
;             if constexpr (SP2) {
;             PG8_LDB(B0, 0, 0); PG8_LDB(B1, 0, 1); PG8_SCHED; PG8_LDA(At, 0, 0); PG8_STAGE(PG8_SA(1, 1), a1 + hstep, voffA);
;             PG8_WAIT_V(8); PG8_WAIT_L(0); PG8_BAR; PG8_MMA(0, 0, At, B0); PG8_MMA(0, 1, At, B1); PG8_BAR; PG8_SCHED;
;             PG8_LDA(At, 0, 1); PG8_STAGE(PG8_SB(0, 0), b2, voffB); PG8_STAGE(PG8_SB(0, 1), b2 + hstep, voffB); PG8_STAGE(PG8_SA(0, 0), a2, voffA);
.LBB0_38:
	v_add_u32_e32 v138, 0x10000, v140
	ds_read_b128 v[142:145], v138
	ds_read_b128 v[146:149], v138 offset:1024
	ds_read_b128 v[150:153], v138 offset:2048
	ds_read_b128 v[154:157], v138 offset:3072
	v_add_u32_e32 v138, 0x14000, v140
	ds_read_b128 v[158:161], v138
	ds_read_b128 v[162:165], v138 offset:1024
	ds_read_b128 v[166:169], v138 offset:2048
	ds_read_b128 v[170:173], v138 offset:3072
	s_add_u32 s58, s44, 0xfffc0080
	s_addc_u32 s59, s45, -1
	s_add_i32 s73, 0, 0x10000
	s_cmp_eq_u32 s72, 12
	s_cselect_b32 s79, s17, s59
	s_cselect_b32 s78, s60, s58
	s_cselect_b32 s59, s15, s71
	s_cselect_b32 s58, s70, s62
	s_add_i32 s76, 0, 0x14000
	v_lshl_add_u64 v[138:139], s[44:45], 0, v[134:135]
	s_add_i32 m0, s38, 0xc000
	ds_read_b128 v[174:177], v141
	ds_read_b128 v[178:181], v141 offset:1024
	ds_read_b128 v[182:185], v141 offset:2048
	ds_read_b128 v[186:189], v141 offset:3072
	ds_read_b128 v[212:215], v141 offset:4096
	ds_read_b128 v[216:219], v141 offset:5120
	ds_read_b128 v[232:235], v141 offset:6144
	ds_read_b128 v[236:239], v141 offset:7168
	global_load_lds_dwordx4 v[138:139], off
	v_lshl_add_u64 v[138:139], s[44:45], 0, v[136:137]
	s_add_i32 m0, s38, 0xe000
	s_nop 0
	global_load_lds_dwordx4 v[138:139], off
	s_waitcnt vmcnt(8)
	s_waitcnt lgkmcnt(0)
	s_barrier
	s_setprio 1
	s_waitcnt lgkmcnt(0)
	v_mfma_f32_16x16x32_bf16 v[124:127], v[142:145], v[174:177], v[124:127]
	v_mfma_f32_16x16x32_bf16 v[120:123], v[150:153], v[174:177], v[120:123]
	v_mfma_f32_16x16x32_bf16 v[108:111], v[142:145], v[182:185], v[108:111]
	v_mfma_f32_16x16x32_bf16 v[104:107], v[150:153], v[182:185], v[104:107]
	v_mfma_f32_16x16x32_bf16 v[92:95], v[142:145], v[212:215], v[92:95]
	v_mfma_f32_16x16x32_bf16 v[88:91], v[150:153], v[212:215], v[88:91]
	v_mfma_f32_16x16x32_bf16 v[76:79], v[142:145], v[232:235], v[76:79]
	v_mfma_f32_16x16x32_bf16 v[72:75], v[150:153], v[232:235], v[72:75]
	v_mfma_f32_16x16x32_bf16 v[124:127], v[146:149], v[178:181], v[124:127]
	v_mfma_f32_16x16x32_bf16 v[120:123], v[154:157], v[178:181], v[120:123]
	v_mfma_f32_16x16x32_bf16 v[108:111], v[146:149], v[186:189], v[108:111]
	v_mfma_f32_16x16x32_bf16 v[104:107], v[154:157], v[186:189], v[104:107]
	v_mfma_f32_16x16x32_bf16 v[92:95], v[146:149], v[216:219], v[92:95]
	v_mfma_f32_16x16x32_bf16 v[88:91], v[154:157], v[216:219], v[88:91]
	v_mfma_f32_16x16x32_bf16 v[76:79], v[146:149], v[236:239], v[76:79]
	v_mfma_f32_16x16x32_bf16 v[72:75], v[154:157], v[236:239], v[72:75]
	s_setprio 0
	s_setprio 1
	v_mfma_f32_16x16x32_bf16 v[116:119], v[158:161], v[174:177], v[116:119]
	v_mfma_f32_16x16x32_bf16 v[112:115], v[166:169], v[174:177], v[112:115]
	v_mfma_f32_16x16x32_bf16 v[100:103], v[158:161], v[182:185], v[100:103]
	v_mfma_f32_16x16x32_bf16 v[96:99], v[166:169], v[182:185], v[96:99]
	v_mfma_f32_16x16x32_bf16 v[84:87], v[158:161], v[212:215], v[84:87]
	v_mfma_f32_16x16x32_bf16 v[80:83], v[166:169], v[212:215], v[80:83]
	v_mfma_f32_16x16x32_bf16 v[68:71], v[158:161], v[232:235], v[68:71]
	v_mfma_f32_16x16x32_bf16 v[64:67], v[166:169], v[232:235], v[64:67]
	v_mfma_f32_16x16x32_bf16 v[116:119], v[162:165], v[178:181], v[116:119]
	v_mfma_f32_16x16x32_bf16 v[112:115], v[170:173], v[178:181], v[112:115]
	v_mfma_f32_16x16x32_bf16 v[100:103], v[162:165], v[186:189], v[100:103]
	v_mfma_f32_16x16x32_bf16 v[96:99], v[170:173], v[186:189], v[96:99]
	v_mfma_f32_16x16x32_bf16 v[84:87], v[162:165], v[216:219], v[84:87]
	v_mfma_f32_16x16x32_bf16 v[80:83], v[170:173], v[216:219], v[80:83]
	v_mfma_f32_16x16x32_bf16 v[68:71], v[162:165], v[236:239], v[68:71]
	v_mfma_f32_16x16x32_bf16 v[64:67], v[170:173], v[236:239], v[64:67]
	s_setprio 0
	s_barrier
	s_add_i32 s73, s73, s35
	v_lshl_add_u64 v[138:139], s[58:59], 0, v[192:193]
	s_mov_b32 m0, s73
	ds_read_b128 v[174:177], v141 offset:16384
	ds_read_b128 v[178:181], v141 offset:17408
	ds_read_b128 v[182:185], v141 offset:18432
	ds_read_b128 v[186:189], v141 offset:19456
	ds_read_b128 v[212:215], v141 offset:20480
	ds_read_b128 v[216:219], v141 offset:21504
	ds_read_b128 v[232:235], v141 offset:22528
	ds_read_b128 v[236:239], v141 offset:23552
	global_load_lds_dwordx4 v[138:139], off
	s_add_i32 m0, s73, 0x2000
	s_add_u32 s74, s58, 0x40000
	v_lshl_add_u64 v[190:191], s[58:59], 0, v[132:133]
	s_addc_u32 s75, s59, 0
	s_add_i32 s73, s76, s35
	global_load_lds_dwordx4 v[190:191], off
	v_lshl_add_u64 v[194:195], s[74:75], 0, v[192:193]
	s_mov_b32 m0, s73
	v_lshl_add_u64 v[196:197], s[78:79], 0, v[130:131]
	global_load_lds_dwordx4 v[194:195], off
	v_lshl_add_u64 v[194:195], s[74:75], 0, v[132:133]
	s_add_i32 m0, s73, 0x2000
	s_nop 0
	global_load_lds_dwordx4 v[194:195], off
	v_lshl_add_u64 v[194:195], s[78:79], 0, v[128:129]
	s_mov_b32 m0, s38
	s_nop 0
	global_load_lds_dwordx4 v[194:195], off
	s_mov_b32 m0, s40
	s_nop 0
	global_load_lds_dwordx4 v[196:197], off
	s_waitcnt vmcnt(8)
	s_waitcnt lgkmcnt(0)
	s_barrier
; #define PG8_STAGE(bufoff, gbase, voff) do { _Pragma("unroll") for (int _i = 0; _i < 2; ++_i) \
;         __builtin_amdgcn_global_load_lds((const unsigned*)((const char*)(gbase) + (voff)[_i]), (PG8_LAS unsigned*)(lds + (bufoff) + ldsw + _i * 8192), 16, 0, 0); } while (0)
; #define PG8_LDA(dst, b, h) do { _Pragma("unroll") for (int m = 0; m < 4; ++m) _Pragma("unroll") for (int k = 0; k < 2; ++k) dst[m][k] = *(const PG8_LAS bf16x8*)(lds + PG8_SA(b, h) + aoff + m * 2048 + k * 1024); } while (0)
; #define PG8_LDB(dst, b, h) do { _Pragma("unroll") for (int n = 0; n < 2; ++n) _Pragma("unroll") for (int k = 0; k < 2; ++k) dst[n][k] = *(const PG8_LAS bf16x8*)(lds + PG8_SB(b, h) + boff + n * 2048 + k * 1024); } while (0)
; #define PG8_MMA(ai, bj, At, Bt) do { __builtin_amdgcn_s_setprio(1); _Pragma("unroll") for (int m = 0; m < 4; ++m) _Pragma("unroll") for (int n = 0; n < 2; ++n) _Pragma("unroll") for (int k = 0; k < 2; ++k) \
;         acc[ai][bj][m][n] = __builtin_amdgcn_mfma_f32_16x16x32_bf16(Bt[n][k], At[m][k], acc[ai][bj][m][n], 0, 0, 0); __builtin_amdgcn_s_setprio(0); } while (0)
; #define PG8_WAIT_V(n) asm volatile("s_waitcnt vmcnt(" #n ")" ::: "memory")
; #define PG8_WAIT_L(n) asm volatile("s_waitcnt lgkmcnt(" #n ")" ::: "memory")
; #define PG8_BAR __builtin_amdgcn_s_barrier()
; #define PG8_SCHED __builtin_amdgcn_sched_barrier(0)
; template <class Epi, class Sched, bool ALIGN_EPI = false, bool SP2 = false>
; __device__ __forceinline__ void gemm_phase(PG8_LAS unsigned char* lds, const Gemm g, const Sched& S, const Epi& E, const int tid) {
;     ...
;             PG8_WAIT_V(8); PG8_WAIT_L(0); PG8_BAR; PG8_MMA(1, 0, At, B0); PG8_MMA(1, 1, At, B1); PG8_BAR; PG8_SCHED;
;             PG8_LDB(B0, 1, 0); PG8_LDB(B1, 1, 1); PG8_SCHED; PG8_LDA(At, 1, 0); PG8_STAGE(PG8_SA(0, 1), a2 + hstep, voffA);
;             PG8_WAIT_V(8); PG8_WAIT_L(0); PG8_BAR; PG8_MMA(0, 0, At, B0); PG8_MMA(0, 1, At, B1); PG8_BAR; PG8_SCHED;
	s_setprio 1
	s_waitcnt lgkmcnt(0)
	v_mfma_f32_16x16x32_bf16 v[60:63], v[142:145], v[174:177], v[60:63]
	v_mfma_f32_16x16x32_bf16 v[56:59], v[150:153], v[174:177], v[56:59]
	v_mfma_f32_16x16x32_bf16 v[44:47], v[142:145], v[182:185], v[44:47]
	v_mfma_f32_16x16x32_bf16 v[40:43], v[150:153], v[182:185], v[40:43]
	v_mfma_f32_16x16x32_bf16 v[28:31], v[142:145], v[212:215], v[28:31]
	v_mfma_f32_16x16x32_bf16 v[24:27], v[150:153], v[212:215], v[24:27]
	v_mfma_f32_16x16x32_bf16 v[12:15], v[142:145], v[232:235], v[12:15]
	v_mfma_f32_16x16x32_bf16 v[8:11], v[150:153], v[232:235], v[8:11]
	v_mfma_f32_16x16x32_bf16 v[60:63], v[146:149], v[178:181], v[60:63]
	v_mfma_f32_16x16x32_bf16 v[56:59], v[154:157], v[178:181], v[56:59]
	v_mfma_f32_16x16x32_bf16 v[44:47], v[146:149], v[186:189], v[44:47]
	v_mfma_f32_16x16x32_bf16 v[40:43], v[154:157], v[186:189], v[40:43]
	v_mfma_f32_16x16x32_bf16 v[28:31], v[146:149], v[216:219], v[28:31]
	v_mfma_f32_16x16x32_bf16 v[24:27], v[154:157], v[216:219], v[24:27]
	v_mfma_f32_16x16x32_bf16 v[12:15], v[146:149], v[236:239], v[12:15]
	v_mfma_f32_16x16x32_bf16 v[8:11], v[154:157], v[236:239], v[8:11]
	s_setprio 0
	s_setprio 1
	v_mfma_f32_16x16x32_bf16 v[52:55], v[158:161], v[174:177], v[52:55]
	v_mfma_f32_16x16x32_bf16 v[48:51], v[166:169], v[174:177], v[48:51]
	v_mfma_f32_16x16x32_bf16 v[36:39], v[158:161], v[182:185], v[36:39]
	v_mfma_f32_16x16x32_bf16 v[32:35], v[166:169], v[182:185], v[32:35]
	v_mfma_f32_16x16x32_bf16 v[20:23], v[158:161], v[212:215], v[20:23]
	v_mfma_f32_16x16x32_bf16 v[16:19], v[166:169], v[212:215], v[16:19]
	v_mfma_f32_16x16x32_bf16 v[4:7], v[158:161], v[232:235], v[4:7]
	v_mfma_f32_16x16x32_bf16 v[0:3], v[166:169], v[232:235], v[0:3]
	v_mfma_f32_16x16x32_bf16 v[52:55], v[162:165], v[178:181], v[52:55]
	v_mfma_f32_16x16x32_bf16 v[48:51], v[170:173], v[178:181], v[48:51]
	v_mfma_f32_16x16x32_bf16 v[36:39], v[162:165], v[186:189], v[36:39]
	v_mfma_f32_16x16x32_bf16 v[32:35], v[170:173], v[186:189], v[32:35]
	v_mfma_f32_16x16x32_bf16 v[20:23], v[162:165], v[216:219], v[20:23]
	v_mfma_f32_16x16x32_bf16 v[16:19], v[170:173], v[216:219], v[16:19]
	v_mfma_f32_16x16x32_bf16 v[4:7], v[162:165], v[236:239], v[4:7]
	v_mfma_f32_16x16x32_bf16 v[0:3], v[170:173], v[236:239], v[0:3]
	s_setprio 0
	s_barrier
	s_add_i32 s73, 0, 0x18000
	s_add_i32 s76, 0, 0x1c000
	v_add_u32_e32 v154, s73, v140
	v_add_u32_e32 v170, s76, v140
	ds_read_b128 v[142:145], v154
	ds_read_b128 v[146:149], v154 offset:1024
	ds_read_b128 v[150:153], v154 offset:2048
	ds_read_b128 v[154:157], v154 offset:3072
	ds_read_b128 v[158:161], v170
	ds_read_b128 v[162:165], v170 offset:1024
	ds_read_b128 v[166:169], v170 offset:2048
	ds_read_b128 v[170:173], v170 offset:3072
	s_add_u32 s74, s78, 0x40000
	s_addc_u32 s75, s79, 0
	s_mov_b32 m0, s41
	v_lshl_add_u64 v[202:203], s[74:75], 0, v[128:129]
	ds_read_b128 v[174:177], v141 offset:32768
	ds_read_b128 v[178:181], v141 offset:33792
	ds_read_b128 v[182:185], v141 offset:34816
	ds_read_b128 v[186:189], v141 offset:35840
	ds_read_b128 v[212:215], v141 offset:36864
	ds_read_b128 v[216:219], v141 offset:37888
	ds_read_b128 v[232:235], v141 offset:38912
	ds_read_b128 v[236:239], v141 offset:39936
	global_load_lds_dwordx4 v[202:203], off
	v_lshl_add_u64 v[202:203], s[74:75], 0, v[130:131]
	s_mov_b32 m0, s46
	s_nop 0
	global_load_lds_dwordx4 v[202:203], off
	s_waitcnt vmcnt(8)
	s_waitcnt lgkmcnt(0)
	s_barrier
	s_setprio 1
	s_waitcnt lgkmcnt(0)
	v_mfma_f32_16x16x32_bf16 v[124:127], v[142:145], v[174:177], v[124:127]
	v_mfma_f32_16x16x32_bf16 v[120:123], v[150:153], v[174:177], v[120:123]
	v_mfma_f32_16x16x32_bf16 v[108:111], v[142:145], v[182:185], v[108:111]
	v_mfma_f32_16x16x32_bf16 v[104:107], v[150:153], v[182:185], v[104:107]
	v_mfma_f32_16x16x32_bf16 v[92:95], v[142:145], v[212:215], v[92:95]
	v_mfma_f32_16x16x32_bf16 v[88:91], v[150:153], v[212:215], v[88:91]
	v_mfma_f32_16x16x32_bf16 v[76:79], v[142:145], v[232:235], v[76:79]
	v_mfma_f32_16x16x32_bf16 v[72:75], v[150:153], v[232:235], v[72:75]
	v_mfma_f32_16x16x32_bf16 v[124:127], v[146:149], v[178:181], v[124:127]
	v_mfma_f32_16x16x32_bf16 v[120:123], v[154:157], v[178:181], v[120:123]
	v_mfma_f32_16x16x32_bf16 v[108:111], v[146:149], v[186:189], v[108:111]
	v_mfma_f32_16x16x32_bf16 v[104:107], v[154:157], v[186:189], v[104:107]
	v_mfma_f32_16x16x32_bf16 v[92:95], v[146:149], v[216:219], v[92:95]
	v_mfma_f32_16x16x32_bf16 v[88:91], v[154:157], v[216:219], v[88:91]
	v_mfma_f32_16x16x32_bf16 v[76:79], v[146:149], v[236:239], v[76:79]
	v_mfma_f32_16x16x32_bf16 v[72:75], v[154:157], v[236:239], v[72:75]
	s_setprio 0
	s_setprio 1
	v_mfma_f32_16x16x32_bf16 v[116:119], v[158:161], v[174:177], v[116:119]
	v_mfma_f32_16x16x32_bf16 v[112:115], v[166:169], v[174:177], v[112:115]
	v_mfma_f32_16x16x32_bf16 v[100:103], v[158:161], v[182:185], v[100:103]
	v_mfma_f32_16x16x32_bf16 v[96:99], v[166:169], v[182:185], v[96:99]
	v_mfma_f32_16x16x32_bf16 v[84:87], v[158:161], v[212:215], v[84:87]
	v_mfma_f32_16x16x32_bf16 v[80:83], v[166:169], v[212:215], v[80:83]
	v_mfma_f32_16x16x32_bf16 v[68:71], v[158:161], v[232:235], v[68:71]
	v_mfma_f32_16x16x32_bf16 v[64:67], v[166:169], v[232:235], v[64:67]
	v_mfma_f32_16x16x32_bf16 v[116:119], v[162:165], v[178:181], v[116:119]
	v_mfma_f32_16x16x32_bf16 v[112:115], v[170:173], v[178:181], v[112:115]
	v_mfma_f32_16x16x32_bf16 v[100:103], v[162:165], v[186:189], v[100:103]
	v_mfma_f32_16x16x32_bf16 v[96:99], v[170:173], v[186:189], v[96:99]
	v_mfma_f32_16x16x32_bf16 v[84:87], v[162:165], v[216:219], v[84:87]
	v_mfma_f32_16x16x32_bf16 v[80:83], v[170:173], v[216:219], v[80:83]
	v_mfma_f32_16x16x32_bf16 v[68:71], v[162:165], v[236:239], v[68:71]
	v_mfma_f32_16x16x32_bf16 v[64:67], v[170:173], v[236:239], v[64:67]
	s_setprio 0
	s_barrier
; #define PG8_STAGE(bufoff, gbase, voff) do { _Pragma("unroll") for (int _i = 0; _i < 2; ++_i) \
;         __builtin_amdgcn_global_load_lds((const unsigned*)((const char*)(gbase) + (voff)[_i]), (PG8_LAS unsigned*)(lds + (bufoff) + ldsw + _i * 8192), 16, 0, 0); } while (0)
; #define PG8_LDA(dst, b, h) do { _Pragma("unroll") for (int m = 0; m < 4; ++m) _Pragma("unroll") for (int k = 0; k < 2; ++k) dst[m][k] = *(const PG8_LAS bf16x8*)(lds + PG8_SA(b, h) + aoff + m * 2048 + k * 1024); } while (0)
; #define PG8_MMA(ai, bj, At, Bt) do { __builtin_amdgcn_s_setprio(1); _Pragma("unroll") for (int m = 0; m < 4; ++m) _Pragma("unroll") for (int n = 0; n < 2; ++n) _Pragma("unroll") for (int k = 0; k < 2; ++k) \
;         acc[ai][bj][m][n] = __builtin_amdgcn_mfma_f32_16x16x32_bf16(Bt[n][k], At[m][k], acc[ai][bj][m][n], 0, 0, 0); __builtin_amdgcn_s_setprio(0); } while (0)
; #define PG8_WAIT_V(n) asm volatile("s_waitcnt vmcnt(" #n ")" ::: "memory")
; #define PG8_WAIT_L(n) asm volatile("s_waitcnt lgkmcnt(" #n ")" ::: "memory")
; #define PG8_BAR __builtin_amdgcn_s_barrier()
; #define PG8_SCHED __builtin_amdgcn_sched_barrier(0)
; template <class Epi, class Sched, bool ALIGN_EPI = false, bool SP2 = false>
; __device__ __forceinline__ void gemm_phase(PG8_LAS unsigned char* lds, const Gemm g, const Sched& S, const Epi& E, const int tid) {
;     ...
;         for (int t = 0; t < nt; t += 2) {
;     ...
;             PG8_LDA(At, 1, 1); PG8_STAGE(PG8_SB(1, 0), b3, voffB); PG8_STAGE(PG8_SB(1, 1), b3 + hstep, voffB); PG8_STAGE(PG8_SA(1, 0), a3, voffA);
;             PG8_WAIT_V(8); PG8_WAIT_L(0); PG8_BAR; PG8_MMA(1, 0, At, B0); PG8_MMA(1, 1, At, B1); PG8_BAR; PG8_SCHED;
	s_add_i32 s73, s73, s35
	v_lshl_add_u64 v[138:139], v[138:139], 0, s[36:37]
	s_mov_b32 m0, s73
	ds_read_b128 v[174:177], v141 offset:49152
	ds_read_b128 v[178:181], v141 offset:50176
	ds_read_b128 v[182:185], v141 offset:51200
	ds_read_b128 v[186:189], v141 offset:52224
	ds_read_b128 v[212:215], v141 offset:53248
	ds_read_b128 v[216:219], v141 offset:54272
	ds_read_b128 v[232:235], v141 offset:55296
	ds_read_b128 v[236:239], v141 offset:56320
	global_load_lds_dwordx4 v[138:139], off
	s_add_i32 m0, s73, 0x2000
	s_add_u32 s58, s58, 0x40080
	v_lshl_add_u64 v[138:139], v[190:191], 0, s[36:37]
	s_addc_u32 s59, s59, 0
	s_add_i32 s73, s76, s35
	global_load_lds_dwordx4 v[138:139], off
	v_lshl_add_u64 v[138:139], s[58:59], 0, v[192:193]
	s_mov_b32 m0, s73
	s_nop 0
	global_load_lds_dwordx4 v[138:139], off
	v_lshl_add_u64 v[138:139], s[58:59], 0, v[132:133]
	s_add_i32 m0, s73, 0x2000
	s_nop 0
	global_load_lds_dwordx4 v[138:139], off
	v_lshl_add_u64 v[138:139], v[194:195], 0, s[36:37]
	s_mov_b32 m0, s47
	s_nop 0
	global_load_lds_dwordx4 v[138:139], off
	v_lshl_add_u64 v[138:139], v[196:197], 0, s[36:37]
	s_mov_b32 m0, s53
	s_nop 0
	global_load_lds_dwordx4 v[138:139], off
	s_add_i32 s72, s72, 2
	s_add_u32 s44, s44, 0x100
	s_addc_u32 s45, s45, 0
	s_add_u32 s62, s62, 0x100
	s_addc_u32 s71, s71, 0
	s_cmp_gt_u32 s72, 13
	s_waitcnt vmcnt(8)
	s_waitcnt lgkmcnt(0)
	s_barrier
	s_setprio 1
	s_waitcnt lgkmcnt(0)
	v_mfma_f32_16x16x32_bf16 v[60:63], v[142:145], v[174:177], v[60:63]
	v_mfma_f32_16x16x32_bf16 v[56:59], v[150:153], v[174:177], v[56:59]
	v_mfma_f32_16x16x32_bf16 v[44:47], v[142:145], v[182:185], v[44:47]
	v_mfma_f32_16x16x32_bf16 v[40:43], v[150:153], v[182:185], v[40:43]
	v_mfma_f32_16x16x32_bf16 v[28:31], v[142:145], v[212:215], v[28:31]
	v_mfma_f32_16x16x32_bf16 v[24:27], v[150:153], v[212:215], v[24:27]
	v_mfma_f32_16x16x32_bf16 v[12:15], v[142:145], v[232:235], v[12:15]
	v_mfma_f32_16x16x32_bf16 v[8:11], v[150:153], v[232:235], v[8:11]
	v_mfma_f32_16x16x32_bf16 v[60:63], v[146:149], v[178:181], v[60:63]
	v_mfma_f32_16x16x32_bf16 v[56:59], v[154:157], v[178:181], v[56:59]
	v_mfma_f32_16x16x32_bf16 v[44:47], v[146:149], v[186:189], v[44:47]
	v_mfma_f32_16x16x32_bf16 v[40:43], v[154:157], v[186:189], v[40:43]
	v_mfma_f32_16x16x32_bf16 v[28:31], v[146:149], v[216:219], v[28:31]
	v_mfma_f32_16x16x32_bf16 v[24:27], v[154:157], v[216:219], v[24:27]
	v_mfma_f32_16x16x32_bf16 v[12:15], v[146:149], v[236:239], v[12:15]
	v_mfma_f32_16x16x32_bf16 v[8:11], v[154:157], v[236:239], v[8:11]
	s_setprio 0
	s_setprio 1
	v_mfma_f32_16x16x32_bf16 v[52:55], v[158:161], v[174:177], v[52:55]
	v_mfma_f32_16x16x32_bf16 v[48:51], v[166:169], v[174:177], v[48:51]
	v_mfma_f32_16x16x32_bf16 v[36:39], v[158:161], v[182:185], v[36:39]
	v_mfma_f32_16x16x32_bf16 v[32:35], v[166:169], v[182:185], v[32:35]
	v_mfma_f32_16x16x32_bf16 v[20:23], v[158:161], v[212:215], v[20:23]
	v_mfma_f32_16x16x32_bf16 v[16:19], v[166:169], v[212:215], v[16:19]
	v_mfma_f32_16x16x32_bf16 v[4:7], v[158:161], v[232:235], v[4:7]
	v_mfma_f32_16x16x32_bf16 v[0:3], v[166:169], v[232:235], v[0:3]
	v_mfma_f32_16x16x32_bf16 v[52:55], v[162:165], v[178:181], v[52:55]
	v_mfma_f32_16x16x32_bf16 v[48:51], v[170:173], v[178:181], v[48:51]
	v_mfma_f32_16x16x32_bf16 v[36:39], v[162:165], v[186:189], v[36:39]
	v_mfma_f32_16x16x32_bf16 v[32:35], v[170:173], v[186:189], v[32:35]
	v_mfma_f32_16x16x32_bf16 v[20:23], v[162:165], v[216:219], v[20:23]
	v_mfma_f32_16x16x32_bf16 v[16:19], v[170:173], v[216:219], v[16:19]
	v_mfma_f32_16x16x32_bf16 v[4:7], v[162:165], v[236:239], v[4:7]
	v_mfma_f32_16x16x32_bf16 v[0:3], v[170:173], v[236:239], v[0:3]
	s_setprio 0
	s_barrier
	s_cbranch_scc0 .LBB0_38
	s_and_b64 vcc, exec, s[10:11]
	s_mov_b64 s[72:73], 0x20000
	s_cbranch_vccz .LBB0_41
	s_barrier

; #define PG8_STAGE(bufoff, gbase, voff) do { _Pragma("unroll") for (int _i = 0; _i < 2; ++_i) \
;         __builtin_amdgcn_global_load_lds((const unsigned*)((const char*)(gbase) + (voff)[_i]), (PG8_LAS unsigned*)(lds + (bufoff) + ldsw + _i * 8192), 16, 0, 0); } while (0)
; #define PG8_LDA(dst, b, h) do { _Pragma("unroll") for (int m = 0; m < 4; ++m) _Pragma("unroll") for (int k = 0; k < 2; ++k) dst[m][k] = *(const PG8_LAS bf16x8*)(lds + PG8_SA(b, h) + aoff + m * 2048 + k * 1024); } while (0)
; #define PG8_LDB(dst, b, h) do { _Pragma("unroll") for (int n = 0; n < 2; ++n) _Pragma("unroll") for (int k = 0; k < 2; ++k) dst[n][k] = *(const PG8_LAS bf16x8*)(lds + PG8_SB(b, h) + boff + n * 2048 + k * 1024); } while (0)
; #define PG8_MMA(ai, bj, At, Bt) do { __builtin_amdgcn_s_setprio(1); _Pragma("unroll") for (int m = 0; m < 4; ++m) _Pragma("unroll") for (int n = 0; n < 2; ++n) _Pragma("unroll") for (int k = 0; k < 2; ++k) \
;         acc[ai][bj][m][n] = __builtin_amdgcn_mfma_f32_16x16x32_bf16(Bt[n][k], At[m][k], acc[ai][bj][m][n], 0, 0, 0); __builtin_amdgcn_s_setprio(0); } while (0)
; #define PG8_WAIT_V(n) asm volatile("s_waitcnt vmcnt(" #n ")" ::: "memory")
; #define PG8_WAIT_L(n) asm volatile("s_waitcnt lgkmcnt(" #n ")" ::: "memory")
; #define PG8_BAR __builtin_amdgcn_s_barrier()
; #define PG8_SCHED __builtin_amdgcn_sched_barrier(0)
; template <class Epi, class Sched, bool ALIGN_EPI = false, bool SP2 = false>
; __device__ __forceinline__ void gemm_phase(PG8_LAS unsigned char* lds, const Gemm g, const Sched& S, const Epi& E, const int tid) {
;     ...
;             const bool last = (t == nt - 2);
;             const char* a1 = cA + (size_t)(t + 1) * kstep;
;             const char* a2 = last ? nA : cA + (size_t)(t + 2) * kstep; const char* b2 = last ? nB : cB + (size_t)(t + 2) * kstep;
;             const char* a3 = a2 + kstep; const char* b3 = b2 + kstep;
;             if (last && has_next) S.a_ready(nxt);
;             if constexpr (SP2) {
;             PG8_LDB(B0, 0, 0); PG8_LDB(B1, 0, 1); PG8_SCHED; PG8_LDA(At, 0, 0); PG8_STAGE(PG8_SA(1, 1), a1 + hstep, voffA);
;             PG8_WAIT_V(8); PG8_WAIT_L(0); PG8_BAR; PG8_MMA(0, 0, At, B0); PG8_MMA(0, 1, At, B1); PG8_BAR; PG8_SCHED;
;             PG8_LDA(At, 0, 1); PG8_STAGE(PG8_SB(0, 0), b2, voffB); PG8_STAGE(PG8_SB(0, 1), b2 + hstep, voffB); PG8_STAGE(PG8_SA(0, 0), a2, voffA);
.LBB0_99:
	v_add_u32_e32 v152, 0x10000, v138
	v_add_u32_e32 v168, 0x14000, v138
	ds_read_b128 v[140:143], v152
	ds_read_b128 v[144:147], v152 offset:1024
	ds_read_b128 v[148:151], v152 offset:2048
	ds_read_b128 v[152:155], v152 offset:3072
	ds_read_b128 v[156:159], v168
	ds_read_b128 v[160:163], v168 offset:1024
	ds_read_b128 v[164:167], v168 offset:2048
	ds_read_b128 v[168:171], v168 offset:3072
	s_add_u32 s20, s18, 0x100
	s_addc_u32 s21, s19, 0
	s_add_i32 s73, 0, 0x10000
	s_cmp_eq_u32 s72, 40
	s_cselect_b32 s45, s9, s21
	s_cselect_b32 s44, s8, s20
	s_cselect_b32 s23, s17, s71
	s_cselect_b32 s22, s16, s62
	s_add_i32 s74, 0, 0x14000
	v_lshl_add_u64 v[194:195], s[18:19], 0, v[134:135]
	s_add_i32 m0, s38, 0xc000
	ds_read_b128 v[172:175], v139
	ds_read_b128 v[176:179], v139 offset:1024
	ds_read_b128 v[180:183], v139 offset:2048
	ds_read_b128 v[184:187], v139 offset:3072
	ds_read_b128 v[188:191], v139 offset:4096
	ds_read_b128 v[212:215], v139 offset:5120
	ds_read_b128 v[216:219], v139 offset:6144
	ds_read_b128 v[232:235], v139 offset:7168
	global_load_lds_dwordx4 v[194:195], off
	v_lshl_add_u64 v[194:195], s[18:19], 0, v[136:137]
	s_add_i32 m0, s38, 0xe000
	s_nop 0
	global_load_lds_dwordx4 v[194:195], off
	s_waitcnt vmcnt(8)
	s_waitcnt lgkmcnt(0)
	s_barrier
	s_setprio 1
	s_waitcnt lgkmcnt(0)
	v_mfma_f32_16x16x32_bf16 v[124:127], v[140:143], v[172:175], v[124:127]
	v_mfma_f32_16x16x32_bf16 v[120:123], v[148:151], v[172:175], v[120:123]
	v_mfma_f32_16x16x32_bf16 v[116:119], v[140:143], v[180:183], v[116:119]
	v_mfma_f32_16x16x32_bf16 v[112:115], v[148:151], v[180:183], v[112:115]
	v_mfma_f32_16x16x32_bf16 v[100:103], v[140:143], v[188:191], v[100:103]
	v_mfma_f32_16x16x32_bf16 v[96:99], v[148:151], v[188:191], v[96:99]
	v_mfma_f32_16x16x32_bf16 v[84:87], v[140:143], v[216:219], v[84:87]
	v_mfma_f32_16x16x32_bf16 v[80:83], v[148:151], v[216:219], v[80:83]
	v_mfma_f32_16x16x32_bf16 v[124:127], v[144:147], v[176:179], v[124:127]
	v_mfma_f32_16x16x32_bf16 v[120:123], v[152:155], v[176:179], v[120:123]
	v_mfma_f32_16x16x32_bf16 v[116:119], v[144:147], v[184:187], v[116:119]
	v_mfma_f32_16x16x32_bf16 v[112:115], v[152:155], v[184:187], v[112:115]
	v_mfma_f32_16x16x32_bf16 v[100:103], v[144:147], v[212:215], v[100:103]
	v_mfma_f32_16x16x32_bf16 v[96:99], v[152:155], v[212:215], v[96:99]
	v_mfma_f32_16x16x32_bf16 v[84:87], v[144:147], v[232:235], v[84:87]
	v_mfma_f32_16x16x32_bf16 v[80:83], v[152:155], v[232:235], v[80:83]
	s_setprio 0
	s_setprio 1
	v_mfma_f32_16x16x32_bf16 v[108:111], v[156:159], v[172:175], v[108:111]
	v_mfma_f32_16x16x32_bf16 v[104:107], v[164:167], v[172:175], v[104:107]
	v_mfma_f32_16x16x32_bf16 v[92:95], v[156:159], v[180:183], v[92:95]
	v_mfma_f32_16x16x32_bf16 v[88:91], v[164:167], v[180:183], v[88:91]
	v_mfma_f32_16x16x32_bf16 v[76:79], v[156:159], v[188:191], v[76:79]
	v_mfma_f32_16x16x32_bf16 v[72:75], v[164:167], v[188:191], v[72:75]
	v_mfma_f32_16x16x32_bf16 v[68:71], v[156:159], v[216:219], v[68:71]
	v_mfma_f32_16x16x32_bf16 v[64:67], v[164:167], v[216:219], v[64:67]
	v_mfma_f32_16x16x32_bf16 v[108:111], v[160:163], v[176:179], v[108:111]
	v_mfma_f32_16x16x32_bf16 v[104:107], v[168:171], v[176:179], v[104:107]
	v_mfma_f32_16x16x32_bf16 v[92:95], v[160:163], v[184:187], v[92:95]
	v_mfma_f32_16x16x32_bf16 v[88:91], v[168:171], v[184:187], v[88:91]
	v_mfma_f32_16x16x32_bf16 v[76:79], v[160:163], v[212:215], v[76:79]
	v_mfma_f32_16x16x32_bf16 v[72:75], v[168:171], v[212:215], v[72:75]
	v_mfma_f32_16x16x32_bf16 v[68:71], v[160:163], v[232:235], v[68:71]
	v_mfma_f32_16x16x32_bf16 v[64:67], v[168:171], v[232:235], v[64:67]
	s_setprio 0
	s_barrier
	s_add_i32 s18, s73, s35
	v_lshl_add_u64 v[194:195], s[22:23], 0, v[192:193]
	s_mov_b32 m0, s18
	ds_read_b128 v[172:175], v139 offset:16384
	ds_read_b128 v[176:179], v139 offset:17408
	ds_read_b128 v[180:183], v139 offset:18432
	ds_read_b128 v[184:187], v139 offset:19456
	ds_read_b128 v[188:191], v139 offset:20480
	ds_read_b128 v[212:215], v139 offset:21504
	ds_read_b128 v[216:219], v139 offset:22528
	ds_read_b128 v[232:235], v139 offset:23552
	global_load_lds_dwordx4 v[194:195], off
	s_add_i32 m0, s18, 0x2000
	s_add_u32 s18, s22, 0xb0000
	v_lshl_add_u64 v[196:197], s[22:23], 0, v[132:133]
	s_addc_u32 s19, s23, 0
	s_add_i32 s73, s74, s35
	global_load_lds_dwordx4 v[196:197], off
	v_lshl_add_u64 v[202:203], s[18:19], 0, v[192:193]
	s_mov_b32 m0, s73
	v_lshl_add_u64 v[204:205], s[44:45], 0, v[130:131]
	global_load_lds_dwordx4 v[202:203], off
	v_lshl_add_u64 v[202:203], s[18:19], 0, v[132:133]
	s_add_i32 m0, s73, 0x2000
	s_nop 0
	global_load_lds_dwordx4 v[202:203], off
	v_lshl_add_u64 v[202:203], s[44:45], 0, v[128:129]
	s_mov_b32 m0, s38
	s_nop 0
	global_load_lds_dwordx4 v[202:203], off
	s_mov_b32 m0, s40
	s_nop 0
	global_load_lds_dwordx4 v[204:205], off
	s_waitcnt vmcnt(8)
	s_waitcnt lgkmcnt(0)
	s_barrier
; #define PG8_STAGE(bufoff, gbase, voff) do { _Pragma("unroll") for (int _i = 0; _i < 2; ++_i) \
;         __builtin_amdgcn_global_load_lds((const unsigned*)((const char*)(gbase) + (voff)[_i]), (PG8_LAS unsigned*)(lds + (bufoff) + ldsw + _i * 8192), 16, 0, 0); } while (0)
; #define PG8_LDA(dst, b, h) do { _Pragma("unroll") for (int m = 0; m < 4; ++m) _Pragma("unroll") for (int k = 0; k < 2; ++k) dst[m][k] = *(const PG8_LAS bf16x8*)(lds + PG8_SA(b, h) + aoff + m * 2048 + k * 1024); } while (0)
; #define PG8_LDB(dst, b, h) do { _Pragma("unroll") for (int n = 0; n < 2; ++n) _Pragma("unroll") for (int k = 0; k < 2; ++k) dst[n][k] = *(const PG8_LAS bf16x8*)(lds + PG8_SB(b, h) + boff + n * 2048 + k * 1024); } while (0)
; #define PG8_MMA(ai, bj, At, Bt) do { __builtin_amdgcn_s_setprio(1); _Pragma("unroll") for (int m = 0; m < 4; ++m) _Pragma("unroll") for (int n = 0; n < 2; ++n) _Pragma("unroll") for (int k = 0; k < 2; ++k) \
;         acc[ai][bj][m][n] = __builtin_amdgcn_mfma_f32_16x16x32_bf16(Bt[n][k], At[m][k], acc[ai][bj][m][n], 0, 0, 0); __builtin_amdgcn_s_setprio(0); } while (0)
; #define PG8_WAIT_V(n) asm volatile("s_waitcnt vmcnt(" #n ")" ::: "memory")
; #define PG8_WAIT_L(n) asm volatile("s_waitcnt lgkmcnt(" #n ")" ::: "memory")
; #define PG8_BAR __builtin_amdgcn_s_barrier()
; #define PG8_SCHED __builtin_amdgcn_sched_barrier(0)
; template <class Epi, class Sched, bool ALIGN_EPI = false, bool SP2 = false>
; __device__ __forceinline__ void gemm_phase(PG8_LAS unsigned char* lds, const Gemm g, const Sched& S, const Epi& E, const int tid) {
;     ...
;             PG8_WAIT_V(8); PG8_WAIT_L(0); PG8_BAR; PG8_MMA(1, 0, At, B0); PG8_MMA(1, 1, At, B1); PG8_BAR; PG8_SCHED;
;             PG8_LDB(B0, 1, 0); PG8_LDB(B1, 1, 1); PG8_SCHED; PG8_LDA(At, 1, 0); PG8_STAGE(PG8_SA(0, 1), a2 + hstep, voffA);
;             PG8_WAIT_V(8); PG8_WAIT_L(0); PG8_BAR; PG8_MMA(0, 0, At, B0); PG8_MMA(0, 1, At, B1); PG8_BAR; PG8_SCHED;
	s_setprio 1
	s_waitcnt lgkmcnt(0)
	v_mfma_f32_16x16x32_bf16 v[60:63], v[140:143], v[172:175], v[60:63]
	v_mfma_f32_16x16x32_bf16 v[56:59], v[148:151], v[172:175], v[56:59]
	v_mfma_f32_16x16x32_bf16 v[52:55], v[140:143], v[180:183], v[52:55]
	v_mfma_f32_16x16x32_bf16 v[48:51], v[148:151], v[180:183], v[48:51]
	v_mfma_f32_16x16x32_bf16 v[36:39], v[140:143], v[188:191], v[36:39]
	v_mfma_f32_16x16x32_bf16 v[32:35], v[148:151], v[188:191], v[32:35]
	v_mfma_f32_16x16x32_bf16 v[20:23], v[140:143], v[216:219], v[20:23]
	v_mfma_f32_16x16x32_bf16 v[16:19], v[148:151], v[216:219], v[16:19]
	v_mfma_f32_16x16x32_bf16 v[60:63], v[144:147], v[176:179], v[60:63]
	v_mfma_f32_16x16x32_bf16 v[56:59], v[152:155], v[176:179], v[56:59]
	v_mfma_f32_16x16x32_bf16 v[52:55], v[144:147], v[184:187], v[52:55]
	v_mfma_f32_16x16x32_bf16 v[48:51], v[152:155], v[184:187], v[48:51]
	v_mfma_f32_16x16x32_bf16 v[36:39], v[144:147], v[212:215], v[36:39]
	v_mfma_f32_16x16x32_bf16 v[32:35], v[152:155], v[212:215], v[32:35]
	v_mfma_f32_16x16x32_bf16 v[20:23], v[144:147], v[232:235], v[20:23]
	v_mfma_f32_16x16x32_bf16 v[16:19], v[152:155], v[232:235], v[16:19]
	s_setprio 0
	s_setprio 1
	v_mfma_f32_16x16x32_bf16 v[44:47], v[156:159], v[172:175], v[44:47]
	v_mfma_f32_16x16x32_bf16 v[40:43], v[164:167], v[172:175], v[40:43]
	v_mfma_f32_16x16x32_bf16 v[28:31], v[156:159], v[180:183], v[28:31]
	v_mfma_f32_16x16x32_bf16 v[24:27], v[164:167], v[180:183], v[24:27]
	v_mfma_f32_16x16x32_bf16 v[12:15], v[156:159], v[188:191], v[12:15]
	v_mfma_f32_16x16x32_bf16 v[8:11], v[164:167], v[188:191], v[8:11]
	v_mfma_f32_16x16x32_bf16 v[4:7], v[156:159], v[216:219], v[4:7]
	v_mfma_f32_16x16x32_bf16 v[0:3], v[164:167], v[216:219], v[0:3]
	v_mfma_f32_16x16x32_bf16 v[44:47], v[160:163], v[176:179], v[44:47]
	v_mfma_f32_16x16x32_bf16 v[40:43], v[168:171], v[176:179], v[40:43]
	v_mfma_f32_16x16x32_bf16 v[28:31], v[160:163], v[184:187], v[28:31]
	v_mfma_f32_16x16x32_bf16 v[24:27], v[168:171], v[184:187], v[24:27]
	v_mfma_f32_16x16x32_bf16 v[12:15], v[160:163], v[212:215], v[12:15]
	v_mfma_f32_16x16x32_bf16 v[8:11], v[168:171], v[212:215], v[8:11]
	v_mfma_f32_16x16x32_bf16 v[4:7], v[160:163], v[232:235], v[4:7]
	v_mfma_f32_16x16x32_bf16 v[0:3], v[168:171], v[232:235], v[0:3]
	s_setprio 0
	s_barrier
	s_add_i32 s73, 0, 0x18000
	s_add_i32 s74, 0, 0x1c000
	v_add_u32_e32 v152, s73, v138
	v_add_u32_e32 v168, s74, v138
	ds_read_b128 v[140:143], v152
	ds_read_b128 v[144:147], v152 offset:1024
	ds_read_b128 v[148:151], v152 offset:2048
	ds_read_b128 v[152:155], v152 offset:3072
	ds_read_b128 v[156:159], v168
	ds_read_b128 v[160:163], v168 offset:1024
	ds_read_b128 v[164:167], v168 offset:2048
	ds_read_b128 v[168:171], v168 offset:3072
	s_add_u32 s18, s44, 0xb0000
	s_addc_u32 s19, s45, 0
	s_mov_b32 m0, s41
	v_lshl_add_u64 v[206:207], s[18:19], 0, v[128:129]
	ds_read_b128 v[172:175], v139 offset:32768
	ds_read_b128 v[176:179], v139 offset:33792
	ds_read_b128 v[180:183], v139 offset:34816
	ds_read_b128 v[184:187], v139 offset:35840
	ds_read_b128 v[188:191], v139 offset:36864
	ds_read_b128 v[212:215], v139 offset:37888
	ds_read_b128 v[216:219], v139 offset:38912
	ds_read_b128 v[232:235], v139 offset:39936
	global_load_lds_dwordx4 v[206:207], off
	v_lshl_add_u64 v[206:207], s[18:19], 0, v[130:131]
	s_mov_b32 m0, s46
	s_nop 0
	global_load_lds_dwordx4 v[206:207], off
	s_waitcnt vmcnt(8)
	s_waitcnt lgkmcnt(0)
	s_barrier
	s_setprio 1
	s_waitcnt lgkmcnt(0)
	v_mfma_f32_16x16x32_bf16 v[124:127], v[140:143], v[172:175], v[124:127]
	v_mfma_f32_16x16x32_bf16 v[120:123], v[148:151], v[172:175], v[120:123]
	v_mfma_f32_16x16x32_bf16 v[116:119], v[140:143], v[180:183], v[116:119]
	v_mfma_f32_16x16x32_bf16 v[112:115], v[148:151], v[180:183], v[112:115]
	v_mfma_f32_16x16x32_bf16 v[100:103], v[140:143], v[188:191], v[100:103]
	v_mfma_f32_16x16x32_bf16 v[96:99], v[148:151], v[188:191], v[96:99]
	v_mfma_f32_16x16x32_bf16 v[84:87], v[140:143], v[216:219], v[84:87]
	v_mfma_f32_16x16x32_bf16 v[80:83], v[148:151], v[216:219], v[80:83]
	v_mfma_f32_16x16x32_bf16 v[124:127], v[144:147], v[176:179], v[124:127]
	v_mfma_f32_16x16x32_bf16 v[120:123], v[152:155], v[176:179], v[120:123]
	v_mfma_f32_16x16x32_bf16 v[116:119], v[144:147], v[184:187], v[116:119]
	v_mfma_f32_16x16x32_bf16 v[112:115], v[152:155], v[184:187], v[112:115]
	v_mfma_f32_16x16x32_bf16 v[100:103], v[144:147], v[212:215], v[100:103]
	v_mfma_f32_16x16x32_bf16 v[96:99], v[152:155], v[212:215], v[96:99]
	v_mfma_f32_16x16x32_bf16 v[84:87], v[144:147], v[232:235], v[84:87]
	v_mfma_f32_16x16x32_bf16 v[80:83], v[152:155], v[232:235], v[80:83]
	s_setprio 0
	s_setprio 1
	v_mfma_f32_16x16x32_bf16 v[108:111], v[156:159], v[172:175], v[108:111]
	v_mfma_f32_16x16x32_bf16 v[104:107], v[164:167], v[172:175], v[104:107]
	v_mfma_f32_16x16x32_bf16 v[92:95], v[156:159], v[180:183], v[92:95]
	v_mfma_f32_16x16x32_bf16 v[88:91], v[164:167], v[180:183], v[88:91]
	v_mfma_f32_16x16x32_bf16 v[76:79], v[156:159], v[188:191], v[76:79]
	v_mfma_f32_16x16x32_bf16 v[72:75], v[164:167], v[188:191], v[72:75]
	v_mfma_f32_16x16x32_bf16 v[68:71], v[156:159], v[216:219], v[68:71]
	v_mfma_f32_16x16x32_bf16 v[64:67], v[164:167], v[216:219], v[64:67]
	v_mfma_f32_16x16x32_bf16 v[108:111], v[160:163], v[176:179], v[108:111]
	v_mfma_f32_16x16x32_bf16 v[104:107], v[168:171], v[176:179], v[104:107]
	v_mfma_f32_16x16x32_bf16 v[92:95], v[160:163], v[184:187], v[92:95]
	v_mfma_f32_16x16x32_bf16 v[88:91], v[168:171], v[184:187], v[88:91]
	v_mfma_f32_16x16x32_bf16 v[76:79], v[160:163], v[212:215], v[76:79]
	v_mfma_f32_16x16x32_bf16 v[72:75], v[168:171], v[212:215], v[72:75]
	v_mfma_f32_16x16x32_bf16 v[68:71], v[160:163], v[232:235], v[68:71]
	v_mfma_f32_16x16x32_bf16 v[64:67], v[168:171], v[232:235], v[64:67]
	s_setprio 0
	s_barrier
; #define PG8_STAGE(bufoff, gbase, voff) do { _Pragma("unroll") for (int _i = 0; _i < 2; ++_i) \
;         __builtin_amdgcn_global_load_lds((const unsigned*)((const char*)(gbase) + (voff)[_i]), (PG8_LAS unsigned*)(lds + (bufoff) + ldsw + _i * 8192), 16, 0, 0); } while (0)
; #define PG8_LDA(dst, b, h) do { _Pragma("unroll") for (int m = 0; m < 4; ++m) _Pragma("unroll") for (int k = 0; k < 2; ++k) dst[m][k] = *(const PG8_LAS bf16x8*)(lds + PG8_SA(b, h) + aoff + m * 2048 + k * 1024); } while (0)
; #define PG8_MMA(ai, bj, At, Bt) do { __builtin_amdgcn_s_setprio(1); _Pragma("unroll") for (int m = 0; m < 4; ++m) _Pragma("unroll") for (int n = 0; n < 2; ++n) _Pragma("unroll") for (int k = 0; k < 2; ++k) \
;         acc[ai][bj][m][n] = __builtin_amdgcn_mfma_f32_16x16x32_bf16(Bt[n][k], At[m][k], acc[ai][bj][m][n], 0, 0, 0); __builtin_amdgcn_s_setprio(0); } while (0)
; #define PG8_WAIT_V(n) asm volatile("s_waitcnt vmcnt(" #n ")" ::: "memory")
; #define PG8_WAIT_L(n) asm volatile("s_waitcnt lgkmcnt(" #n ")" ::: "memory")
; #define PG8_BAR __builtin_amdgcn_s_barrier()
; #define PG8_SCHED __builtin_amdgcn_sched_barrier(0)
; template <class Epi, class Sched, bool ALIGN_EPI = false, bool SP2 = false>
; __device__ __forceinline__ void gemm_phase(PG8_LAS unsigned char* lds, const Gemm g, const Sched& S, const Epi& E, const int tid) {
;     ...
;         for (int t = 0; t < nt; t += 2) {
;     ...
;             PG8_LDA(At, 1, 1); PG8_STAGE(PG8_SB(1, 0), b3, voffB); PG8_STAGE(PG8_SB(1, 1), b3 + hstep, voffB); PG8_STAGE(PG8_SA(1, 0), a3, voffA);
;             PG8_WAIT_V(8); PG8_WAIT_L(0); PG8_BAR; PG8_MMA(1, 0, At, B0); PG8_MMA(1, 1, At, B1); PG8_BAR; PG8_SCHED;
	s_add_i32 s18, s73, s35
	v_lshl_add_u64 v[194:195], v[194:195], 0, s[36:37]
	s_mov_b32 m0, s18
	ds_read_b128 v[172:175], v139 offset:49152
	ds_read_b128 v[176:179], v139 offset:50176
	ds_read_b128 v[180:183], v139 offset:51200
	ds_read_b128 v[184:187], v139 offset:52224
	ds_read_b128 v[188:191], v139 offset:53248
	ds_read_b128 v[212:215], v139 offset:54272
	ds_read_b128 v[216:219], v139 offset:55296
	ds_read_b128 v[232:235], v139 offset:56320
	global_load_lds_dwordx4 v[194:195], off
	s_add_i32 m0, s18, 0x2000
	s_add_u32 s18, s22, 0xb0080
	v_lshl_add_u64 v[194:195], v[196:197], 0, s[36:37]
	s_addc_u32 s19, s23, 0
	s_add_i32 s22, s74, s35
	global_load_lds_dwordx4 v[194:195], off
	v_lshl_add_u64 v[194:195], s[18:19], 0, v[192:193]
	s_mov_b32 m0, s22
	s_nop 0
	global_load_lds_dwordx4 v[194:195], off
	v_lshl_add_u64 v[194:195], s[18:19], 0, v[132:133]
	s_add_i32 m0, s22, 0x2000
	s_nop 0
	global_load_lds_dwordx4 v[194:195], off
	v_lshl_add_u64 v[194:195], v[202:203], 0, s[36:37]
	s_mov_b32 m0, s47
	s_nop 0
	global_load_lds_dwordx4 v[194:195], off
	v_lshl_add_u64 v[194:195], v[204:205], 0, s[36:37]
	s_mov_b32 m0, s53
	s_nop 0
	global_load_lds_dwordx4 v[194:195], off
	s_add_i32 s72, s72, 2
	s_add_u32 s62, s62, 0x100
	s_addc_u32 s71, s71, 0
	s_cmp_gt_u32 s72, 41
	s_mov_b64 s[18:19], s[20:21]
	s_waitcnt vmcnt(8)
	s_waitcnt lgkmcnt(0)
	s_barrier
	s_setprio 1
	s_waitcnt lgkmcnt(0)
	v_mfma_f32_16x16x32_bf16 v[60:63], v[140:143], v[172:175], v[60:63]
	v_mfma_f32_16x16x32_bf16 v[56:59], v[148:151], v[172:175], v[56:59]
	v_mfma_f32_16x16x32_bf16 v[52:55], v[140:143], v[180:183], v[52:55]
	v_mfma_f32_16x16x32_bf16 v[48:51], v[148:151], v[180:183], v[48:51]
	v_mfma_f32_16x16x32_bf16 v[36:39], v[140:143], v[188:191], v[36:39]
	v_mfma_f32_16x16x32_bf16 v[32:35], v[148:151], v[188:191], v[32:35]
	v_mfma_f32_16x16x32_bf16 v[20:23], v[140:143], v[216:219], v[20:23]
	v_mfma_f32_16x16x32_bf16 v[16:19], v[148:151], v[216:219], v[16:19]
	v_mfma_f32_16x16x32_bf16 v[60:63], v[144:147], v[176:179], v[60:63]
	v_mfma_f32_16x16x32_bf16 v[56:59], v[152:155], v[176:179], v[56:59]
	v_mfma_f32_16x16x32_bf16 v[52:55], v[144:147], v[184:187], v[52:55]
	v_mfma_f32_16x16x32_bf16 v[48:51], v[152:155], v[184:187], v[48:51]
	v_mfma_f32_16x16x32_bf16 v[36:39], v[144:147], v[212:215], v[36:39]
	v_mfma_f32_16x16x32_bf16 v[32:35], v[152:155], v[212:215], v[32:35]
	v_mfma_f32_16x16x32_bf16 v[20:23], v[144:147], v[232:235], v[20:23]
	v_mfma_f32_16x16x32_bf16 v[16:19], v[152:155], v[232:235], v[16:19]
	s_setprio 0
	s_setprio 1
	v_mfma_f32_16x16x32_bf16 v[44:47], v[156:159], v[172:175], v[44:47]
	v_mfma_f32_16x16x32_bf16 v[40:43], v[164:167], v[172:175], v[40:43]
	v_mfma_f32_16x16x32_bf16 v[28:31], v[156:159], v[180:183], v[28:31]
	v_mfma_f32_16x16x32_bf16 v[24:27], v[164:167], v[180:183], v[24:27]
	v_mfma_f32_16x16x32_bf16 v[12:15], v[156:159], v[188:191], v[12:15]
	v_mfma_f32_16x16x32_bf16 v[8:11], v[164:167], v[188:191], v[8:11]
	v_mfma_f32_16x16x32_bf16 v[4:7], v[156:159], v[216:219], v[4:7]
	v_mfma_f32_16x16x32_bf16 v[0:3], v[164:167], v[216:219], v[0:3]
	v_mfma_f32_16x16x32_bf16 v[44:47], v[160:163], v[176:179], v[44:47]
	v_mfma_f32_16x16x32_bf16 v[40:43], v[168:171], v[176:179], v[40:43]
	v_mfma_f32_16x16x32_bf16 v[28:31], v[160:163], v[184:187], v[28:31]
	v_mfma_f32_16x16x32_bf16 v[24:27], v[168:171], v[184:187], v[24:27]
	v_mfma_f32_16x16x32_bf16 v[12:15], v[160:163], v[212:215], v[12:15]
	v_mfma_f32_16x16x32_bf16 v[8:11], v[168:171], v[212:215], v[8:11]
	v_mfma_f32_16x16x32_bf16 v[4:7], v[160:163], v[232:235], v[4:7]
	v_mfma_f32_16x16x32_bf16 v[0:3], v[168:171], v[232:235], v[0:3]
	s_setprio 0
	s_barrier
	s_cbranch_scc0 .LBB0_99
	s_and_b64 vcc, exec, s[14:15]
	s_cbranch_vccz .LBB0_102
	s_barrier

; #define PG8_STAGE(bufoff, gbase, voff) do { _Pragma("unroll") for (int _i = 0; _i < 2; ++_i) \
;         __builtin_amdgcn_global_load_lds((const unsigned*)((const char*)(gbase) + (voff)[_i]), (PG8_LAS unsigned*)(lds + (bufoff) + ldsw + _i * 8192), 16, 0, 0); } while (0)
; #define PG8_LDA(dst, b, h) do { _Pragma("unroll") for (int m = 0; m < 4; ++m) _Pragma("unroll") for (int k = 0; k < 2; ++k) dst[m][k] = *(const PG8_LAS bf16x8*)(lds + PG8_SA(b, h) + aoff + m * 2048 + k * 1024); } while (0)
; #define PG8_LDB(dst, b, h) do { _Pragma("unroll") for (int n = 0; n < 2; ++n) _Pragma("unroll") for (int k = 0; k < 2; ++k) dst[n][k] = *(const PG8_LAS bf16x8*)(lds + PG8_SB(b, h) + boff + n * 2048 + k * 1024); } while (0)
; #define PG8_MMA(ai, bj, At, Bt) do { __builtin_amdgcn_s_setprio(1); _Pragma("unroll") for (int m = 0; m < 4; ++m) _Pragma("unroll") for (int n = 0; n < 2; ++n) _Pragma("unroll") for (int k = 0; k < 2; ++k) \
;         acc[ai][bj][m][n] = __builtin_amdgcn_mfma_f32_16x16x32_bf16(Bt[n][k], At[m][k], acc[ai][bj][m][n], 0, 0, 0); __builtin_amdgcn_s_setprio(0); } while (0)
; #define PG8_WAIT_V(n) asm volatile("s_waitcnt vmcnt(" #n ")" ::: "memory")
; #define PG8_WAIT_L(n) asm volatile("s_waitcnt lgkmcnt(" #n ")" ::: "memory")
; #define PG8_BAR __builtin_amdgcn_s_barrier()
; #define PG8_SCHED __builtin_amdgcn_sched_barrier(0)
; template <class Epi, class Sched, bool ALIGN_EPI = false, bool SP2 = false>
; __device__ __forceinline__ void gemm_phase(PG8_LAS unsigned char* lds, const Gemm g, const Sched& S, const Epi& E, const int tid) {
;     ...
;             const bool last = (t == nt - 2);
;             const char* a1 = cA + (size_t)(t + 1) * kstep;
;             const char* a2 = last ? nA : cA + (size_t)(t + 2) * kstep; const char* b2 = last ? nB : cB + (size_t)(t + 2) * kstep;
;             const char* a3 = a2 + kstep; const char* b3 = b2 + kstep;
;             if (last && has_next) S.a_ready(nxt);
;             if constexpr (SP2) {
;             PG8_LDB(B0, 0, 0); PG8_LDB(B1, 0, 1); PG8_SCHED; PG8_LDA(At, 0, 0); PG8_STAGE(PG8_SA(1, 1), a1 + hstep, voffA);
;             PG8_WAIT_V(8); PG8_WAIT_L(0); PG8_BAR; PG8_MMA(0, 0, At, B0); PG8_MMA(0, 1, At, B1); PG8_BAR; PG8_SCHED;
;             PG8_LDA(At, 0, 1); PG8_STAGE(PG8_SB(0, 0), b2, voffB); PG8_STAGE(PG8_SB(0, 1), b2 + hstep, voffB); PG8_STAGE(PG8_SA(0, 0), a2, voffA);
.LBB0_127:
	s_waitcnt lgkmcnt(0)
	v_add_u32_e32 v156, 0x10000, v142
	v_add_u32_e32 v172, 0x14000, v142
	ds_read_b128 v[144:147], v156
	ds_read_b128 v[148:151], v156 offset:1024
	ds_read_b128 v[152:155], v156 offset:2048
	ds_read_b128 v[156:159], v156 offset:3072
	ds_read_b128 v[160:163], v172
	ds_read_b128 v[164:167], v172 offset:1024
	ds_read_b128 v[168:171], v172 offset:2048
	ds_read_b128 v[172:175], v172 offset:3072
	s_add_u32 s44, s16, s22
	s_addc_u32 s45, s17, s23
	s_add_u32 s44, s44, 0x100
	s_addc_u32 s45, s45, 0
	s_add_u32 s75, s19, s22
	s_addc_u32 s76, s62, s23
	s_add_i32 s77, 0, 0x10000
	s_cmpk_eq_i32 s22, 0x1500
	s_cselect_b32 s59, s21, s45
	s_cselect_b32 s58, s20, s44
	s_cselect_b32 s45, s11, s76
	s_cselect_b32 s44, s10, s75
	s_add_i32 s75, 0, 0x14000
	v_lshl_add_u64 v[194:195], v[138:139], 0, s[22:23]
	s_add_i32 m0, s47, 0xc000
	ds_read_b128 v[176:179], v143
	ds_read_b128 v[180:183], v143 offset:1024
	ds_read_b128 v[184:187], v143 offset:2048
	ds_read_b128 v[188:191], v143 offset:3072
	ds_read_b128 v[212:215], v143 offset:4096
	ds_read_b128 v[216:219], v143 offset:5120
	ds_read_b128 v[232:235], v143 offset:6144
	ds_read_b128 v[236:239], v143 offset:7168
	global_load_lds_dwordx4 v[194:195], off
	v_lshl_add_u64 v[194:195], v[140:141], 0, s[22:23]
	s_add_i32 m0, s47, 0xe000
	s_nop 0
	global_load_lds_dwordx4 v[194:195], off
	s_waitcnt vmcnt(8)
	s_waitcnt lgkmcnt(0)
	s_barrier
	s_setprio 1
	s_waitcnt lgkmcnt(0)
	v_mfma_f32_16x16x32_bf16 v[124:127], v[144:147], v[176:179], v[124:127]
	v_mfma_f32_16x16x32_bf16 v[120:123], v[152:155], v[176:179], v[120:123]
	v_mfma_f32_16x16x32_bf16 v[108:111], v[144:147], v[184:187], v[108:111]
	v_mfma_f32_16x16x32_bf16 v[104:107], v[152:155], v[184:187], v[104:107]
	v_mfma_f32_16x16x32_bf16 v[92:95], v[144:147], v[212:215], v[92:95]
	v_mfma_f32_16x16x32_bf16 v[88:91], v[152:155], v[212:215], v[88:91]
	v_mfma_f32_16x16x32_bf16 v[76:79], v[144:147], v[232:235], v[76:79]
	v_mfma_f32_16x16x32_bf16 v[72:75], v[152:155], v[232:235], v[72:75]
	v_mfma_f32_16x16x32_bf16 v[124:127], v[148:151], v[180:183], v[124:127]
	v_mfma_f32_16x16x32_bf16 v[120:123], v[156:159], v[180:183], v[120:123]
	v_mfma_f32_16x16x32_bf16 v[108:111], v[148:151], v[188:191], v[108:111]
	v_mfma_f32_16x16x32_bf16 v[104:107], v[156:159], v[188:191], v[104:107]
	v_mfma_f32_16x16x32_bf16 v[92:95], v[148:151], v[216:219], v[92:95]
	v_mfma_f32_16x16x32_bf16 v[88:91], v[156:159], v[216:219], v[88:91]
	v_mfma_f32_16x16x32_bf16 v[76:79], v[148:151], v[236:239], v[76:79]
	v_mfma_f32_16x16x32_bf16 v[72:75], v[156:159], v[236:239], v[72:75]
	s_setprio 0
	s_setprio 1
	v_mfma_f32_16x16x32_bf16 v[116:119], v[160:163], v[176:179], v[116:119]
	v_mfma_f32_16x16x32_bf16 v[112:115], v[168:171], v[176:179], v[112:115]
	v_mfma_f32_16x16x32_bf16 v[100:103], v[160:163], v[184:187], v[100:103]
	v_mfma_f32_16x16x32_bf16 v[96:99], v[168:171], v[184:187], v[96:99]
	v_mfma_f32_16x16x32_bf16 v[84:87], v[160:163], v[212:215], v[84:87]
	v_mfma_f32_16x16x32_bf16 v[80:83], v[168:171], v[212:215], v[80:83]
	v_mfma_f32_16x16x32_bf16 v[68:71], v[160:163], v[232:235], v[68:71]
	v_mfma_f32_16x16x32_bf16 v[64:67], v[168:171], v[232:235], v[64:67]
	v_mfma_f32_16x16x32_bf16 v[116:119], v[164:167], v[180:183], v[116:119]
	v_mfma_f32_16x16x32_bf16 v[112:115], v[172:175], v[180:183], v[112:115]
	v_mfma_f32_16x16x32_bf16 v[100:103], v[164:167], v[188:191], v[100:103]
	v_mfma_f32_16x16x32_bf16 v[96:99], v[172:175], v[188:191], v[96:99]
	v_mfma_f32_16x16x32_bf16 v[84:87], v[164:167], v[216:219], v[84:87]
	v_mfma_f32_16x16x32_bf16 v[80:83], v[172:175], v[216:219], v[80:83]
	v_mfma_f32_16x16x32_bf16 v[68:71], v[164:167], v[236:239], v[68:71]
	v_mfma_f32_16x16x32_bf16 v[64:67], v[172:175], v[236:239], v[64:67]
	s_setprio 0
	s_barrier
	s_add_i32 s76, s77, s46
	v_lshl_add_u64 v[194:195], s[44:45], 0, v[192:193]
	s_mov_b32 m0, s76
	ds_read_b128 v[176:179], v143 offset:16384
	ds_read_b128 v[180:183], v143 offset:17408
	ds_read_b128 v[184:187], v143 offset:18432
	ds_read_b128 v[188:191], v143 offset:19456
	ds_read_b128 v[212:215], v143 offset:20480
	ds_read_b128 v[216:219], v143 offset:21504
	ds_read_b128 v[232:235], v143 offset:22528
	ds_read_b128 v[236:239], v143 offset:23552
	global_load_lds_dwordx4 v[194:195], off
	s_add_i32 m0, s76, 0x2000
	s_add_u32 s76, s44, 0xb0000
	v_lshl_add_u64 v[196:197], s[44:45], 0, v[132:133]
	s_addc_u32 s77, s45, 0
	s_add_i32 s75, s75, s46
	global_load_lds_dwordx4 v[196:197], off
	v_lshl_add_u64 v[202:203], s[76:77], 0, v[192:193]
	s_mov_b32 m0, s75
	v_lshl_add_u64 v[204:205], s[58:59], 0, v[130:131]
	global_load_lds_dwordx4 v[202:203], off
	v_lshl_add_u64 v[202:203], s[76:77], 0, v[132:133]
	s_add_i32 m0, s75, 0x2000
	s_nop 0
	global_load_lds_dwordx4 v[202:203], off
	v_lshl_add_u64 v[202:203], s[58:59], 0, v[128:129]
	s_mov_b32 m0, s47
	s_nop 0
	global_load_lds_dwordx4 v[202:203], off
	s_mov_b32 m0, s53
	s_nop 0
	global_load_lds_dwordx4 v[204:205], off
	s_waitcnt vmcnt(8)
	s_waitcnt lgkmcnt(0)
	s_barrier
; #define PG8_STAGE(bufoff, gbase, voff) do { _Pragma("unroll") for (int _i = 0; _i < 2; ++_i) \
;         __builtin_amdgcn_global_load_lds((const unsigned*)((const char*)(gbase) + (voff)[_i]), (PG8_LAS unsigned*)(lds + (bufoff) + ldsw + _i * 8192), 16, 0, 0); } while (0)
; #define PG8_LDA(dst, b, h) do { _Pragma("unroll") for (int m = 0; m < 4; ++m) _Pragma("unroll") for (int k = 0; k < 2; ++k) dst[m][k] = *(const PG8_LAS bf16x8*)(lds + PG8_SA(b, h) + aoff + m * 2048 + k * 1024); } while (0)
; #define PG8_LDB(dst, b, h) do { _Pragma("unroll") for (int n = 0; n < 2; ++n) _Pragma("unroll") for (int k = 0; k < 2; ++k) dst[n][k] = *(const PG8_LAS bf16x8*)(lds + PG8_SB(b, h) + boff + n * 2048 + k * 1024); } while (0)
; #define PG8_MMA(ai, bj, At, Bt) do { __builtin_amdgcn_s_setprio(1); _Pragma("unroll") for (int m = 0; m < 4; ++m) _Pragma("unroll") for (int n = 0; n < 2; ++n) _Pragma("unroll") for (int k = 0; k < 2; ++k) \
;         acc[ai][bj][m][n] = __builtin_amdgcn_mfma_f32_16x16x32_bf16(Bt[n][k], At[m][k], acc[ai][bj][m][n], 0, 0, 0); __builtin_amdgcn_s_setprio(0); } while (0)
; #define PG8_WAIT_V(n) asm volatile("s_waitcnt vmcnt(" #n ")" ::: "memory")
; #define PG8_WAIT_L(n) asm volatile("s_waitcnt lgkmcnt(" #n ")" ::: "memory")
; #define PG8_BAR __builtin_amdgcn_s_barrier()
; #define PG8_SCHED __builtin_amdgcn_sched_barrier(0)
; template <class Epi, class Sched, bool ALIGN_EPI = false, bool SP2 = false>
; __device__ __forceinline__ void gemm_phase(PG8_LAS unsigned char* lds, const Gemm g, const Sched& S, const Epi& E, const int tid) {
;     ...
;             PG8_WAIT_V(8); PG8_WAIT_L(0); PG8_BAR; PG8_MMA(1, 0, At, B0); PG8_MMA(1, 1, At, B1); PG8_BAR; PG8_SCHED;
;             PG8_LDB(B0, 1, 0); PG8_LDB(B1, 1, 1); PG8_SCHED; PG8_LDA(At, 1, 0); PG8_STAGE(PG8_SA(0, 1), a2 + hstep, voffA);
;             PG8_WAIT_V(8); PG8_WAIT_L(0); PG8_BAR; PG8_MMA(0, 0, At, B0); PG8_MMA(0, 1, At, B1); PG8_BAR; PG8_SCHED;
	s_setprio 1
	s_waitcnt lgkmcnt(0)
	v_mfma_f32_16x16x32_bf16 v[60:63], v[144:147], v[176:179], v[60:63]
	v_mfma_f32_16x16x32_bf16 v[56:59], v[152:155], v[176:179], v[56:59]
	v_mfma_f32_16x16x32_bf16 v[44:47], v[144:147], v[184:187], v[44:47]
	v_mfma_f32_16x16x32_bf16 v[40:43], v[152:155], v[184:187], v[40:43]
	v_mfma_f32_16x16x32_bf16 v[28:31], v[144:147], v[212:215], v[28:31]
	v_mfma_f32_16x16x32_bf16 v[24:27], v[152:155], v[212:215], v[24:27]
	v_mfma_f32_16x16x32_bf16 v[12:15], v[144:147], v[232:235], v[12:15]
	v_mfma_f32_16x16x32_bf16 v[8:11], v[152:155], v[232:235], v[8:11]
	v_mfma_f32_16x16x32_bf16 v[60:63], v[148:151], v[180:183], v[60:63]
	v_mfma_f32_16x16x32_bf16 v[56:59], v[156:159], v[180:183], v[56:59]
	v_mfma_f32_16x16x32_bf16 v[44:47], v[148:151], v[188:191], v[44:47]
	v_mfma_f32_16x16x32_bf16 v[40:43], v[156:159], v[188:191], v[40:43]
	v_mfma_f32_16x16x32_bf16 v[28:31], v[148:151], v[216:219], v[28:31]
	v_mfma_f32_16x16x32_bf16 v[24:27], v[156:159], v[216:219], v[24:27]
	v_mfma_f32_16x16x32_bf16 v[12:15], v[148:151], v[236:239], v[12:15]
	v_mfma_f32_16x16x32_bf16 v[8:11], v[156:159], v[236:239], v[8:11]
	s_setprio 0
	s_setprio 1
	v_mfma_f32_16x16x32_bf16 v[52:55], v[160:163], v[176:179], v[52:55]
	v_mfma_f32_16x16x32_bf16 v[48:51], v[168:171], v[176:179], v[48:51]
	v_mfma_f32_16x16x32_bf16 v[36:39], v[160:163], v[184:187], v[36:39]
	v_mfma_f32_16x16x32_bf16 v[32:35], v[168:171], v[184:187], v[32:35]
	v_mfma_f32_16x16x32_bf16 v[20:23], v[160:163], v[212:215], v[20:23]
	v_mfma_f32_16x16x32_bf16 v[16:19], v[168:171], v[212:215], v[16:19]
	v_mfma_f32_16x16x32_bf16 v[4:7], v[160:163], v[232:235], v[4:7]
	v_mfma_f32_16x16x32_bf16 v[0:3], v[168:171], v[232:235], v[0:3]
	v_mfma_f32_16x16x32_bf16 v[52:55], v[164:167], v[180:183], v[52:55]
	v_mfma_f32_16x16x32_bf16 v[48:51], v[172:175], v[180:183], v[48:51]
	v_mfma_f32_16x16x32_bf16 v[36:39], v[164:167], v[188:191], v[36:39]
	v_mfma_f32_16x16x32_bf16 v[32:35], v[172:175], v[188:191], v[32:35]
	v_mfma_f32_16x16x32_bf16 v[20:23], v[164:167], v[216:219], v[20:23]
	v_mfma_f32_16x16x32_bf16 v[16:19], v[172:175], v[216:219], v[16:19]
	v_mfma_f32_16x16x32_bf16 v[4:7], v[164:167], v[236:239], v[4:7]
	v_mfma_f32_16x16x32_bf16 v[0:3], v[172:175], v[236:239], v[0:3]
	s_setprio 0
	s_barrier
	s_add_i32 s75, 0, 0x18000
	s_add_i32 s76, 0, 0x1c000
	v_add_u32_e32 v156, s75, v142
	v_add_u32_e32 v172, s76, v142
	ds_read_b128 v[144:147], v156
	ds_read_b128 v[148:151], v156 offset:1024
	ds_read_b128 v[152:155], v156 offset:2048
	ds_read_b128 v[156:159], v156 offset:3072
	ds_read_b128 v[160:163], v172
	ds_read_b128 v[164:167], v172 offset:1024
	ds_read_b128 v[168:171], v172 offset:2048
	ds_read_b128 v[172:175], v172 offset:3072
	s_add_u32 s58, s58, 0xb0000
	s_addc_u32 s59, s59, 0
	s_mov_b32 m0, s54
	v_lshl_add_u64 v[206:207], s[58:59], 0, v[128:129]
	ds_read_b128 v[176:179], v143 offset:32768
	ds_read_b128 v[180:183], v143 offset:33792
	ds_read_b128 v[184:187], v143 offset:34816
	ds_read_b128 v[188:191], v143 offset:35840
	ds_read_b128 v[212:215], v143 offset:36864
	ds_read_b128 v[216:219], v143 offset:37888
	ds_read_b128 v[232:235], v143 offset:38912
	ds_read_b128 v[236:239], v143 offset:39936
	global_load_lds_dwordx4 v[206:207], off
	v_lshl_add_u64 v[206:207], s[58:59], 0, v[130:131]
	s_mov_b32 m0, s55
	s_nop 0
	global_load_lds_dwordx4 v[206:207], off
	s_waitcnt vmcnt(8)
	s_waitcnt lgkmcnt(0)
	s_barrier
	s_setprio 1
	s_waitcnt lgkmcnt(0)
	v_mfma_f32_16x16x32_bf16 v[124:127], v[144:147], v[176:179], v[124:127]
	v_mfma_f32_16x16x32_bf16 v[120:123], v[152:155], v[176:179], v[120:123]
	v_mfma_f32_16x16x32_bf16 v[108:111], v[144:147], v[184:187], v[108:111]
	v_mfma_f32_16x16x32_bf16 v[104:107], v[152:155], v[184:187], v[104:107]
	v_mfma_f32_16x16x32_bf16 v[92:95], v[144:147], v[212:215], v[92:95]
	v_mfma_f32_16x16x32_bf16 v[88:91], v[152:155], v[212:215], v[88:91]
	v_mfma_f32_16x16x32_bf16 v[76:79], v[144:147], v[232:235], v[76:79]
	v_mfma_f32_16x16x32_bf16 v[72:75], v[152:155], v[232:235], v[72:75]
	v_mfma_f32_16x16x32_bf16 v[124:127], v[148:151], v[180:183], v[124:127]
	v_mfma_f32_16x16x32_bf16 v[120:123], v[156:159], v[180:183], v[120:123]
	v_mfma_f32_16x16x32_bf16 v[108:111], v[148:151], v[188:191], v[108:111]
	v_mfma_f32_16x16x32_bf16 v[104:107], v[156:159], v[188:191], v[104:107]
	v_mfma_f32_16x16x32_bf16 v[92:95], v[148:151], v[216:219], v[92:95]
	v_mfma_f32_16x16x32_bf16 v[88:91], v[156:159], v[216:219], v[88:91]
	v_mfma_f32_16x16x32_bf16 v[76:79], v[148:151], v[236:239], v[76:79]
	v_mfma_f32_16x16x32_bf16 v[72:75], v[156:159], v[236:239], v[72:75]
	s_setprio 0
	s_setprio 1
	v_mfma_f32_16x16x32_bf16 v[116:119], v[160:163], v[176:179], v[116:119]
	v_mfma_f32_16x16x32_bf16 v[112:115], v[168:171], v[176:179], v[112:115]
	v_mfma_f32_16x16x32_bf16 v[100:103], v[160:163], v[184:187], v[100:103]
	v_mfma_f32_16x16x32_bf16 v[96:99], v[168:171], v[184:187], v[96:99]
	v_mfma_f32_16x16x32_bf16 v[84:87], v[160:163], v[212:215], v[84:87]
	v_mfma_f32_16x16x32_bf16 v[80:83], v[168:171], v[212:215], v[80:83]
	v_mfma_f32_16x16x32_bf16 v[68:71], v[160:163], v[232:235], v[68:71]
	v_mfma_f32_16x16x32_bf16 v[64:67], v[168:171], v[232:235], v[64:67]
	v_mfma_f32_16x16x32_bf16 v[116:119], v[164:167], v[180:183], v[116:119]
	v_mfma_f32_16x16x32_bf16 v[112:115], v[172:175], v[180:183], v[112:115]
	v_mfma_f32_16x16x32_bf16 v[100:103], v[164:167], v[188:191], v[100:103]
	v_mfma_f32_16x16x32_bf16 v[96:99], v[172:175], v[188:191], v[96:99]
	v_mfma_f32_16x16x32_bf16 v[84:87], v[164:167], v[216:219], v[84:87]
	v_mfma_f32_16x16x32_bf16 v[80:83], v[172:175], v[216:219], v[80:83]
	v_mfma_f32_16x16x32_bf16 v[68:71], v[164:167], v[236:239], v[68:71]
	v_mfma_f32_16x16x32_bf16 v[64:67], v[172:175], v[236:239], v[64:67]
	s_setprio 0
	s_barrier
; #define PG8_STAGE(bufoff, gbase, voff) do { _Pragma("unroll") for (int _i = 0; _i < 2; ++_i) \
;         __builtin_amdgcn_global_load_lds((const unsigned*)((const char*)(gbase) + (voff)[_i]), (PG8_LAS unsigned*)(lds + (bufoff) + ldsw + _i * 8192), 16, 0, 0); } while (0)
; #define PG8_LDA(dst, b, h) do { _Pragma("unroll") for (int m = 0; m < 4; ++m) _Pragma("unroll") for (int k = 0; k < 2; ++k) dst[m][k] = *(const PG8_LAS bf16x8*)(lds + PG8_SA(b, h) + aoff + m * 2048 + k * 1024); } while (0)
; #define PG8_MMA(ai, bj, At, Bt) do { __builtin_amdgcn_s_setprio(1); _Pragma("unroll") for (int m = 0; m < 4; ++m) _Pragma("unroll") for (int n = 0; n < 2; ++n) _Pragma("unroll") for (int k = 0; k < 2; ++k) \
;         acc[ai][bj][m][n] = __builtin_amdgcn_mfma_f32_16x16x32_bf16(Bt[n][k], At[m][k], acc[ai][bj][m][n], 0, 0, 0); __builtin_amdgcn_s_setprio(0); } while (0)
; #define PG8_WAIT_V(n) asm volatile("s_waitcnt vmcnt(" #n ")" ::: "memory")
; #define PG8_WAIT_L(n) asm volatile("s_waitcnt lgkmcnt(" #n ")" ::: "memory")
; #define PG8_BAR __builtin_amdgcn_s_barrier()
; #define PG8_SCHED __builtin_amdgcn_sched_barrier(0)
; template <class Epi, class Sched, bool ALIGN_EPI = false, bool SP2 = false>
; __device__ __forceinline__ void gemm_phase(PG8_LAS unsigned char* lds, const Gemm g, const Sched& S, const Epi& E, const int tid) {
;     ...
;             PG8_LDA(At, 1, 1); PG8_STAGE(PG8_SB(1, 0), b3, voffB); PG8_STAGE(PG8_SB(1, 1), b3 + hstep, voffB); PG8_STAGE(PG8_SA(1, 0), a3, voffA);
;             PG8_WAIT_V(8); PG8_WAIT_L(0); PG8_BAR; PG8_MMA(1, 0, At, B0); PG8_MMA(1, 1, At, B1); PG8_BAR; PG8_SCHED;
;     ...
;         if (!has_next) break;
; #pragma unroll
;         for (int a = 0; a < 2; ++a)
; #pragma unroll
;             for (int b = 0; b < 2; ++b)
; #pragma unroll
;                 for (int m = 0; m < 4; ++m)
; #pragma unroll
;                     for (int n = 0; n < 2; ++n) acc[a][b][m][n] = (f32x4){0.f, 0.f, 0.f, 0.f};
;         cur = nxt; cA = nA; cB = nB; ++ui;
	s_add_i32 s58, s75, s46
	v_lshl_add_u64 v[194:195], v[194:195], 0, s[36:37]
	s_mov_b32 m0, s58
	ds_read_b128 v[176:179], v143 offset:49152
	ds_read_b128 v[180:183], v143 offset:50176
	ds_read_b128 v[184:187], v143 offset:51200
	ds_read_b128 v[188:191], v143 offset:52224
	ds_read_b128 v[212:215], v143 offset:53248
	ds_read_b128 v[216:219], v143 offset:54272
	ds_read_b128 v[232:235], v143 offset:55296
	ds_read_b128 v[236:239], v143 offset:56320
	global_load_lds_dwordx4 v[194:195], off
	s_add_i32 m0, s58, 0x2000
	s_add_u32 s44, s44, 0xb0080
	v_lshl_add_u64 v[194:195], v[196:197], 0, s[36:37]
	s_addc_u32 s45, s45, 0
	s_add_i32 s58, s76, s46
	global_load_lds_dwordx4 v[194:195], off
	v_lshl_add_u64 v[194:195], s[44:45], 0, v[192:193]
	s_mov_b32 m0, s58
	s_nop 0
	global_load_lds_dwordx4 v[194:195], off
	v_lshl_add_u64 v[194:195], s[44:45], 0, v[132:133]
	s_add_i32 m0, s58, 0x2000
	s_nop 0
	global_load_lds_dwordx4 v[194:195], off
	v_lshl_add_u64 v[194:195], v[202:203], 0, s[36:37]
	s_mov_b32 m0, s60
	s_nop 0
	global_load_lds_dwordx4 v[194:195], off
	v_lshl_add_u64 v[194:195], v[204:205], 0, s[36:37]
	s_mov_b32 m0, s70
	s_nop 0
	global_load_lds_dwordx4 v[194:195], off
	s_add_i32 s74, s74, 2
	s_add_u32 s22, s22, 0x100
	s_addc_u32 s23, s23, 0
	s_cmp_gt_u32 s74, 41
	s_waitcnt vmcnt(8)
	s_waitcnt lgkmcnt(0)
	s_barrier
	s_setprio 1
	s_waitcnt lgkmcnt(0)
	v_mfma_f32_16x16x32_bf16 v[60:63], v[144:147], v[176:179], v[60:63]
	v_mfma_f32_16x16x32_bf16 v[56:59], v[152:155], v[176:179], v[56:59]
	v_mfma_f32_16x16x32_bf16 v[44:47], v[144:147], v[184:187], v[44:47]
	v_mfma_f32_16x16x32_bf16 v[40:43], v[152:155], v[184:187], v[40:43]
	v_mfma_f32_16x16x32_bf16 v[28:31], v[144:147], v[212:215], v[28:31]
	v_mfma_f32_16x16x32_bf16 v[24:27], v[152:155], v[212:215], v[24:27]
	v_mfma_f32_16x16x32_bf16 v[12:15], v[144:147], v[232:235], v[12:15]
	v_mfma_f32_16x16x32_bf16 v[8:11], v[152:155], v[232:235], v[8:11]
	v_mfma_f32_16x16x32_bf16 v[60:63], v[148:151], v[180:183], v[60:63]
	v_mfma_f32_16x16x32_bf16 v[56:59], v[156:159], v[180:183], v[56:59]
	v_mfma_f32_16x16x32_bf16 v[44:47], v[148:151], v[188:191], v[44:47]
	v_mfma_f32_16x16x32_bf16 v[40:43], v[156:159], v[188:191], v[40:43]
	v_mfma_f32_16x16x32_bf16 v[28:31], v[148:151], v[216:219], v[28:31]
	v_mfma_f32_16x16x32_bf16 v[24:27], v[156:159], v[216:219], v[24:27]
	v_mfma_f32_16x16x32_bf16 v[12:15], v[148:151], v[236:239], v[12:15]
	v_mfma_f32_16x16x32_bf16 v[8:11], v[156:159], v[236:239], v[8:11]
	s_setprio 0
	s_setprio 1
	v_mfma_f32_16x16x32_bf16 v[52:55], v[160:163], v[176:179], v[52:55]
	v_mfma_f32_16x16x32_bf16 v[48:51], v[168:171], v[176:179], v[48:51]
	v_mfma_f32_16x16x32_bf16 v[36:39], v[160:163], v[184:187], v[36:39]
	v_mfma_f32_16x16x32_bf16 v[32:35], v[168:171], v[184:187], v[32:35]
	v_mfma_f32_16x16x32_bf16 v[20:23], v[160:163], v[212:215], v[20:23]
	v_mfma_f32_16x16x32_bf16 v[16:19], v[168:171], v[212:215], v[16:19]
	v_mfma_f32_16x16x32_bf16 v[4:7], v[160:163], v[232:235], v[4:7]
	v_mfma_f32_16x16x32_bf16 v[0:3], v[168:171], v[232:235], v[0:3]
	v_mfma_f32_16x16x32_bf16 v[52:55], v[164:167], v[180:183], v[52:55]
	v_mfma_f32_16x16x32_bf16 v[48:51], v[172:175], v[180:183], v[48:51]
	v_mfma_f32_16x16x32_bf16 v[36:39], v[164:167], v[188:191], v[36:39]
	v_mfma_f32_16x16x32_bf16 v[32:35], v[172:175], v[188:191], v[32:35]
	v_mfma_f32_16x16x32_bf16 v[20:23], v[164:167], v[216:219], v[20:23]
	v_mfma_f32_16x16x32_bf16 v[16:19], v[172:175], v[216:219], v[16:19]
	v_mfma_f32_16x16x32_bf16 v[4:7], v[164:167], v[236:239], v[4:7]
	v_mfma_f32_16x16x32_bf16 v[0:3], v[172:175], v[236:239], v[0:3]
	s_setprio 0
	s_barrier
	s_cbranch_scc0 .LBB0_127
	s_add_u32 s22, s19, 0xffffff00
	s_addc_u32 s23, s62, -1
	s_and_b64 vcc, exec, s[8:9]
	s_cbranch_vccnz .LBB0_130
	v_mov_b32_e32 v0, 0
	s_mov_b32 s14, s72
	s_mov_b32 s1, s73
	s_mov_b64 s[16:17], s[20:21]
	s_mov_b32 s71, s18
	v_mov_b32_e32 v1, v0
	v_mov_b32_e32 v2, v0
	v_mov_b32_e32 v3, v0
	v_mov_b32_e32 v4, v0
	v_mov_b32_e32 v5, v0
	v_mov_b32_e32 v6, v0
	v_mov_b32_e32 v7, v0
	v_mov_b32_e32 v16, v0
	v_mov_b32_e32 v17, v0
	v_mov_b32_e32 v18, v0
	v_mov_b32_e32 v19, v0
	v_mov_b32_e32 v20, v0
	v_mov_b32_e32 v21, v0
	v_mov_b32_e32 v22, v0
	v_mov_b32_e32 v23, v0
	v_mov_b32_e32 v32, v0
	v_mov_b32_e32 v33, v0
	v_mov_b32_e32 v34, v0
	v_mov_b32_e32 v35, v0
	v_mov_b32_e32 v36, v0
	v_mov_b32_e32 v37, v0
	v_mov_b32_e32 v38, v0
	v_mov_b32_e32 v39, v0
	v_mov_b32_e32 v48, v0
	v_mov_b32_e32 v49, v0
	v_mov_b32_e32 v50, v0
	v_mov_b32_e32 v51, v0
	v_mov_b32_e32 v52, v0
	v_mov_b32_e32 v53, v0
	v_mov_b32_e32 v54, v0
	v_mov_b32_e32 v55, v0
	v_mov_b32_e32 v8, v0
	v_mov_b32_e32 v9, v0
	v_mov_b32_e32 v10, v0
	v_mov_b32_e32 v11, v0
	v_mov_b32_e32 v12, v0
	v_mov_b32_e32 v13, v0
	v_mov_b32_e32 v14, v0
	v_mov_b32_e32 v15, v0
	v_mov_b32_e32 v24, v0
	v_mov_b32_e32 v25, v0
	v_mov_b32_e32 v26, v0
	v_mov_b32_e32 v27, v0
	v_mov_b32_e32 v28, v0
	v_mov_b32_e32 v29, v0
	v_mov_b32_e32 v30, v0
	v_mov_b32_e32 v31, v0
	v_mov_b32_e32 v40, v0
	v_mov_b32_e32 v41, v0
	v_mov_b32_e32 v42, v0
	v_mov_b32_e32 v43, v0
	v_mov_b32_e32 v44, v0
	v_mov_b32_e32 v45, v0
	v_mov_b32_e32 v46, v0
	v_mov_b32_e32 v47, v0
	v_mov_b32_e32 v56, v0
	v_mov_b32_e32 v57, v0
	v_mov_b32_e32 v58, v0
	v_mov_b32_e32 v59, v0
	v_mov_b32_e32 v60, v0
	v_mov_b32_e32 v61, v0
	v_mov_b32_e32 v62, v0
	v_mov_b32_e32 v63, v0
	v_mov_b32_e32 v64, v0
	v_mov_b32_e32 v65, v0
	v_mov_b32_e32 v66, v0
	v_mov_b32_e32 v67, v0
	v_mov_b32_e32 v68, v0
	v_mov_b32_e32 v69, v0
	v_mov_b32_e32 v70, v0
	v_mov_b32_e32 v71, v0
	v_mov_b32_e32 v80, v0
	v_mov_b32_e32 v81, v0
	v_mov_b32_e32 v82, v0
	v_mov_b32_e32 v83, v0
	v_mov_b32_e32 v84, v0
	v_mov_b32_e32 v85, v0
	v_mov_b32_e32 v86, v0
	v_mov_b32_e32 v87, v0
	v_mov_b32_e32 v96, v0
	v_mov_b32_e32 v97, v0
	v_mov_b32_e32 v98, v0
	v_mov_b32_e32 v99, v0
	v_mov_b32_e32 v100, v0
	v_mov_b32_e32 v101, v0
	v_mov_b32_e32 v102, v0
	v_mov_b32_e32 v103, v0
	v_mov_b32_e32 v112, v0
	v_mov_b32_e32 v113, v0
	v_mov_b32_e32 v114, v0
	v_mov_b32_e32 v115, v0
	v_mov_b32_e32 v116, v0
	v_mov_b32_e32 v117, v0
	v_mov_b32_e32 v118, v0
	v_mov_b32_e32 v119, v0
	v_mov_b32_e32 v72, v0
	v_mov_b32_e32 v73, v0
	v_mov_b32_e32 v74, v0
	v_mov_b32_e32 v75, v0
	v_mov_b32_e32 v76, v0
	v_mov_b32_e32 v77, v0
	v_mov_b32_e32 v78, v0
	v_mov_b32_e32 v79, v0
	v_mov_b32_e32 v88, v0
	v_mov_b32_e32 v89, v0
	v_mov_b32_e32 v90, v0
	v_mov_b32_e32 v91, v0
	v_mov_b32_e32 v92, v0
	v_mov_b32_e32 v93, v0
	v_mov_b32_e32 v94, v0
	v_mov_b32_e32 v95, v0
	v_mov_b32_e32 v104, v0
	v_mov_b32_e32 v105, v0
	v_mov_b32_e32 v106, v0
	v_mov_b32_e32 v107, v0
	v_mov_b32_e32 v108, v0
	v_mov_b32_e32 v109, v0
	v_mov_b32_e32 v110, v0
	v_mov_b32_e32 v111, v0
	v_mov_b32_e32 v120, v0
	v_mov_b32_e32 v121, v0
	v_mov_b32_e32 v122, v0
	v_mov_b32_e32 v123, v0
	v_mov_b32_e32 v124, v0
	v_mov_b32_e32 v125, v0
	v_mov_b32_e32 v126, v0
	v_mov_b32_e32 v127, v0
	s_load_dword s75, s[96:97], 0x0
	s_andn2_b64 vcc, exec, s[6:7]
	s_cbranch_vccnz .LBB0_131
	s_branch .LBB0_189

; #define PG8_STAGE(bufoff, gbase, voff) do { _Pragma("unroll") for (int _i = 0; _i < 2; ++_i) \
;         __builtin_amdgcn_global_load_lds((const unsigned*)((const char*)(gbase) + (voff)[_i]), (PG8_LAS unsigned*)(lds + (bufoff) + ldsw + _i * 8192), 16, 0, 0); } while (0)
; #define PG8_LDA(dst, b, h) do { _Pragma("unroll") for (int m = 0; m < 4; ++m) _Pragma("unroll") for (int k = 0; k < 2; ++k) dst[m][k] = *(const PG8_LAS bf16x8*)(lds + PG8_SA(b, h) + aoff + m * 2048 + k * 1024); } while (0)
; #define PG8_LDB(dst, b, h) do { _Pragma("unroll") for (int n = 0; n < 2; ++n) _Pragma("unroll") for (int k = 0; k < 2; ++k) dst[n][k] = *(const PG8_LAS bf16x8*)(lds + PG8_SB(b, h) + boff + n * 2048 + k * 1024); } while (0)
; #define PG8_MMA(ai, bj, At, Bt) do { __builtin_amdgcn_s_setprio(1); _Pragma("unroll") for (int m = 0; m < 4; ++m) _Pragma("unroll") for (int n = 0; n < 2; ++n) _Pragma("unroll") for (int k = 0; k < 2; ++k) \
;         acc[ai][bj][m][n] = __builtin_amdgcn_mfma_f32_16x16x32_bf16(Bt[n][k], At[m][k], acc[ai][bj][m][n], 0, 0, 0); __builtin_amdgcn_s_setprio(0); } while (0)
; #define PG8_WAIT_V(n) asm volatile("s_waitcnt vmcnt(" #n ")" ::: "memory")
; #define PG8_BAR __builtin_amdgcn_s_barrier()
; template <class Epi, class Sched, bool ALIGN_EPI = false, bool SP2 = false>
; __device__ __forceinline__ void gemm_phase(PG8_LAS unsigned char* lds, const Gemm g, const Sched& S, const Epi& E, const int tid) {
;     ...
;         for (int t = 0; t < nt; t += 2) {
;             const bool last = (t == nt - 2);
;             const char* a1 = cA + (size_t)(t + 1) * kstep;
;             const char* a2 = last ? nA : cA + (size_t)(t + 2) * kstep; const char* b2 = last ? nB : cB + (size_t)(t + 2) * kstep;
;             const char* a3 = a2 + kstep; const char* b3 = b2 + kstep;
;             if (last && has_next) S.a_ready(nxt);
;             if constexpr (SP2) {
;             PG8_LDB(B0, 0, 0); PG8_LDB(B1, 0, 1); PG8_SCHED; PG8_LDA(At, 0, 0); PG8_STAGE(PG8_SA(1, 1), a1 + hstep, voffA);
;             PG8_WAIT_V(8); PG8_WAIT_L(0); PG8_BAR; PG8_MMA(0, 0, At, B0); PG8_MMA(0, 1, At, B1); PG8_BAR; PG8_SCHED;
;             PG8_LDA(At, 0, 1); PG8_STAGE(PG8_SB(0, 0), b2, voffB); PG8_STAGE(PG8_SB(0, 1), b2 + hstep, voffB); PG8_STAGE(PG8_SA(0, 0), a2, voffA);
;             PG8_WAIT_V(8); PG8_WAIT_L(0); PG8_BAR; PG8_MMA(1, 0, At, B0); PG8_MMA(1, 1, At, B1); PG8_BAR; PG8_SCHED;
.LBB0_143:
	v_add_u32_e32 v138, 0x10000, v140
	ds_read_b128 v[142:145], v138
	ds_read_b128 v[146:149], v138 offset:1024
	ds_read_b128 v[150:153], v138 offset:2048
	ds_read_b128 v[154:157], v138 offset:3072
	v_add_u32_e32 v138, 0x14000, v140
	ds_read_b128 v[158:161], v138
	ds_read_b128 v[162:165], v138 offset:1024
	ds_read_b128 v[166:169], v138 offset:2048
	ds_read_b128 v[170:173], v138 offset:3072
	s_add_u32 s58, s44, 0xfffc0080
	s_addc_u32 s59, s45, -1
	s_add_i32 s72, 0, 0x10000
	s_cmp_eq_u32 s71, 12
	s_cselect_b32 s79, s17, s59
	s_cselect_b32 s78, s55, s58
	s_cselect_b32 s59, s15, s70
	s_cselect_b32 s58, s60, s62
	s_add_i32 s74, 0, 0x14000
	v_lshl_add_u64 v[138:139], s[44:45], 0, v[134:135]
	s_add_i32 m0, s38, 0xc000
	ds_read_b128 v[174:177], v141
	ds_read_b128 v[178:181], v141 offset:1024
	ds_read_b128 v[182:185], v141 offset:2048
	ds_read_b128 v[186:189], v141 offset:3072
	ds_read_b128 v[212:215], v141 offset:4096
	ds_read_b128 v[216:219], v141 offset:5120
	ds_read_b128 v[232:235], v141 offset:6144
	ds_read_b128 v[236:239], v141 offset:7168
	global_load_lds_dwordx4 v[138:139], off
	v_lshl_add_u64 v[138:139], s[44:45], 0, v[136:137]
	s_add_i32 m0, s38, 0xe000
	s_nop 0
	global_load_lds_dwordx4 v[138:139], off
	s_waitcnt vmcnt(8)
	s_waitcnt lgkmcnt(0)
	s_barrier
	s_setprio 1
	s_waitcnt lgkmcnt(0)
	v_mfma_f32_16x16x32_bf16 v[124:127], v[142:145], v[174:177], v[124:127]
	v_mfma_f32_16x16x32_bf16 v[116:119], v[150:153], v[174:177], v[116:119]
	v_mfma_f32_16x16x32_bf16 v[108:111], v[142:145], v[182:185], v[108:111]
	v_mfma_f32_16x16x32_bf16 v[100:103], v[150:153], v[182:185], v[100:103]
	v_mfma_f32_16x16x32_bf16 v[92:95], v[142:145], v[212:215], v[92:95]
	v_mfma_f32_16x16x32_bf16 v[84:87], v[150:153], v[212:215], v[84:87]
	v_mfma_f32_16x16x32_bf16 v[76:79], v[142:145], v[232:235], v[76:79]
	v_mfma_f32_16x16x32_bf16 v[68:71], v[150:153], v[232:235], v[68:71]
	v_mfma_f32_16x16x32_bf16 v[124:127], v[146:149], v[178:181], v[124:127]
	v_mfma_f32_16x16x32_bf16 v[116:119], v[154:157], v[178:181], v[116:119]
	v_mfma_f32_16x16x32_bf16 v[108:111], v[146:149], v[186:189], v[108:111]
	v_mfma_f32_16x16x32_bf16 v[100:103], v[154:157], v[186:189], v[100:103]
	v_mfma_f32_16x16x32_bf16 v[92:95], v[146:149], v[216:219], v[92:95]
	v_mfma_f32_16x16x32_bf16 v[84:87], v[154:157], v[216:219], v[84:87]
	v_mfma_f32_16x16x32_bf16 v[76:79], v[146:149], v[236:239], v[76:79]
	v_mfma_f32_16x16x32_bf16 v[68:71], v[154:157], v[236:239], v[68:71]
	s_setprio 0
	s_setprio 1
	v_mfma_f32_16x16x32_bf16 v[120:123], v[158:161], v[174:177], v[120:123]
	v_mfma_f32_16x16x32_bf16 v[112:115], v[166:169], v[174:177], v[112:115]
	v_mfma_f32_16x16x32_bf16 v[104:107], v[158:161], v[182:185], v[104:107]
	v_mfma_f32_16x16x32_bf16 v[96:99], v[166:169], v[182:185], v[96:99]
	v_mfma_f32_16x16x32_bf16 v[88:91], v[158:161], v[212:215], v[88:91]
	v_mfma_f32_16x16x32_bf16 v[80:83], v[166:169], v[212:215], v[80:83]
	v_mfma_f32_16x16x32_bf16 v[72:75], v[158:161], v[232:235], v[72:75]
	v_mfma_f32_16x16x32_bf16 v[64:67], v[166:169], v[232:235], v[64:67]
	v_mfma_f32_16x16x32_bf16 v[120:123], v[162:165], v[178:181], v[120:123]
	v_mfma_f32_16x16x32_bf16 v[112:115], v[170:173], v[178:181], v[112:115]
	v_mfma_f32_16x16x32_bf16 v[104:107], v[162:165], v[186:189], v[104:107]
	v_mfma_f32_16x16x32_bf16 v[96:99], v[170:173], v[186:189], v[96:99]
	v_mfma_f32_16x16x32_bf16 v[88:91], v[162:165], v[216:219], v[88:91]
	v_mfma_f32_16x16x32_bf16 v[80:83], v[170:173], v[216:219], v[80:83]
	v_mfma_f32_16x16x32_bf16 v[72:75], v[162:165], v[236:239], v[72:75]
	v_mfma_f32_16x16x32_bf16 v[64:67], v[170:173], v[236:239], v[64:67]
	s_setprio 0
	s_barrier
	s_add_i32 s72, s72, s34
	v_lshl_add_u64 v[138:139], s[58:59], 0, v[192:193]
	s_mov_b32 m0, s72
	ds_read_b128 v[174:177], v141 offset:16384
	ds_read_b128 v[178:181], v141 offset:17408
	ds_read_b128 v[182:185], v141 offset:18432
	ds_read_b128 v[186:189], v141 offset:19456
	ds_read_b128 v[212:215], v141 offset:20480
	ds_read_b128 v[216:219], v141 offset:21504
	ds_read_b128 v[232:235], v141 offset:22528
	ds_read_b128 v[236:239], v141 offset:23552
	global_load_lds_dwordx4 v[138:139], off
	s_add_i32 m0, s72, 0x2000
	s_add_u32 s72, s58, 0x40000
	v_lshl_add_u64 v[190:191], s[58:59], 0, v[128:129]
	s_addc_u32 s73, s59, 0
	s_add_i32 s74, s74, s34
	global_load_lds_dwordx4 v[190:191], off
	v_lshl_add_u64 v[194:195], s[72:73], 0, v[192:193]
	s_mov_b32 m0, s74
	v_lshl_add_u64 v[196:197], s[78:79], 0, v[130:131]
	global_load_lds_dwordx4 v[194:195], off
	v_lshl_add_u64 v[194:195], s[72:73], 0, v[128:129]
	s_add_i32 m0, s74, 0x2000
	s_nop 0
	global_load_lds_dwordx4 v[194:195], off
	v_lshl_add_u64 v[194:195], s[78:79], 0, v[132:133]
	s_mov_b32 m0, s38
	s_nop 0
	global_load_lds_dwordx4 v[194:195], off
	s_mov_b32 m0, s40
	s_nop 0
	global_load_lds_dwordx4 v[196:197], off
	s_waitcnt vmcnt(8)
	s_waitcnt lgkmcnt(0)
	s_barrier
; #define PG8_STAGE(bufoff, gbase, voff) do { _Pragma("unroll") for (int _i = 0; _i < 2; ++_i) \
;         __builtin_amdgcn_global_load_lds((const unsigned*)((const char*)(gbase) + (voff)[_i]), (PG8_LAS unsigned*)(lds + (bufoff) + ldsw + _i * 8192), 16, 0, 0); } while (0)
; #define PG8_LDA(dst, b, h) do { _Pragma("unroll") for (int m = 0; m < 4; ++m) _Pragma("unroll") for (int k = 0; k < 2; ++k) dst[m][k] = *(const PG8_LAS bf16x8*)(lds + PG8_SA(b, h) + aoff + m * 2048 + k * 1024); } while (0)
; #define PG8_LDB(dst, b, h) do { _Pragma("unroll") for (int n = 0; n < 2; ++n) _Pragma("unroll") for (int k = 0; k < 2; ++k) dst[n][k] = *(const PG8_LAS bf16x8*)(lds + PG8_SB(b, h) + boff + n * 2048 + k * 1024); } while (0)
; #define PG8_MMA(ai, bj, At, Bt) do { __builtin_amdgcn_s_setprio(1); _Pragma("unroll") for (int m = 0; m < 4; ++m) _Pragma("unroll") for (int n = 0; n < 2; ++n) _Pragma("unroll") for (int k = 0; k < 2; ++k) \
;         acc[ai][bj][m][n] = __builtin_amdgcn_mfma_f32_16x16x32_bf16(Bt[n][k], At[m][k], acc[ai][bj][m][n], 0, 0, 0); __builtin_amdgcn_s_setprio(0); } while (0)
; #define PG8_WAIT_V(n) asm volatile("s_waitcnt vmcnt(" #n ")" ::: "memory")
; #define PG8_WAIT_L(n) asm volatile("s_waitcnt lgkmcnt(" #n ")" ::: "memory")
; #define PG8_BAR __builtin_amdgcn_s_barrier()
; #define PG8_SCHED __builtin_amdgcn_sched_barrier(0)
; template <class Epi, class Sched, bool ALIGN_EPI = false, bool SP2 = false>
; __device__ __forceinline__ void gemm_phase(PG8_LAS unsigned char* lds, const Gemm g, const Sched& S, const Epi& E, const int tid) {
;     ...
;             PG8_WAIT_V(8); PG8_WAIT_L(0); PG8_BAR; PG8_MMA(1, 0, At, B0); PG8_MMA(1, 1, At, B1); PG8_BAR; PG8_SCHED;
;             PG8_LDB(B0, 1, 0); PG8_LDB(B1, 1, 1); PG8_SCHED; PG8_LDA(At, 1, 0); PG8_STAGE(PG8_SA(0, 1), a2 + hstep, voffA);
;             PG8_WAIT_V(8); PG8_WAIT_L(0); PG8_BAR; PG8_MMA(0, 0, At, B0); PG8_MMA(0, 1, At, B1); PG8_BAR; PG8_SCHED;
	s_setprio 1
	s_waitcnt lgkmcnt(0)
	v_mfma_f32_16x16x32_bf16 v[60:63], v[142:145], v[174:177], v[60:63]
	v_mfma_f32_16x16x32_bf16 v[52:55], v[150:153], v[174:177], v[52:55]
	v_mfma_f32_16x16x32_bf16 v[44:47], v[142:145], v[182:185], v[44:47]
	v_mfma_f32_16x16x32_bf16 v[36:39], v[150:153], v[182:185], v[36:39]
	v_mfma_f32_16x16x32_bf16 v[28:31], v[142:145], v[212:215], v[28:31]
	v_mfma_f32_16x16x32_bf16 v[20:23], v[150:153], v[212:215], v[20:23]
	v_mfma_f32_16x16x32_bf16 v[12:15], v[142:145], v[232:235], v[12:15]
	v_mfma_f32_16x16x32_bf16 v[4:7], v[150:153], v[232:235], v[4:7]
	v_mfma_f32_16x16x32_bf16 v[60:63], v[146:149], v[178:181], v[60:63]
	v_mfma_f32_16x16x32_bf16 v[52:55], v[154:157], v[178:181], v[52:55]
	v_mfma_f32_16x16x32_bf16 v[44:47], v[146:149], v[186:189], v[44:47]
	v_mfma_f32_16x16x32_bf16 v[36:39], v[154:157], v[186:189], v[36:39]
	v_mfma_f32_16x16x32_bf16 v[28:31], v[146:149], v[216:219], v[28:31]
	v_mfma_f32_16x16x32_bf16 v[20:23], v[154:157], v[216:219], v[20:23]
	v_mfma_f32_16x16x32_bf16 v[12:15], v[146:149], v[236:239], v[12:15]
	v_mfma_f32_16x16x32_bf16 v[4:7], v[154:157], v[236:239], v[4:7]
	s_setprio 0
	s_setprio 1
	v_mfma_f32_16x16x32_bf16 v[56:59], v[158:161], v[174:177], v[56:59]
	v_mfma_f32_16x16x32_bf16 v[48:51], v[166:169], v[174:177], v[48:51]
	v_mfma_f32_16x16x32_bf16 v[40:43], v[158:161], v[182:185], v[40:43]
	v_mfma_f32_16x16x32_bf16 v[32:35], v[166:169], v[182:185], v[32:35]
	v_mfma_f32_16x16x32_bf16 v[24:27], v[158:161], v[212:215], v[24:27]
	v_mfma_f32_16x16x32_bf16 v[16:19], v[166:169], v[212:215], v[16:19]
	v_mfma_f32_16x16x32_bf16 v[8:11], v[158:161], v[232:235], v[8:11]
	v_mfma_f32_16x16x32_bf16 v[0:3], v[166:169], v[232:235], v[0:3]
	v_mfma_f32_16x16x32_bf16 v[56:59], v[162:165], v[178:181], v[56:59]
	v_mfma_f32_16x16x32_bf16 v[48:51], v[170:173], v[178:181], v[48:51]
	v_mfma_f32_16x16x32_bf16 v[40:43], v[162:165], v[186:189], v[40:43]
	v_mfma_f32_16x16x32_bf16 v[32:35], v[170:173], v[186:189], v[32:35]
	v_mfma_f32_16x16x32_bf16 v[24:27], v[162:165], v[216:219], v[24:27]
	v_mfma_f32_16x16x32_bf16 v[16:19], v[170:173], v[216:219], v[16:19]
	v_mfma_f32_16x16x32_bf16 v[8:11], v[162:165], v[236:239], v[8:11]
	v_mfma_f32_16x16x32_bf16 v[0:3], v[170:173], v[236:239], v[0:3]
	s_setprio 0
	s_barrier
	s_add_i32 s74, 0, 0x18000
	s_add_i32 s75, 0, 0x1c000
	v_add_u32_e32 v154, s74, v140
	v_add_u32_e32 v170, s75, v140
	ds_read_b128 v[142:145], v154
	ds_read_b128 v[146:149], v154 offset:1024
	ds_read_b128 v[150:153], v154 offset:2048
	ds_read_b128 v[154:157], v154 offset:3072
	ds_read_b128 v[158:161], v170
	ds_read_b128 v[162:165], v170 offset:1024
	ds_read_b128 v[166:169], v170 offset:2048
	ds_read_b128 v[170:173], v170 offset:3072
	s_add_u32 s72, s78, 0x40000
	s_addc_u32 s73, s79, 0
	s_mov_b32 m0, s41
	v_lshl_add_u64 v[202:203], s[72:73], 0, v[132:133]
	ds_read_b128 v[174:177], v141 offset:32768
	ds_read_b128 v[178:181], v141 offset:33792
	ds_read_b128 v[182:185], v141 offset:34816
	ds_read_b128 v[186:189], v141 offset:35840
	ds_read_b128 v[212:215], v141 offset:36864
	ds_read_b128 v[216:219], v141 offset:37888
	ds_read_b128 v[232:235], v141 offset:38912
	ds_read_b128 v[236:239], v141 offset:39936
	global_load_lds_dwordx4 v[202:203], off
	v_lshl_add_u64 v[202:203], s[72:73], 0, v[130:131]
	s_mov_b32 m0, s46
	s_nop 0
	global_load_lds_dwordx4 v[202:203], off
	s_waitcnt vmcnt(8)
	s_waitcnt lgkmcnt(0)
	s_barrier
	s_setprio 1
	s_waitcnt lgkmcnt(0)
	v_mfma_f32_16x16x32_bf16 v[124:127], v[142:145], v[174:177], v[124:127]
	v_mfma_f32_16x16x32_bf16 v[116:119], v[150:153], v[174:177], v[116:119]
	v_mfma_f32_16x16x32_bf16 v[108:111], v[142:145], v[182:185], v[108:111]
	v_mfma_f32_16x16x32_bf16 v[100:103], v[150:153], v[182:185], v[100:103]
	v_mfma_f32_16x16x32_bf16 v[92:95], v[142:145], v[212:215], v[92:95]
	v_mfma_f32_16x16x32_bf16 v[84:87], v[150:153], v[212:215], v[84:87]
	v_mfma_f32_16x16x32_bf16 v[76:79], v[142:145], v[232:235], v[76:79]
	v_mfma_f32_16x16x32_bf16 v[68:71], v[150:153], v[232:235], v[68:71]
	v_mfma_f32_16x16x32_bf16 v[124:127], v[146:149], v[178:181], v[124:127]
	v_mfma_f32_16x16x32_bf16 v[116:119], v[154:157], v[178:181], v[116:119]
	v_mfma_f32_16x16x32_bf16 v[108:111], v[146:149], v[186:189], v[108:111]
	v_mfma_f32_16x16x32_bf16 v[100:103], v[154:157], v[186:189], v[100:103]
	v_mfma_f32_16x16x32_bf16 v[92:95], v[146:149], v[216:219], v[92:95]
	v_mfma_f32_16x16x32_bf16 v[84:87], v[154:157], v[216:219], v[84:87]
	v_mfma_f32_16x16x32_bf16 v[76:79], v[146:149], v[236:239], v[76:79]
	v_mfma_f32_16x16x32_bf16 v[68:71], v[154:157], v[236:239], v[68:71]
	s_setprio 0
	s_setprio 1
	v_mfma_f32_16x16x32_bf16 v[120:123], v[158:161], v[174:177], v[120:123]
	v_mfma_f32_16x16x32_bf16 v[112:115], v[166:169], v[174:177], v[112:115]
	v_mfma_f32_16x16x32_bf16 v[104:107], v[158:161], v[182:185], v[104:107]
	v_mfma_f32_16x16x32_bf16 v[96:99], v[166:169], v[182:185], v[96:99]
	v_mfma_f32_16x16x32_bf16 v[88:91], v[158:161], v[212:215], v[88:91]
	v_mfma_f32_16x16x32_bf16 v[80:83], v[166:169], v[212:215], v[80:83]
	v_mfma_f32_16x16x32_bf16 v[72:75], v[158:161], v[232:235], v[72:75]
	v_mfma_f32_16x16x32_bf16 v[64:67], v[166:169], v[232:235], v[64:67]
	v_mfma_f32_16x16x32_bf16 v[120:123], v[162:165], v[178:181], v[120:123]
	v_mfma_f32_16x16x32_bf16 v[112:115], v[170:173], v[178:181], v[112:115]
	v_mfma_f32_16x16x32_bf16 v[104:107], v[162:165], v[186:189], v[104:107]
	v_mfma_f32_16x16x32_bf16 v[96:99], v[170:173], v[186:189], v[96:99]
	v_mfma_f32_16x16x32_bf16 v[88:91], v[162:165], v[216:219], v[88:91]
	v_mfma_f32_16x16x32_bf16 v[80:83], v[170:173], v[216:219], v[80:83]
	v_mfma_f32_16x16x32_bf16 v[72:75], v[162:165], v[236:239], v[72:75]
	v_mfma_f32_16x16x32_bf16 v[64:67], v[170:173], v[236:239], v[64:67]
	s_setprio 0
	s_barrier
; #define PG8_STAGE(bufoff, gbase, voff) do { _Pragma("unroll") for (int _i = 0; _i < 2; ++_i) \
;         __builtin_amdgcn_global_load_lds((const unsigned*)((const char*)(gbase) + (voff)[_i]), (PG8_LAS unsigned*)(lds + (bufoff) + ldsw + _i * 8192), 16, 0, 0); } while (0)
; #define PG8_LDA(dst, b, h) do { _Pragma("unroll") for (int m = 0; m < 4; ++m) _Pragma("unroll") for (int k = 0; k < 2; ++k) dst[m][k] = *(const PG8_LAS bf16x8*)(lds + PG8_SA(b, h) + aoff + m * 2048 + k * 1024); } while (0)
; #define PG8_MMA(ai, bj, At, Bt) do { __builtin_amdgcn_s_setprio(1); _Pragma("unroll") for (int m = 0; m < 4; ++m) _Pragma("unroll") for (int n = 0; n < 2; ++n) _Pragma("unroll") for (int k = 0; k < 2; ++k) \
;         acc[ai][bj][m][n] = __builtin_amdgcn_mfma_f32_16x16x32_bf16(Bt[n][k], At[m][k], acc[ai][bj][m][n], 0, 0, 0); __builtin_amdgcn_s_setprio(0); } while (0)
; #define PG8_WAIT_V(n) asm volatile("s_waitcnt vmcnt(" #n ")" ::: "memory")
; #define PG8_WAIT_L(n) asm volatile("s_waitcnt lgkmcnt(" #n ")" ::: "memory")
; #define PG8_BAR __builtin_amdgcn_s_barrier()
; #define PG8_SCHED __builtin_amdgcn_sched_barrier(0)
; template <class Epi, class Sched, bool ALIGN_EPI = false, bool SP2 = false>
; __device__ __forceinline__ void gemm_phase(PG8_LAS unsigned char* lds, const Gemm g, const Sched& S, const Epi& E, const int tid) {
;     ...
;             PG8_LDA(At, 1, 1); PG8_STAGE(PG8_SB(1, 0), b3, voffB); PG8_STAGE(PG8_SB(1, 1), b3 + hstep, voffB); PG8_STAGE(PG8_SA(1, 0), a3, voffA);
;             PG8_WAIT_V(8); PG8_WAIT_L(0); PG8_BAR; PG8_MMA(1, 0, At, B0); PG8_MMA(1, 1, At, B1); PG8_BAR; PG8_SCHED;
;     ...
;         if constexpr (ALIGN_EPI) { if (wr == 0) PG8_BAR; }
	s_add_i32 s72, s74, s34
	v_lshl_add_u64 v[138:139], v[138:139], 0, s[36:37]
	s_mov_b32 m0, s72
	ds_read_b128 v[174:177], v141 offset:49152
	ds_read_b128 v[178:181], v141 offset:50176
	ds_read_b128 v[182:185], v141 offset:51200
	ds_read_b128 v[186:189], v141 offset:52224
	ds_read_b128 v[212:215], v141 offset:53248
	ds_read_b128 v[216:219], v141 offset:54272
	ds_read_b128 v[232:235], v141 offset:55296
	ds_read_b128 v[236:239], v141 offset:56320
	global_load_lds_dwordx4 v[138:139], off
	s_add_i32 m0, s72, 0x2000
	s_add_u32 s58, s58, 0x40080
	v_lshl_add_u64 v[138:139], v[190:191], 0, s[36:37]
	s_addc_u32 s59, s59, 0
	s_add_i32 s72, s75, s34
	global_load_lds_dwordx4 v[138:139], off
	v_lshl_add_u64 v[138:139], s[58:59], 0, v[192:193]
	s_mov_b32 m0, s72
	s_nop 0
	global_load_lds_dwordx4 v[138:139], off
	v_lshl_add_u64 v[138:139], s[58:59], 0, v[128:129]
	s_add_i32 m0, s72, 0x2000
	s_nop 0
	global_load_lds_dwordx4 v[138:139], off
	v_lshl_add_u64 v[138:139], v[194:195], 0, s[36:37]
	s_mov_b32 m0, s47
	s_nop 0
	global_load_lds_dwordx4 v[138:139], off
	v_lshl_add_u64 v[138:139], v[196:197], 0, s[36:37]
	s_mov_b32 m0, s52
	s_nop 0
	global_load_lds_dwordx4 v[138:139], off
	s_add_i32 s71, s71, 2
	s_add_u32 s44, s44, 0x100
	s_addc_u32 s45, s45, 0
	s_add_u32 s62, s62, 0x100
	s_addc_u32 s70, s70, 0
	s_cmp_gt_u32 s71, 13
	s_waitcnt vmcnt(8)
	s_waitcnt lgkmcnt(0)
	s_barrier
	s_setprio 1
	s_waitcnt lgkmcnt(0)
	v_mfma_f32_16x16x32_bf16 v[60:63], v[142:145], v[174:177], v[60:63]
	v_mfma_f32_16x16x32_bf16 v[52:55], v[150:153], v[174:177], v[52:55]
	v_mfma_f32_16x16x32_bf16 v[44:47], v[142:145], v[182:185], v[44:47]
	v_mfma_f32_16x16x32_bf16 v[36:39], v[150:153], v[182:185], v[36:39]
	v_mfma_f32_16x16x32_bf16 v[28:31], v[142:145], v[212:215], v[28:31]
	v_mfma_f32_16x16x32_bf16 v[20:23], v[150:153], v[212:215], v[20:23]
	v_mfma_f32_16x16x32_bf16 v[12:15], v[142:145], v[232:235], v[12:15]
	v_mfma_f32_16x16x32_bf16 v[4:7], v[150:153], v[232:235], v[4:7]
	v_mfma_f32_16x16x32_bf16 v[60:63], v[146:149], v[178:181], v[60:63]
	v_mfma_f32_16x16x32_bf16 v[52:55], v[154:157], v[178:181], v[52:55]
	v_mfma_f32_16x16x32_bf16 v[44:47], v[146:149], v[186:189], v[44:47]
	v_mfma_f32_16x16x32_bf16 v[36:39], v[154:157], v[186:189], v[36:39]
	v_mfma_f32_16x16x32_bf16 v[28:31], v[146:149], v[216:219], v[28:31]
	v_mfma_f32_16x16x32_bf16 v[20:23], v[154:157], v[216:219], v[20:23]
	v_mfma_f32_16x16x32_bf16 v[12:15], v[146:149], v[236:239], v[12:15]
	v_mfma_f32_16x16x32_bf16 v[4:7], v[154:157], v[236:239], v[4:7]
	s_setprio 0
	s_setprio 1
	v_mfma_f32_16x16x32_bf16 v[56:59], v[158:161], v[174:177], v[56:59]
	v_mfma_f32_16x16x32_bf16 v[48:51], v[166:169], v[174:177], v[48:51]
	v_mfma_f32_16x16x32_bf16 v[40:43], v[158:161], v[182:185], v[40:43]
	v_mfma_f32_16x16x32_bf16 v[32:35], v[166:169], v[182:185], v[32:35]
	v_mfma_f32_16x16x32_bf16 v[24:27], v[158:161], v[212:215], v[24:27]
	v_mfma_f32_16x16x32_bf16 v[16:19], v[166:169], v[212:215], v[16:19]
	v_mfma_f32_16x16x32_bf16 v[8:11], v[158:161], v[232:235], v[8:11]
	v_mfma_f32_16x16x32_bf16 v[0:3], v[166:169], v[232:235], v[0:3]
	v_mfma_f32_16x16x32_bf16 v[56:59], v[162:165], v[178:181], v[56:59]
	v_mfma_f32_16x16x32_bf16 v[48:51], v[170:173], v[178:181], v[48:51]
	v_mfma_f32_16x16x32_bf16 v[40:43], v[162:165], v[186:189], v[40:43]
	v_mfma_f32_16x16x32_bf16 v[32:35], v[170:173], v[186:189], v[32:35]
	v_mfma_f32_16x16x32_bf16 v[24:27], v[162:165], v[216:219], v[24:27]
	v_mfma_f32_16x16x32_bf16 v[16:19], v[170:173], v[216:219], v[16:19]
	v_mfma_f32_16x16x32_bf16 v[8:11], v[162:165], v[236:239], v[8:11]
	v_mfma_f32_16x16x32_bf16 v[0:3], v[170:173], v[236:239], v[0:3]
	s_setprio 0
	s_barrier
	s_cbranch_scc0 .LBB0_143
	s_and_b64 vcc, exec, s[10:11]
	s_cbranch_vccz .LBB0_146
	s_barrier

; #define PG8_STAGE(bufoff, gbase, voff) do { _Pragma("unroll") for (int _i = 0; _i < 2; ++_i) \
;         __builtin_amdgcn_global_load_lds((const unsigned*)((const char*)(gbase) + (voff)[_i]), (PG8_LAS unsigned*)(lds + (bufoff) + ldsw + _i * 8192), 16, 0, 0); } while (0)
; #define PG8_LDA(dst, b, h) do { _Pragma("unroll") for (int m = 0; m < 4; ++m) _Pragma("unroll") for (int k = 0; k < 2; ++k) dst[m][k] = *(const PG8_LAS bf16x8*)(lds + PG8_SA(b, h) + aoff + m * 2048 + k * 1024); } while (0)
; #define PG8_LDB(dst, b, h) do { _Pragma("unroll") for (int n = 0; n < 2; ++n) _Pragma("unroll") for (int k = 0; k < 2; ++k) dst[n][k] = *(const PG8_LAS bf16x8*)(lds + PG8_SB(b, h) + boff + n * 2048 + k * 1024); } while (0)
; #define PG8_MMA(ai, bj, At, Bt) do { __builtin_amdgcn_s_setprio(1); _Pragma("unroll") for (int m = 0; m < 4; ++m) _Pragma("unroll") for (int n = 0; n < 2; ++n) _Pragma("unroll") for (int k = 0; k < 2; ++k) \
;         acc[ai][bj][m][n] = __builtin_amdgcn_mfma_f32_16x16x32_bf16(Bt[n][k], At[m][k], acc[ai][bj][m][n], 0, 0, 0); __builtin_amdgcn_s_setprio(0); } while (0)
; #define PG8_WAIT_V(n) asm volatile("s_waitcnt vmcnt(" #n ")" ::: "memory")
; #define PG8_BAR __builtin_amdgcn_s_barrier()
; template <class Epi, class Sched, bool ALIGN_EPI = false, bool SP2 = false>
; __device__ __forceinline__ void gemm_phase(PG8_LAS unsigned char* lds, const Gemm g, const Sched& S, const Epi& E, const int tid) {
;     ...
;         for (int t = 0; t < nt; t += 2) {
;             const bool last = (t == nt - 2);
;             const char* a1 = cA + (size_t)(t + 1) * kstep;
;             const char* a2 = last ? nA : cA + (size_t)(t + 2) * kstep; const char* b2 = last ? nB : cB + (size_t)(t + 2) * kstep;
;             const char* a3 = a2 + kstep; const char* b3 = b2 + kstep;
;             if (last && has_next) S.a_ready(nxt);
;             if constexpr (SP2) {
;             PG8_LDB(B0, 0, 0); PG8_LDB(B1, 0, 1); PG8_SCHED; PG8_LDA(At, 0, 0); PG8_STAGE(PG8_SA(1, 1), a1 + hstep, voffA);
;             PG8_WAIT_V(8); PG8_WAIT_L(0); PG8_BAR; PG8_MMA(0, 0, At, B0); PG8_MMA(0, 1, At, B1); PG8_BAR; PG8_SCHED;
;             PG8_LDA(At, 0, 1); PG8_STAGE(PG8_SB(0, 0), b2, voffB); PG8_STAGE(PG8_SB(0, 1), b2 + hstep, voffB); PG8_STAGE(PG8_SA(0, 0), a2, voffA);
;             PG8_WAIT_V(8); PG8_WAIT_L(0); PG8_BAR; PG8_MMA(1, 0, At, B0); PG8_MMA(1, 1, At, B1); PG8_BAR; PG8_SCHED;
.LBB0_183:
	v_add_u32_e32 v154, 0x10000, v140
	v_add_u32_e32 v170, 0x14000, v140
	ds_read_b128 v[142:145], v154
	ds_read_b128 v[146:149], v154 offset:1024
	ds_read_b128 v[150:153], v154 offset:2048
	ds_read_b128 v[154:157], v154 offset:3072
	ds_read_b128 v[158:161], v170
	ds_read_b128 v[162:165], v170 offset:1024
	ds_read_b128 v[166:169], v170 offset:2048
	ds_read_b128 v[170:173], v170 offset:3072
	s_add_u32 s28, s22, 0xfffc0080
	s_addc_u32 s29, s23, -1
	s_add_i32 s71, 0, 0x10000
	s_cmp_eq_u32 s70, 12
	s_cselect_b32 s45, s17, s29
	s_cselect_b32 s44, s58, s28
	s_cselect_b32 s29, s13, s62
	s_cselect_b32 s28, s59, s60
	s_add_i32 s74, 0, 0x14000
	v_lshl_add_u64 v[190:191], s[22:23], 0, v[136:137]
	s_add_i32 m0, s15, 0xc000
	ds_read_b128 v[174:177], v141
	ds_read_b128 v[178:181], v141 offset:1024
	ds_read_b128 v[182:185], v141 offset:2048
	ds_read_b128 v[186:189], v141 offset:3072
	ds_read_b128 v[212:215], v141 offset:4096
	ds_read_b128 v[216:219], v141 offset:5120
	ds_read_b128 v[232:235], v141 offset:6144
	ds_read_b128 v[236:239], v141 offset:7168
	global_load_lds_dwordx4 v[190:191], off
	v_lshl_add_u64 v[190:191], s[22:23], 0, v[138:139]
	s_add_i32 m0, s15, 0xe000
	s_nop 0
	global_load_lds_dwordx4 v[190:191], off
	s_waitcnt vmcnt(8)
	s_waitcnt lgkmcnt(0)
	s_barrier
	s_setprio 1
	s_waitcnt lgkmcnt(0)
	v_mfma_f32_16x16x32_bf16 v[124:127], v[142:145], v[174:177], v[124:127]
	v_mfma_f32_16x16x32_bf16 v[120:123], v[150:153], v[174:177], v[120:123]
	v_mfma_f32_16x16x32_bf16 v[116:119], v[142:145], v[182:185], v[116:119]
	v_mfma_f32_16x16x32_bf16 v[112:115], v[150:153], v[182:185], v[112:115]
	v_mfma_f32_16x16x32_bf16 v[100:103], v[142:145], v[212:215], v[100:103]
	v_mfma_f32_16x16x32_bf16 v[96:99], v[150:153], v[212:215], v[96:99]
	v_mfma_f32_16x16x32_bf16 v[84:87], v[142:145], v[232:235], v[84:87]
	v_mfma_f32_16x16x32_bf16 v[80:83], v[150:153], v[232:235], v[80:83]
	v_mfma_f32_16x16x32_bf16 v[124:127], v[146:149], v[178:181], v[124:127]
	v_mfma_f32_16x16x32_bf16 v[120:123], v[154:157], v[178:181], v[120:123]
	v_mfma_f32_16x16x32_bf16 v[116:119], v[146:149], v[186:189], v[116:119]
	v_mfma_f32_16x16x32_bf16 v[112:115], v[154:157], v[186:189], v[112:115]
	v_mfma_f32_16x16x32_bf16 v[100:103], v[146:149], v[216:219], v[100:103]
	v_mfma_f32_16x16x32_bf16 v[96:99], v[154:157], v[216:219], v[96:99]
	v_mfma_f32_16x16x32_bf16 v[84:87], v[146:149], v[236:239], v[84:87]
	v_mfma_f32_16x16x32_bf16 v[80:83], v[154:157], v[236:239], v[80:83]
	s_setprio 0
	s_setprio 1
	v_mfma_f32_16x16x32_bf16 v[108:111], v[158:161], v[174:177], v[108:111]
	v_mfma_f32_16x16x32_bf16 v[104:107], v[166:169], v[174:177], v[104:107]
	v_mfma_f32_16x16x32_bf16 v[92:95], v[158:161], v[182:185], v[92:95]
	v_mfma_f32_16x16x32_bf16 v[88:91], v[166:169], v[182:185], v[88:91]
	v_mfma_f32_16x16x32_bf16 v[76:79], v[158:161], v[212:215], v[76:79]
	v_mfma_f32_16x16x32_bf16 v[72:75], v[166:169], v[212:215], v[72:75]
	v_mfma_f32_16x16x32_bf16 v[68:71], v[158:161], v[232:235], v[68:71]
	v_mfma_f32_16x16x32_bf16 v[64:67], v[166:169], v[232:235], v[64:67]
	v_mfma_f32_16x16x32_bf16 v[108:111], v[162:165], v[178:181], v[108:111]
	v_mfma_f32_16x16x32_bf16 v[104:107], v[170:173], v[178:181], v[104:107]
	v_mfma_f32_16x16x32_bf16 v[92:95], v[162:165], v[186:189], v[92:95]
	v_mfma_f32_16x16x32_bf16 v[88:91], v[170:173], v[186:189], v[88:91]
	v_mfma_f32_16x16x32_bf16 v[76:79], v[162:165], v[216:219], v[76:79]
	v_mfma_f32_16x16x32_bf16 v[72:75], v[170:173], v[216:219], v[72:75]
	v_mfma_f32_16x16x32_bf16 v[68:71], v[162:165], v[236:239], v[68:71]
	v_mfma_f32_16x16x32_bf16 v[64:67], v[170:173], v[236:239], v[64:67]
	s_setprio 0
	s_barrier
	s_add_i32 s71, s71, s38
	v_lshl_add_u64 v[190:191], s[28:29], 0, v[192:193]
	s_mov_b32 m0, s71
	ds_read_b128 v[174:177], v141 offset:16384
	ds_read_b128 v[178:181], v141 offset:17408
	ds_read_b128 v[182:185], v141 offset:18432
	ds_read_b128 v[186:189], v141 offset:19456
	ds_read_b128 v[212:215], v141 offset:20480
	ds_read_b128 v[216:219], v141 offset:21504
	ds_read_b128 v[232:235], v141 offset:22528
	ds_read_b128 v[236:239], v141 offset:23552
	global_load_lds_dwordx4 v[190:191], off
	s_add_i32 m0, s71, 0x2000
	s_add_u32 s72, s28, 0x40000
	v_lshl_add_u64 v[194:195], s[28:29], 0, v[132:133]
	s_addc_u32 s73, s29, 0
	s_add_i32 s71, s74, s38
	global_load_lds_dwordx4 v[194:195], off
	v_lshl_add_u64 v[196:197], s[72:73], 0, v[192:193]
	s_mov_b32 m0, s71
	v_lshl_add_u64 v[202:203], s[44:45], 0, v[130:131]
	global_load_lds_dwordx4 v[196:197], off
	v_lshl_add_u64 v[196:197], s[72:73], 0, v[132:133]
	s_add_i32 m0, s71, 0x2000
	s_nop 0
	global_load_lds_dwordx4 v[196:197], off
	v_lshl_add_u64 v[196:197], s[44:45], 0, v[128:129]
	s_mov_b32 m0, s15
	s_nop 0
	global_load_lds_dwordx4 v[196:197], off
	s_mov_b32 m0, s40
	s_nop 0
	global_load_lds_dwordx4 v[202:203], off
	s_waitcnt vmcnt(8)
	s_waitcnt lgkmcnt(0)
	s_barrier
; #define PG8_STAGE(bufoff, gbase, voff) do { _Pragma("unroll") for (int _i = 0; _i < 2; ++_i) \
;         __builtin_amdgcn_global_load_lds((const unsigned*)((const char*)(gbase) + (voff)[_i]), (PG8_LAS unsigned*)(lds + (bufoff) + ldsw + _i * 8192), 16, 0, 0); } while (0)
; #define PG8_LDA(dst, b, h) do { _Pragma("unroll") for (int m = 0; m < 4; ++m) _Pragma("unroll") for (int k = 0; k < 2; ++k) dst[m][k] = *(const PG8_LAS bf16x8*)(lds + PG8_SA(b, h) + aoff + m * 2048 + k * 1024); } while (0)
; #define PG8_LDB(dst, b, h) do { _Pragma("unroll") for (int n = 0; n < 2; ++n) _Pragma("unroll") for (int k = 0; k < 2; ++k) dst[n][k] = *(const PG8_LAS bf16x8*)(lds + PG8_SB(b, h) + boff + n * 2048 + k * 1024); } while (0)
; #define PG8_MMA(ai, bj, At, Bt) do { __builtin_amdgcn_s_setprio(1); _Pragma("unroll") for (int m = 0; m < 4; ++m) _Pragma("unroll") for (int n = 0; n < 2; ++n) _Pragma("unroll") for (int k = 0; k < 2; ++k) \
;         acc[ai][bj][m][n] = __builtin_amdgcn_mfma_f32_16x16x32_bf16(Bt[n][k], At[m][k], acc[ai][bj][m][n], 0, 0, 0); __builtin_amdgcn_s_setprio(0); } while (0)
; #define PG8_WAIT_V(n) asm volatile("s_waitcnt vmcnt(" #n ")" ::: "memory")
; #define PG8_WAIT_L(n) asm volatile("s_waitcnt lgkmcnt(" #n ")" ::: "memory")
; #define PG8_BAR __builtin_amdgcn_s_barrier()
; #define PG8_SCHED __builtin_amdgcn_sched_barrier(0)
; template <class Epi, class Sched, bool ALIGN_EPI = false, bool SP2 = false>
; __device__ __forceinline__ void gemm_phase(PG8_LAS unsigned char* lds, const Gemm g, const Sched& S, const Epi& E, const int tid) {
;     ...
;             PG8_WAIT_V(8); PG8_WAIT_L(0); PG8_BAR; PG8_MMA(1, 0, At, B0); PG8_MMA(1, 1, At, B1); PG8_BAR; PG8_SCHED;
;             PG8_LDB(B0, 1, 0); PG8_LDB(B1, 1, 1); PG8_SCHED; PG8_LDA(At, 1, 0); PG8_STAGE(PG8_SA(0, 1), a2 + hstep, voffA);
;             PG8_WAIT_V(8); PG8_WAIT_L(0); PG8_BAR; PG8_MMA(0, 0, At, B0); PG8_MMA(0, 1, At, B1); PG8_BAR; PG8_SCHED;
	s_setprio 1
	s_waitcnt lgkmcnt(0)
	v_mfma_f32_16x16x32_bf16 v[60:63], v[142:145], v[174:177], v[60:63]
	v_mfma_f32_16x16x32_bf16 v[56:59], v[150:153], v[174:177], v[56:59]
	v_mfma_f32_16x16x32_bf16 v[52:55], v[142:145], v[182:185], v[52:55]
	v_mfma_f32_16x16x32_bf16 v[48:51], v[150:153], v[182:185], v[48:51]
	v_mfma_f32_16x16x32_bf16 v[36:39], v[142:145], v[212:215], v[36:39]
	v_mfma_f32_16x16x32_bf16 v[32:35], v[150:153], v[212:215], v[32:35]
	v_mfma_f32_16x16x32_bf16 v[20:23], v[142:145], v[232:235], v[20:23]
	v_mfma_f32_16x16x32_bf16 v[16:19], v[150:153], v[232:235], v[16:19]
	v_mfma_f32_16x16x32_bf16 v[60:63], v[146:149], v[178:181], v[60:63]
	v_mfma_f32_16x16x32_bf16 v[56:59], v[154:157], v[178:181], v[56:59]
	v_mfma_f32_16x16x32_bf16 v[52:55], v[146:149], v[186:189], v[52:55]
	v_mfma_f32_16x16x32_bf16 v[48:51], v[154:157], v[186:189], v[48:51]
	v_mfma_f32_16x16x32_bf16 v[36:39], v[146:149], v[216:219], v[36:39]
	v_mfma_f32_16x16x32_bf16 v[32:35], v[154:157], v[216:219], v[32:35]
	v_mfma_f32_16x16x32_bf16 v[20:23], v[146:149], v[236:239], v[20:23]
	v_mfma_f32_16x16x32_bf16 v[16:19], v[154:157], v[236:239], v[16:19]
	s_setprio 0
	s_setprio 1
	v_mfma_f32_16x16x32_bf16 v[44:47], v[158:161], v[174:177], v[44:47]
	v_mfma_f32_16x16x32_bf16 v[40:43], v[166:169], v[174:177], v[40:43]
	v_mfma_f32_16x16x32_bf16 v[28:31], v[158:161], v[182:185], v[28:31]
	v_mfma_f32_16x16x32_bf16 v[24:27], v[166:169], v[182:185], v[24:27]
	v_mfma_f32_16x16x32_bf16 v[12:15], v[158:161], v[212:215], v[12:15]
	v_mfma_f32_16x16x32_bf16 v[8:11], v[166:169], v[212:215], v[8:11]
	v_mfma_f32_16x16x32_bf16 v[4:7], v[158:161], v[232:235], v[4:7]
	v_mfma_f32_16x16x32_bf16 v[0:3], v[166:169], v[232:235], v[0:3]
	v_mfma_f32_16x16x32_bf16 v[44:47], v[162:165], v[178:181], v[44:47]
	v_mfma_f32_16x16x32_bf16 v[40:43], v[170:173], v[178:181], v[40:43]
	v_mfma_f32_16x16x32_bf16 v[28:31], v[162:165], v[186:189], v[28:31]
	v_mfma_f32_16x16x32_bf16 v[24:27], v[170:173], v[186:189], v[24:27]
	v_mfma_f32_16x16x32_bf16 v[12:15], v[162:165], v[216:219], v[12:15]
	v_mfma_f32_16x16x32_bf16 v[8:11], v[170:173], v[216:219], v[8:11]
	v_mfma_f32_16x16x32_bf16 v[4:7], v[162:165], v[236:239], v[4:7]
	v_mfma_f32_16x16x32_bf16 v[0:3], v[170:173], v[236:239], v[0:3]
	s_setprio 0
	s_barrier
	s_add_i32 s71, 0, 0x18000
	s_add_i32 s72, 0, 0x1c000
	v_add_u32_e32 v154, s71, v140
	v_add_u32_e32 v170, s72, v140
	ds_read_b128 v[142:145], v154
	ds_read_b128 v[146:149], v154 offset:1024
	ds_read_b128 v[150:153], v154 offset:2048
	ds_read_b128 v[154:157], v154 offset:3072
	ds_read_b128 v[158:161], v170
	ds_read_b128 v[162:165], v170 offset:1024
	ds_read_b128 v[166:169], v170 offset:2048
	ds_read_b128 v[170:173], v170 offset:3072
	s_add_u32 s44, s44, 0x40000
	s_addc_u32 s45, s45, 0
	s_mov_b32 m0, s41
	v_lshl_add_u64 v[204:205], s[44:45], 0, v[128:129]
	ds_read_b128 v[174:177], v141 offset:32768
	ds_read_b128 v[178:181], v141 offset:33792
	ds_read_b128 v[182:185], v141 offset:34816
	ds_read_b128 v[186:189], v141 offset:35840
	ds_read_b128 v[212:215], v141 offset:36864
	ds_read_b128 v[216:219], v141 offset:37888
	ds_read_b128 v[232:235], v141 offset:38912
	ds_read_b128 v[236:239], v141 offset:39936
	global_load_lds_dwordx4 v[204:205], off
	v_lshl_add_u64 v[204:205], s[44:45], 0, v[130:131]
	s_mov_b32 m0, s46
	s_nop 0
	global_load_lds_dwordx4 v[204:205], off
	s_waitcnt vmcnt(8)
	s_waitcnt lgkmcnt(0)
	s_barrier
	s_setprio 1
	s_waitcnt lgkmcnt(0)
	v_mfma_f32_16x16x32_bf16 v[124:127], v[142:145], v[174:177], v[124:127]
	v_mfma_f32_16x16x32_bf16 v[120:123], v[150:153], v[174:177], v[120:123]
	v_mfma_f32_16x16x32_bf16 v[116:119], v[142:145], v[182:185], v[116:119]
	v_mfma_f32_16x16x32_bf16 v[112:115], v[150:153], v[182:185], v[112:115]
	v_mfma_f32_16x16x32_bf16 v[100:103], v[142:145], v[212:215], v[100:103]
	v_mfma_f32_16x16x32_bf16 v[96:99], v[150:153], v[212:215], v[96:99]
	v_mfma_f32_16x16x32_bf16 v[84:87], v[142:145], v[232:235], v[84:87]
	v_mfma_f32_16x16x32_bf16 v[80:83], v[150:153], v[232:235], v[80:83]
	v_mfma_f32_16x16x32_bf16 v[124:127], v[146:149], v[178:181], v[124:127]
	v_mfma_f32_16x16x32_bf16 v[120:123], v[154:157], v[178:181], v[120:123]
	v_mfma_f32_16x16x32_bf16 v[116:119], v[146:149], v[186:189], v[116:119]
	v_mfma_f32_16x16x32_bf16 v[112:115], v[154:157], v[186:189], v[112:115]
	v_mfma_f32_16x16x32_bf16 v[100:103], v[146:149], v[216:219], v[100:103]
	v_mfma_f32_16x16x32_bf16 v[96:99], v[154:157], v[216:219], v[96:99]
	v_mfma_f32_16x16x32_bf16 v[84:87], v[146:149], v[236:239], v[84:87]
	v_mfma_f32_16x16x32_bf16 v[80:83], v[154:157], v[236:239], v[80:83]
	s_setprio 0
	s_setprio 1
	v_mfma_f32_16x16x32_bf16 v[108:111], v[158:161], v[174:177], v[108:111]
	v_mfma_f32_16x16x32_bf16 v[104:107], v[166:169], v[174:177], v[104:107]
	v_mfma_f32_16x16x32_bf16 v[92:95], v[158:161], v[182:185], v[92:95]
	v_mfma_f32_16x16x32_bf16 v[88:91], v[166:169], v[182:185], v[88:91]
	v_mfma_f32_16x16x32_bf16 v[76:79], v[158:161], v[212:215], v[76:79]
	v_mfma_f32_16x16x32_bf16 v[72:75], v[166:169], v[212:215], v[72:75]
	v_mfma_f32_16x16x32_bf16 v[68:71], v[158:161], v[232:235], v[68:71]
	v_mfma_f32_16x16x32_bf16 v[64:67], v[166:169], v[232:235], v[64:67]
	v_mfma_f32_16x16x32_bf16 v[108:111], v[162:165], v[178:181], v[108:111]
	v_mfma_f32_16x16x32_bf16 v[104:107], v[170:173], v[178:181], v[104:107]
	v_mfma_f32_16x16x32_bf16 v[92:95], v[162:165], v[186:189], v[92:95]
	v_mfma_f32_16x16x32_bf16 v[88:91], v[170:173], v[186:189], v[88:91]
	v_mfma_f32_16x16x32_bf16 v[76:79], v[162:165], v[216:219], v[76:79]
	v_mfma_f32_16x16x32_bf16 v[72:75], v[170:173], v[216:219], v[72:75]
	v_mfma_f32_16x16x32_bf16 v[68:71], v[162:165], v[236:239], v[68:71]
	v_mfma_f32_16x16x32_bf16 v[64:67], v[170:173], v[236:239], v[64:67]
	s_setprio 0
	s_barrier
; #define PG8_STAGE(bufoff, gbase, voff) do { _Pragma("unroll") for (int _i = 0; _i < 2; ++_i) \
;         __builtin_amdgcn_global_load_lds((const unsigned*)((const char*)(gbase) + (voff)[_i]), (PG8_LAS unsigned*)(lds + (bufoff) + ldsw + _i * 8192), 16, 0, 0); } while (0)
; #define PG8_LDA(dst, b, h) do { _Pragma("unroll") for (int m = 0; m < 4; ++m) _Pragma("unroll") for (int k = 0; k < 2; ++k) dst[m][k] = *(const PG8_LAS bf16x8*)(lds + PG8_SA(b, h) + aoff + m * 2048 + k * 1024); } while (0)
; #define PG8_MMA(ai, bj, At, Bt) do { __builtin_amdgcn_s_setprio(1); _Pragma("unroll") for (int m = 0; m < 4; ++m) _Pragma("unroll") for (int n = 0; n < 2; ++n) _Pragma("unroll") for (int k = 0; k < 2; ++k) \
;         acc[ai][bj][m][n] = __builtin_amdgcn_mfma_f32_16x16x32_bf16(Bt[n][k], At[m][k], acc[ai][bj][m][n], 0, 0, 0); __builtin_amdgcn_s_setprio(0); } while (0)
; #define PG8_WAIT_V(n) asm volatile("s_waitcnt vmcnt(" #n ")" ::: "memory")
; #define PG8_WAIT_L(n) asm volatile("s_waitcnt lgkmcnt(" #n ")" ::: "memory")
; #define PG8_BAR __builtin_amdgcn_s_barrier()
; #define PG8_SCHED __builtin_amdgcn_sched_barrier(0)
; template <class Epi, class Sched, bool ALIGN_EPI = false, bool SP2 = false>
; __device__ __forceinline__ void gemm_phase(PG8_LAS unsigned char* lds, const Gemm g, const Sched& S, const Epi& E, const int tid) {
;     ...
;             PG8_LDA(At, 1, 1); PG8_STAGE(PG8_SB(1, 0), b3, voffB); PG8_STAGE(PG8_SB(1, 1), b3 + hstep, voffB); PG8_STAGE(PG8_SA(1, 0), a3, voffA);
;             PG8_WAIT_V(8); PG8_WAIT_L(0); PG8_BAR; PG8_MMA(1, 0, At, B0); PG8_MMA(1, 1, At, B1); PG8_BAR; PG8_SCHED;
;     ...
;         if constexpr (ALIGN_EPI) { if (wr == 0) PG8_BAR; }
	s_add_i32 s44, s71, s38
	v_lshl_add_u64 v[190:191], v[190:191], 0, s[36:37]
	s_mov_b32 m0, s44
	ds_read_b128 v[174:177], v141 offset:49152
	ds_read_b128 v[178:181], v141 offset:50176
	ds_read_b128 v[182:185], v141 offset:51200
	ds_read_b128 v[186:189], v141 offset:52224
	ds_read_b128 v[212:215], v141 offset:53248
	ds_read_b128 v[216:219], v141 offset:54272
	ds_read_b128 v[232:235], v141 offset:55296
	ds_read_b128 v[236:239], v141 offset:56320
	global_load_lds_dwordx4 v[190:191], off
	s_add_i32 m0, s44, 0x2000
	s_add_u32 s28, s28, 0x40080
	v_lshl_add_u64 v[190:191], v[194:195], 0, s[36:37]
	s_addc_u32 s29, s29, 0
	s_add_i32 s44, s72, s38
	global_load_lds_dwordx4 v[190:191], off
	v_lshl_add_u64 v[190:191], s[28:29], 0, v[192:193]
	s_mov_b32 m0, s44
	s_nop 0
	global_load_lds_dwordx4 v[190:191], off
	v_lshl_add_u64 v[190:191], s[28:29], 0, v[132:133]
	s_add_i32 m0, s44, 0x2000
	s_nop 0
	global_load_lds_dwordx4 v[190:191], off
	v_lshl_add_u64 v[190:191], v[196:197], 0, s[36:37]
	s_mov_b32 m0, s47
	s_nop 0
	global_load_lds_dwordx4 v[190:191], off
	v_lshl_add_u64 v[190:191], v[202:203], 0, s[36:37]
	s_mov_b32 m0, s52
	s_nop 0
	global_load_lds_dwordx4 v[190:191], off
	s_add_i32 s70, s70, 2
	s_add_u32 s22, s22, 0x100
	s_addc_u32 s23, s23, 0
	s_add_u32 s60, s60, 0x100
	s_addc_u32 s62, s62, 0
	s_cmp_gt_u32 s70, 13
	s_waitcnt vmcnt(8)
	s_waitcnt lgkmcnt(0)
	s_barrier
	s_setprio 1
	s_waitcnt lgkmcnt(0)
	v_mfma_f32_16x16x32_bf16 v[60:63], v[142:145], v[174:177], v[60:63]
	v_mfma_f32_16x16x32_bf16 v[56:59], v[150:153], v[174:177], v[56:59]
	v_mfma_f32_16x16x32_bf16 v[52:55], v[142:145], v[182:185], v[52:55]
	v_mfma_f32_16x16x32_bf16 v[48:51], v[150:153], v[182:185], v[48:51]
	v_mfma_f32_16x16x32_bf16 v[36:39], v[142:145], v[212:215], v[36:39]
	v_mfma_f32_16x16x32_bf16 v[32:35], v[150:153], v[212:215], v[32:35]
	v_mfma_f32_16x16x32_bf16 v[20:23], v[142:145], v[232:235], v[20:23]
	v_mfma_f32_16x16x32_bf16 v[16:19], v[150:153], v[232:235], v[16:19]
	v_mfma_f32_16x16x32_bf16 v[60:63], v[146:149], v[178:181], v[60:63]
	v_mfma_f32_16x16x32_bf16 v[56:59], v[154:157], v[178:181], v[56:59]
	v_mfma_f32_16x16x32_bf16 v[52:55], v[146:149], v[186:189], v[52:55]
	v_mfma_f32_16x16x32_bf16 v[48:51], v[154:157], v[186:189], v[48:51]
	v_mfma_f32_16x16x32_bf16 v[36:39], v[146:149], v[216:219], v[36:39]
	v_mfma_f32_16x16x32_bf16 v[32:35], v[154:157], v[216:219], v[32:35]
	v_mfma_f32_16x16x32_bf16 v[20:23], v[146:149], v[236:239], v[20:23]
	v_mfma_f32_16x16x32_bf16 v[16:19], v[154:157], v[236:239], v[16:19]
	s_setprio 0
	s_setprio 1
	v_mfma_f32_16x16x32_bf16 v[44:47], v[158:161], v[174:177], v[44:47]
	v_mfma_f32_16x16x32_bf16 v[40:43], v[166:169], v[174:177], v[40:43]
	v_mfma_f32_16x16x32_bf16 v[28:31], v[158:161], v[182:185], v[28:31]
	v_mfma_f32_16x16x32_bf16 v[24:27], v[166:169], v[182:185], v[24:27]
	v_mfma_f32_16x16x32_bf16 v[12:15], v[158:161], v[212:215], v[12:15]
	v_mfma_f32_16x16x32_bf16 v[8:11], v[166:169], v[212:215], v[8:11]
	v_mfma_f32_16x16x32_bf16 v[4:7], v[158:161], v[232:235], v[4:7]
	v_mfma_f32_16x16x32_bf16 v[0:3], v[166:169], v[232:235], v[0:3]
	v_mfma_f32_16x16x32_bf16 v[44:47], v[162:165], v[178:181], v[44:47]
	v_mfma_f32_16x16x32_bf16 v[40:43], v[170:173], v[178:181], v[40:43]
	v_mfma_f32_16x16x32_bf16 v[28:31], v[162:165], v[186:189], v[28:31]
	v_mfma_f32_16x16x32_bf16 v[24:27], v[170:173], v[186:189], v[24:27]
	v_mfma_f32_16x16x32_bf16 v[12:15], v[162:165], v[216:219], v[12:15]
	v_mfma_f32_16x16x32_bf16 v[8:11], v[170:173], v[216:219], v[8:11]
	v_mfma_f32_16x16x32_bf16 v[4:7], v[162:165], v[236:239], v[4:7]
	v_mfma_f32_16x16x32_bf16 v[0:3], v[170:173], v[236:239], v[0:3]
	s_setprio 0
	s_barrier
	s_cbranch_scc0 .LBB0_183
	s_and_b64 vcc, exec, s[10:11]
	s_cbranch_vccz .LBB0_186
	s_barrier

; #define PG8_STAGE(bufoff, gbase, voff) do { _Pragma("unroll") for (int _i = 0; _i < 2; ++_i) \
;         __builtin_amdgcn_global_load_lds((const unsigned*)((const char*)(gbase) + (voff)[_i]), (PG8_LAS unsigned*)(lds + (bufoff) + ldsw + _i * 8192), 16, 0, 0); } while (0)
; #define PG8_LDA(dst, b, h) do { _Pragma("unroll") for (int m = 0; m < 4; ++m) _Pragma("unroll") for (int k = 0; k < 2; ++k) dst[m][k] = *(const PG8_LAS bf16x8*)(lds + PG8_SA(b, h) + aoff + m * 2048 + k * 1024); } while (0)
; #define PG8_LDB(dst, b, h) do { _Pragma("unroll") for (int n = 0; n < 2; ++n) _Pragma("unroll") for (int k = 0; k < 2; ++k) dst[n][k] = *(const PG8_LAS bf16x8*)(lds + PG8_SB(b, h) + boff + n * 2048 + k * 1024); } while (0)
; #define PG8_MMA(ai, bj, At, Bt) do { __builtin_amdgcn_s_setprio(1); _Pragma("unroll") for (int m = 0; m < 4; ++m) _Pragma("unroll") for (int n = 0; n < 2; ++n) _Pragma("unroll") for (int k = 0; k < 2; ++k) \
;         acc[ai][bj][m][n] = __builtin_amdgcn_mfma_f32_16x16x32_bf16(Bt[n][k], At[m][k], acc[ai][bj][m][n], 0, 0, 0); __builtin_amdgcn_s_setprio(0); } while (0)
; #define PG8_WAIT_V(n) asm volatile("s_waitcnt vmcnt(" #n ")" ::: "memory")
; #define PG8_BAR __builtin_amdgcn_s_barrier()
; template <class Epi, class Sched, bool ALIGN_EPI = false, bool SP2 = false>
; __device__ __forceinline__ void gemm_phase(PG8_LAS unsigned char* lds, const Gemm g, const Sched& S, const Epi& E, const int tid) {
;     ...
;         for (int t = 0; t < nt; t += 2) {
;             const bool last = (t == nt - 2);
;             const char* a1 = cA + (size_t)(t + 1) * kstep;
;             const char* a2 = last ? nA : cA + (size_t)(t + 2) * kstep; const char* b2 = last ? nB : cB + (size_t)(t + 2) * kstep;
;             const char* a3 = a2 + kstep; const char* b3 = b2 + kstep;
;             if (last && has_next) S.a_ready(nxt);
;             if constexpr (SP2) {
;             PG8_LDB(B0, 0, 0); PG8_LDB(B1, 0, 1); PG8_SCHED; PG8_LDA(At, 0, 0); PG8_STAGE(PG8_SA(1, 1), a1 + hstep, voffA);
;             PG8_WAIT_V(8); PG8_WAIT_L(0); PG8_BAR; PG8_MMA(0, 0, At, B0); PG8_MMA(0, 1, At, B1); PG8_BAR; PG8_SCHED;
;             PG8_LDA(At, 0, 1); PG8_STAGE(PG8_SB(0, 0), b2, voffB); PG8_STAGE(PG8_SB(0, 1), b2 + hstep, voffB); PG8_STAGE(PG8_SA(0, 0), a2, voffA);
;             PG8_WAIT_V(8); PG8_WAIT_L(0); PG8_BAR; PG8_MMA(1, 0, At, B0); PG8_MMA(1, 1, At, B1); PG8_BAR; PG8_SCHED;
.LBB0_239:
	s_waitcnt lgkmcnt(0)
	v_add_u32_e32 v156, 0x10000, v142
	v_add_u32_e32 v172, 0x14000, v142
	ds_read_b128 v[144:147], v156
	ds_read_b128 v[148:151], v156 offset:1024
	ds_read_b128 v[152:155], v156 offset:2048
	ds_read_b128 v[156:159], v156 offset:3072
	ds_read_b128 v[160:163], v172
	ds_read_b128 v[164:167], v172 offset:1024
	ds_read_b128 v[168:171], v172 offset:2048
	ds_read_b128 v[172:175], v172 offset:3072
	s_add_u32 s58, s10, s44
	s_addc_u32 s59, s11, s45
	s_add_u32 s58, s58, 0x100
	s_addc_u32 s59, s59, 0
	s_add_u32 s73, s19, s44
	s_addc_u32 s74, s62, s45
	s_add_i32 s75, 0, 0x10000
	s_cmpk_eq_i32 s44, 0x700
	s_cselect_b32 s79, s15, s59
	s_cselect_b32 s78, s70, s58
	s_cselect_b32 s59, s13, s74
	s_cselect_b32 s58, s71, s73
	s_add_i32 s73, 0, 0x14000
	v_lshl_add_u64 v[194:195], v[138:139], 0, s[44:45]
	s_add_i32 m0, s46, 0xc000
	ds_read_b128 v[176:179], v143
	ds_read_b128 v[180:183], v143 offset:1024
	ds_read_b128 v[184:187], v143 offset:2048
	ds_read_b128 v[188:191], v143 offset:3072
	ds_read_b128 v[212:215], v143 offset:4096
	ds_read_b128 v[216:219], v143 offset:5120
	ds_read_b128 v[234:237], v143 offset:6144
	ds_read_b128 v[238:241], v143 offset:7168
	global_load_lds_dwordx4 v[194:195], off
	v_lshl_add_u64 v[194:195], v[140:141], 0, s[44:45]
	s_add_i32 m0, s46, 0xe000
	s_nop 0
	global_load_lds_dwordx4 v[194:195], off
	s_waitcnt vmcnt(8)
	s_waitcnt lgkmcnt(0)
	s_barrier
	s_setprio 1
	s_waitcnt lgkmcnt(0)
	v_mfma_f32_16x16x32_bf16 v[76:79], v[144:147], v[176:179], v[76:79]
	v_mfma_f32_16x16x32_bf16 v[72:75], v[152:155], v[176:179], v[72:75]
	v_mfma_f32_16x16x32_bf16 v[100:103], v[144:147], v[184:187], v[100:103]
	v_mfma_f32_16x16x32_bf16 v[96:99], v[152:155], v[184:187], v[96:99]
	v_mfma_f32_16x16x32_bf16 v[124:127], v[144:147], v[212:215], v[124:127]
	v_mfma_f32_16x16x32_bf16 v[120:123], v[152:155], v[212:215], v[120:123]
	v_mfma_f32_16x16x32_bf16 v[92:95], v[144:147], v[234:237], v[92:95]
	v_mfma_f32_16x16x32_bf16 v[84:87], v[152:155], v[234:237], v[84:87]
	v_mfma_f32_16x16x32_bf16 v[76:79], v[148:151], v[180:183], v[76:79]
	v_mfma_f32_16x16x32_bf16 v[72:75], v[156:159], v[180:183], v[72:75]
	v_mfma_f32_16x16x32_bf16 v[100:103], v[148:151], v[188:191], v[100:103]
	v_mfma_f32_16x16x32_bf16 v[96:99], v[156:159], v[188:191], v[96:99]
	v_mfma_f32_16x16x32_bf16 v[124:127], v[148:151], v[216:219], v[124:127]
	v_mfma_f32_16x16x32_bf16 v[120:123], v[156:159], v[216:219], v[120:123]
	v_mfma_f32_16x16x32_bf16 v[92:95], v[148:151], v[238:241], v[92:95]
	v_mfma_f32_16x16x32_bf16 v[84:87], v[156:159], v[238:241], v[84:87]
	s_setprio 0
	s_setprio 1
	v_mfma_f32_16x16x32_bf16 v[80:83], v[160:163], v[176:179], v[80:83]
	v_mfma_f32_16x16x32_bf16 v[88:91], v[168:171], v[176:179], v[88:91]
	v_mfma_f32_16x16x32_bf16 v[108:111], v[160:163], v[184:187], v[108:111]
	v_mfma_f32_16x16x32_bf16 v[116:119], v[168:171], v[184:187], v[116:119]
	v_mfma_f32_16x16x32_bf16 v[112:115], v[160:163], v[212:215], v[112:115]
	v_mfma_f32_16x16x32_bf16 v[104:107], v[168:171], v[212:215], v[104:107]
	v_mfma_f32_16x16x32_bf16 v[68:71], v[160:163], v[234:237], v[68:71]
	v_mfma_f32_16x16x32_bf16 v[64:67], v[168:171], v[234:237], v[64:67]
	v_mfma_f32_16x16x32_bf16 v[80:83], v[164:167], v[180:183], v[80:83]
	v_mfma_f32_16x16x32_bf16 v[88:91], v[172:175], v[180:183], v[88:91]
	v_mfma_f32_16x16x32_bf16 v[108:111], v[164:167], v[188:191], v[108:111]
	v_mfma_f32_16x16x32_bf16 v[116:119], v[172:175], v[188:191], v[116:119]
	v_mfma_f32_16x16x32_bf16 v[112:115], v[164:167], v[216:219], v[112:115]
	v_mfma_f32_16x16x32_bf16 v[104:107], v[172:175], v[216:219], v[104:107]
	v_mfma_f32_16x16x32_bf16 v[68:71], v[164:167], v[238:241], v[68:71]
	v_mfma_f32_16x16x32_bf16 v[64:67], v[172:175], v[238:241], v[64:67]
	s_setprio 0
	s_barrier
	s_add_i32 s74, s75, s41
	v_lshl_add_u64 v[194:195], s[58:59], 0, v[192:193]
	s_mov_b32 m0, s74
	ds_read_b128 v[176:179], v143 offset:16384
	ds_read_b128 v[180:183], v143 offset:17408
	ds_read_b128 v[184:187], v143 offset:18432
	ds_read_b128 v[188:191], v143 offset:19456
	ds_read_b128 v[212:215], v143 offset:20480
	ds_read_b128 v[216:219], v143 offset:21504
	ds_read_b128 v[234:237], v143 offset:22528
	ds_read_b128 v[238:241], v143 offset:23552
	global_load_lds_dwordx4 v[194:195], off
	s_add_i32 m0, s74, 0x2000
	s_add_u32 s74, s58, 0x40000
	v_lshl_add_u64 v[196:197], s[58:59], 0, v[132:133]
	s_addc_u32 s75, s59, 0
	s_add_i32 s73, s73, s41
	global_load_lds_dwordx4 v[196:197], off
	v_lshl_add_u64 v[202:203], s[74:75], 0, v[192:193]
	s_mov_b32 m0, s73
	v_lshl_add_u64 v[204:205], s[78:79], 0, v[130:131]
	global_load_lds_dwordx4 v[202:203], off
	v_lshl_add_u64 v[202:203], s[74:75], 0, v[132:133]
	s_add_i32 m0, s73, 0x2000
	s_nop 0
	global_load_lds_dwordx4 v[202:203], off
	v_lshl_add_u64 v[202:203], s[78:79], 0, v[128:129]
	s_mov_b32 m0, s46
	s_nop 0
	global_load_lds_dwordx4 v[202:203], off
	s_mov_b32 m0, s47
	s_nop 0
	global_load_lds_dwordx4 v[204:205], off
	s_waitcnt vmcnt(8)
	s_waitcnt lgkmcnt(0)
	s_barrier
; #define PG8_STAGE(bufoff, gbase, voff) do { _Pragma("unroll") for (int _i = 0; _i < 2; ++_i) \
;         __builtin_amdgcn_global_load_lds((const unsigned*)((const char*)(gbase) + (voff)[_i]), (PG8_LAS unsigned*)(lds + (bufoff) + ldsw + _i * 8192), 16, 0, 0); } while (0)
; #define PG8_LDA(dst, b, h) do { _Pragma("unroll") for (int m = 0; m < 4; ++m) _Pragma("unroll") for (int k = 0; k < 2; ++k) dst[m][k] = *(const PG8_LAS bf16x8*)(lds + PG8_SA(b, h) + aoff + m * 2048 + k * 1024); } while (0)
; #define PG8_LDB(dst, b, h) do { _Pragma("unroll") for (int n = 0; n < 2; ++n) _Pragma("unroll") for (int k = 0; k < 2; ++k) dst[n][k] = *(const PG8_LAS bf16x8*)(lds + PG8_SB(b, h) + boff + n * 2048 + k * 1024); } while (0)
; #define PG8_MMA(ai, bj, At, Bt) do { __builtin_amdgcn_s_setprio(1); _Pragma("unroll") for (int m = 0; m < 4; ++m) _Pragma("unroll") for (int n = 0; n < 2; ++n) _Pragma("unroll") for (int k = 0; k < 2; ++k) \
;         acc[ai][bj][m][n] = __builtin_amdgcn_mfma_f32_16x16x32_bf16(Bt[n][k], At[m][k], acc[ai][bj][m][n], 0, 0, 0); __builtin_amdgcn_s_setprio(0); } while (0)
; #define PG8_WAIT_V(n) asm volatile("s_waitcnt vmcnt(" #n ")" ::: "memory")
; #define PG8_WAIT_L(n) asm volatile("s_waitcnt lgkmcnt(" #n ")" ::: "memory")
; #define PG8_BAR __builtin_amdgcn_s_barrier()
; #define PG8_SCHED __builtin_amdgcn_sched_barrier(0)
; template <class Epi, class Sched, bool ALIGN_EPI = false, bool SP2 = false>
; __device__ __forceinline__ void gemm_phase(PG8_LAS unsigned char* lds, const Gemm g, const Sched& S, const Epi& E, const int tid) {
;     ...
;             PG8_WAIT_V(8); PG8_WAIT_L(0); PG8_BAR; PG8_MMA(1, 0, At, B0); PG8_MMA(1, 1, At, B1); PG8_BAR; PG8_SCHED;
;             PG8_LDB(B0, 1, 0); PG8_LDB(B1, 1, 1); PG8_SCHED; PG8_LDA(At, 1, 0); PG8_STAGE(PG8_SA(0, 1), a2 + hstep, voffA);
;             PG8_WAIT_V(8); PG8_WAIT_L(0); PG8_BAR; PG8_MMA(0, 0, At, B0); PG8_MMA(0, 1, At, B1); PG8_BAR; PG8_SCHED;
	s_setprio 1
	s_waitcnt lgkmcnt(0)
	v_mfma_f32_16x16x32_bf16 v[60:63], v[144:147], v[176:179], v[60:63]
	v_mfma_f32_16x16x32_bf16 v[56:59], v[152:155], v[176:179], v[56:59]
	v_mfma_f32_16x16x32_bf16 v[44:47], v[144:147], v[184:187], v[44:47]
	v_mfma_f32_16x16x32_bf16 v[40:43], v[152:155], v[184:187], v[40:43]
	v_mfma_f32_16x16x32_bf16 v[28:31], v[144:147], v[212:215], v[28:31]
	v_mfma_f32_16x16x32_bf16 v[24:27], v[152:155], v[212:215], v[24:27]
	v_mfma_f32_16x16x32_bf16 v[12:15], v[144:147], v[234:237], v[12:15]
	v_mfma_f32_16x16x32_bf16 v[8:11], v[152:155], v[234:237], v[8:11]
	v_mfma_f32_16x16x32_bf16 v[60:63], v[148:151], v[180:183], v[60:63]
	v_mfma_f32_16x16x32_bf16 v[56:59], v[156:159], v[180:183], v[56:59]
	v_mfma_f32_16x16x32_bf16 v[44:47], v[148:151], v[188:191], v[44:47]
	v_mfma_f32_16x16x32_bf16 v[40:43], v[156:159], v[188:191], v[40:43]
	v_mfma_f32_16x16x32_bf16 v[28:31], v[148:151], v[216:219], v[28:31]
	v_mfma_f32_16x16x32_bf16 v[24:27], v[156:159], v[216:219], v[24:27]
	v_mfma_f32_16x16x32_bf16 v[12:15], v[148:151], v[238:241], v[12:15]
	v_mfma_f32_16x16x32_bf16 v[8:11], v[156:159], v[238:241], v[8:11]
	s_setprio 0
	s_setprio 1
	v_mfma_f32_16x16x32_bf16 v[52:55], v[160:163], v[176:179], v[52:55]
	v_mfma_f32_16x16x32_bf16 v[48:51], v[168:171], v[176:179], v[48:51]
	v_mfma_f32_16x16x32_bf16 v[36:39], v[160:163], v[184:187], v[36:39]
	v_mfma_f32_16x16x32_bf16 v[32:35], v[168:171], v[184:187], v[32:35]
	v_mfma_f32_16x16x32_bf16 v[20:23], v[160:163], v[212:215], v[20:23]
	v_mfma_f32_16x16x32_bf16 v[16:19], v[168:171], v[212:215], v[16:19]
	v_mfma_f32_16x16x32_bf16 v[4:7], v[160:163], v[234:237], v[4:7]
	v_mfma_f32_16x16x32_bf16 v[0:3], v[168:171], v[234:237], v[0:3]
	v_mfma_f32_16x16x32_bf16 v[52:55], v[164:167], v[180:183], v[52:55]
	v_mfma_f32_16x16x32_bf16 v[48:51], v[172:175], v[180:183], v[48:51]
	v_mfma_f32_16x16x32_bf16 v[36:39], v[164:167], v[188:191], v[36:39]
	v_mfma_f32_16x16x32_bf16 v[32:35], v[172:175], v[188:191], v[32:35]
	v_mfma_f32_16x16x32_bf16 v[20:23], v[164:167], v[216:219], v[20:23]
	v_mfma_f32_16x16x32_bf16 v[16:19], v[172:175], v[216:219], v[16:19]
	v_mfma_f32_16x16x32_bf16 v[4:7], v[164:167], v[238:241], v[4:7]
	v_mfma_f32_16x16x32_bf16 v[0:3], v[172:175], v[238:241], v[0:3]
	s_setprio 0
	s_barrier
	s_add_i32 s73, 0, 0x18000
	s_add_i32 s76, 0, 0x1c000
	v_add_u32_e32 v156, s73, v142
	v_add_u32_e32 v172, s76, v142
	ds_read_b128 v[144:147], v156
	ds_read_b128 v[148:151], v156 offset:1024
	ds_read_b128 v[152:155], v156 offset:2048
	ds_read_b128 v[156:159], v156 offset:3072
	ds_read_b128 v[160:163], v172
	ds_read_b128 v[164:167], v172 offset:1024
	ds_read_b128 v[168:171], v172 offset:2048
	ds_read_b128 v[172:175], v172 offset:3072
	s_add_u32 s74, s78, 0x40000
	s_addc_u32 s75, s79, 0
	s_mov_b32 m0, s52
	v_lshl_add_u64 v[206:207], s[74:75], 0, v[128:129]
	ds_read_b128 v[176:179], v143 offset:32768
	ds_read_b128 v[180:183], v143 offset:33792
	ds_read_b128 v[184:187], v143 offset:34816
	ds_read_b128 v[188:191], v143 offset:35840
	ds_read_b128 v[212:215], v143 offset:36864
	ds_read_b128 v[216:219], v143 offset:37888
	ds_read_b128 v[234:237], v143 offset:38912
	ds_read_b128 v[238:241], v143 offset:39936
	global_load_lds_dwordx4 v[206:207], off
	v_lshl_add_u64 v[206:207], s[74:75], 0, v[130:131]
	s_mov_b32 m0, s53
	s_nop 0
	global_load_lds_dwordx4 v[206:207], off
	s_waitcnt vmcnt(8)
	s_waitcnt lgkmcnt(0)
	s_barrier
	s_setprio 1
	s_waitcnt lgkmcnt(0)
	v_mfma_f32_16x16x32_bf16 v[76:79], v[144:147], v[176:179], v[76:79]
	v_mfma_f32_16x16x32_bf16 v[72:75], v[152:155], v[176:179], v[72:75]
	v_mfma_f32_16x16x32_bf16 v[100:103], v[144:147], v[184:187], v[100:103]
	v_mfma_f32_16x16x32_bf16 v[96:99], v[152:155], v[184:187], v[96:99]
	v_mfma_f32_16x16x32_bf16 v[124:127], v[144:147], v[212:215], v[124:127]
	v_mfma_f32_16x16x32_bf16 v[120:123], v[152:155], v[212:215], v[120:123]
	v_mfma_f32_16x16x32_bf16 v[92:95], v[144:147], v[234:237], v[92:95]
	v_mfma_f32_16x16x32_bf16 v[84:87], v[152:155], v[234:237], v[84:87]
	v_mfma_f32_16x16x32_bf16 v[76:79], v[148:151], v[180:183], v[76:79]
	v_mfma_f32_16x16x32_bf16 v[72:75], v[156:159], v[180:183], v[72:75]
	v_mfma_f32_16x16x32_bf16 v[100:103], v[148:151], v[188:191], v[100:103]
	v_mfma_f32_16x16x32_bf16 v[96:99], v[156:159], v[188:191], v[96:99]
	v_mfma_f32_16x16x32_bf16 v[124:127], v[148:151], v[216:219], v[124:127]
	v_mfma_f32_16x16x32_bf16 v[120:123], v[156:159], v[216:219], v[120:123]
	v_mfma_f32_16x16x32_bf16 v[92:95], v[148:151], v[238:241], v[92:95]
	v_mfma_f32_16x16x32_bf16 v[84:87], v[156:159], v[238:241], v[84:87]
	s_setprio 0
	s_setprio 1
	v_mfma_f32_16x16x32_bf16 v[80:83], v[160:163], v[176:179], v[80:83]
	v_mfma_f32_16x16x32_bf16 v[88:91], v[168:171], v[176:179], v[88:91]
	v_mfma_f32_16x16x32_bf16 v[108:111], v[160:163], v[184:187], v[108:111]
	v_mfma_f32_16x16x32_bf16 v[116:119], v[168:171], v[184:187], v[116:119]
	v_mfma_f32_16x16x32_bf16 v[112:115], v[160:163], v[212:215], v[112:115]
	v_mfma_f32_16x16x32_bf16 v[104:107], v[168:171], v[212:215], v[104:107]
	v_mfma_f32_16x16x32_bf16 v[68:71], v[160:163], v[234:237], v[68:71]
	v_mfma_f32_16x16x32_bf16 v[64:67], v[168:171], v[234:237], v[64:67]
	v_mfma_f32_16x16x32_bf16 v[80:83], v[164:167], v[180:183], v[80:83]
	v_mfma_f32_16x16x32_bf16 v[88:91], v[172:175], v[180:183], v[88:91]
	v_mfma_f32_16x16x32_bf16 v[108:111], v[164:167], v[188:191], v[108:111]
	v_mfma_f32_16x16x32_bf16 v[116:119], v[172:175], v[188:191], v[116:119]
	v_mfma_f32_16x16x32_bf16 v[112:115], v[164:167], v[216:219], v[112:115]
	v_mfma_f32_16x16x32_bf16 v[104:107], v[172:175], v[216:219], v[104:107]
	v_mfma_f32_16x16x32_bf16 v[68:71], v[164:167], v[238:241], v[68:71]
	v_mfma_f32_16x16x32_bf16 v[64:67], v[172:175], v[238:241], v[64:67]
	s_setprio 0
	s_barrier
; #define PG8_STAGE(bufoff, gbase, voff) do { _Pragma("unroll") for (int _i = 0; _i < 2; ++_i) \
;         __builtin_amdgcn_global_load_lds((const unsigned*)((const char*)(gbase) + (voff)[_i]), (PG8_LAS unsigned*)(lds + (bufoff) + ldsw + _i * 8192), 16, 0, 0); } while (0)
; #define PG8_LDA(dst, b, h) do { _Pragma("unroll") for (int m = 0; m < 4; ++m) _Pragma("unroll") for (int k = 0; k < 2; ++k) dst[m][k] = *(const PG8_LAS bf16x8*)(lds + PG8_SA(b, h) + aoff + m * 2048 + k * 1024); } while (0)
; #define PG8_MMA(ai, bj, At, Bt) do { __builtin_amdgcn_s_setprio(1); _Pragma("unroll") for (int m = 0; m < 4; ++m) _Pragma("unroll") for (int n = 0; n < 2; ++n) _Pragma("unroll") for (int k = 0; k < 2; ++k) \
;         acc[ai][bj][m][n] = __builtin_amdgcn_mfma_f32_16x16x32_bf16(Bt[n][k], At[m][k], acc[ai][bj][m][n], 0, 0, 0); __builtin_amdgcn_s_setprio(0); } while (0)
; #define PG8_WAIT_V(n) asm volatile("s_waitcnt vmcnt(" #n ")" ::: "memory")
; #define PG8_WAIT_L(n) asm volatile("s_waitcnt lgkmcnt(" #n ")" ::: "memory")
; #define PG8_BAR __builtin_amdgcn_s_barrier()
; #define PG8_SCHED __builtin_amdgcn_sched_barrier(0)
; template <class Epi, class Sched, bool ALIGN_EPI = false, bool SP2 = false>
; __device__ __forceinline__ void gemm_phase(PG8_LAS unsigned char* lds, const Gemm g, const Sched& S, const Epi& E, const int tid) {
;     ...
;             PG8_LDA(At, 1, 1); PG8_STAGE(PG8_SB(1, 0), b3, voffB); PG8_STAGE(PG8_SB(1, 1), b3 + hstep, voffB); PG8_STAGE(PG8_SA(1, 0), a3, voffA);
;             PG8_WAIT_V(8); PG8_WAIT_L(0); PG8_BAR; PG8_MMA(1, 0, At, B0); PG8_MMA(1, 1, At, B1); PG8_BAR; PG8_SCHED;
;     ...
;         if (!has_next) break;
; #pragma unroll
;         for (int a = 0; a < 2; ++a)
; #pragma unroll
;             for (int b = 0; b < 2; ++b)
; #pragma unroll
;                 for (int m = 0; m < 4; ++m)
; #pragma unroll
;                     for (int n = 0; n < 2; ++n) acc[a][b][m][n] = (f32x4){0.f, 0.f, 0.f, 0.f};
;         cur = nxt; cA = nA; cB = nB; ++ui;
	s_add_i32 s73, s73, s41
	v_lshl_add_u64 v[194:195], v[194:195], 0, s[36:37]
	s_mov_b32 m0, s73
	ds_read_b128 v[176:179], v143 offset:49152
	ds_read_b128 v[180:183], v143 offset:50176
	ds_read_b128 v[184:187], v143 offset:51200
	ds_read_b128 v[188:191], v143 offset:52224
	ds_read_b128 v[212:215], v143 offset:53248
	ds_read_b128 v[216:219], v143 offset:54272
	ds_read_b128 v[234:237], v143 offset:55296
	ds_read_b128 v[238:241], v143 offset:56320
	global_load_lds_dwordx4 v[194:195], off
	s_add_i32 m0, s73, 0x2000
	s_add_u32 s58, s58, 0x40080
	v_lshl_add_u64 v[194:195], v[196:197], 0, s[36:37]
	s_addc_u32 s59, s59, 0
	s_add_i32 s73, s76, s41
	global_load_lds_dwordx4 v[194:195], off
	v_lshl_add_u64 v[194:195], s[58:59], 0, v[192:193]
	s_mov_b32 m0, s73
	s_nop 0
	global_load_lds_dwordx4 v[194:195], off
	v_lshl_add_u64 v[194:195], s[58:59], 0, v[132:133]
	s_add_i32 m0, s73, 0x2000
	s_nop 0
	global_load_lds_dwordx4 v[194:195], off
	v_lshl_add_u64 v[194:195], v[202:203], 0, s[36:37]
	s_mov_b32 m0, s54
	s_nop 0
	global_load_lds_dwordx4 v[194:195], off
	v_lshl_add_u64 v[194:195], v[204:205], 0, s[36:37]
	s_mov_b32 m0, s55
	s_nop 0
	global_load_lds_dwordx4 v[194:195], off
	s_add_i32 s72, s72, 2
	s_add_u32 s44, s44, 0x100
	s_addc_u32 s45, s45, 0
	s_cmp_gt_u32 s72, 13
	s_waitcnt vmcnt(8)
	s_waitcnt lgkmcnt(0)
	s_barrier
	s_setprio 1
	s_waitcnt lgkmcnt(0)
	v_mfma_f32_16x16x32_bf16 v[60:63], v[144:147], v[176:179], v[60:63]
	v_mfma_f32_16x16x32_bf16 v[56:59], v[152:155], v[176:179], v[56:59]
	v_mfma_f32_16x16x32_bf16 v[44:47], v[144:147], v[184:187], v[44:47]
	v_mfma_f32_16x16x32_bf16 v[40:43], v[152:155], v[184:187], v[40:43]
	v_mfma_f32_16x16x32_bf16 v[28:31], v[144:147], v[212:215], v[28:31]
	v_mfma_f32_16x16x32_bf16 v[24:27], v[152:155], v[212:215], v[24:27]
	v_mfma_f32_16x16x32_bf16 v[12:15], v[144:147], v[234:237], v[12:15]
	v_mfma_f32_16x16x32_bf16 v[8:11], v[152:155], v[234:237], v[8:11]
	v_mfma_f32_16x16x32_bf16 v[60:63], v[148:151], v[180:183], v[60:63]
	v_mfma_f32_16x16x32_bf16 v[56:59], v[156:159], v[180:183], v[56:59]
	v_mfma_f32_16x16x32_bf16 v[44:47], v[148:151], v[188:191], v[44:47]
	v_mfma_f32_16x16x32_bf16 v[40:43], v[156:159], v[188:191], v[40:43]
	v_mfma_f32_16x16x32_bf16 v[28:31], v[148:151], v[216:219], v[28:31]
	v_mfma_f32_16x16x32_bf16 v[24:27], v[156:159], v[216:219], v[24:27]
	v_mfma_f32_16x16x32_bf16 v[12:15], v[148:151], v[238:241], v[12:15]
	v_mfma_f32_16x16x32_bf16 v[8:11], v[156:159], v[238:241], v[8:11]
	s_setprio 0
	s_setprio 1
	v_mfma_f32_16x16x32_bf16 v[52:55], v[160:163], v[176:179], v[52:55]
	v_mfma_f32_16x16x32_bf16 v[48:51], v[168:171], v[176:179], v[48:51]
	v_mfma_f32_16x16x32_bf16 v[36:39], v[160:163], v[184:187], v[36:39]
	v_mfma_f32_16x16x32_bf16 v[32:35], v[168:171], v[184:187], v[32:35]
	v_mfma_f32_16x16x32_bf16 v[20:23], v[160:163], v[212:215], v[20:23]
	v_mfma_f32_16x16x32_bf16 v[16:19], v[168:171], v[212:215], v[16:19]
	v_mfma_f32_16x16x32_bf16 v[4:7], v[160:163], v[234:237], v[4:7]
	v_mfma_f32_16x16x32_bf16 v[0:3], v[168:171], v[234:237], v[0:3]
	v_mfma_f32_16x16x32_bf16 v[52:55], v[164:167], v[180:183], v[52:55]
	v_mfma_f32_16x16x32_bf16 v[48:51], v[172:175], v[180:183], v[48:51]
	v_mfma_f32_16x16x32_bf16 v[36:39], v[164:167], v[188:191], v[36:39]
	v_mfma_f32_16x16x32_bf16 v[32:35], v[172:175], v[188:191], v[32:35]
	v_mfma_f32_16x16x32_bf16 v[20:23], v[164:167], v[216:219], v[20:23]
	v_mfma_f32_16x16x32_bf16 v[16:19], v[172:175], v[216:219], v[16:19]
	v_mfma_f32_16x16x32_bf16 v[4:7], v[164:167], v[238:241], v[4:7]
	v_mfma_f32_16x16x32_bf16 v[0:3], v[172:175], v[238:241], v[0:3]
	s_setprio 0
	s_barrier
	s_cbranch_scc0 .LBB0_239
	s_add_u32 s44, s19, 0xffffff00
	s_addc_u32 s45, s62, -1
	s_andn2_b64 vcc, exec, s[8:9]
	s_cbranch_vccnz .LBB0_242
	v_mov_b32_e32 v0, 0
	s_mov_b32 s22, s12
	s_mov_b32 s20, s14
	s_mov_b64 s[10:11], s[28:29]
	s_mov_b32 s60, s18
	v_mov_b32_e32 v1, v0
	v_mov_b32_e32 v2, v0
	v_mov_b32_e32 v3, v0
	v_mov_b32_e32 v4, v0
	v_mov_b32_e32 v5, v0
	v_mov_b32_e32 v6, v0
	v_mov_b32_e32 v7, v0
	v_mov_b32_e32 v16, v0
	v_mov_b32_e32 v17, v0
	v_mov_b32_e32 v18, v0
	v_mov_b32_e32 v19, v0
	v_mov_b32_e32 v20, v0
	v_mov_b32_e32 v21, v0
	v_mov_b32_e32 v22, v0
	v_mov_b32_e32 v23, v0
	v_mov_b32_e32 v32, v0
	v_mov_b32_e32 v33, v0
	v_mov_b32_e32 v34, v0
	v_mov_b32_e32 v35, v0
	v_mov_b32_e32 v36, v0
	v_mov_b32_e32 v37, v0
	v_mov_b32_e32 v38, v0
	v_mov_b32_e32 v39, v0
	v_mov_b32_e32 v48, v0
	v_mov_b32_e32 v49, v0
	v_mov_b32_e32 v50, v0
	v_mov_b32_e32 v51, v0
	v_mov_b32_e32 v52, v0
	v_mov_b32_e32 v53, v0
	v_mov_b32_e32 v54, v0
	v_mov_b32_e32 v55, v0
	v_mov_b32_e32 v8, v0
	v_mov_b32_e32 v9, v0
	v_mov_b32_e32 v10, v0
	v_mov_b32_e32 v11, v0
	v_mov_b32_e32 v12, v0
	v_mov_b32_e32 v13, v0
	v_mov_b32_e32 v14, v0
	v_mov_b32_e32 v15, v0
	v_mov_b32_e32 v24, v0
	v_mov_b32_e32 v25, v0
	v_mov_b32_e32 v26, v0
	v_mov_b32_e32 v27, v0
	v_mov_b32_e32 v28, v0
	v_mov_b32_e32 v29, v0
	v_mov_b32_e32 v30, v0
	v_mov_b32_e32 v31, v0
	v_mov_b32_e32 v40, v0
	v_mov_b32_e32 v41, v0
	v_mov_b32_e32 v42, v0
	v_mov_b32_e32 v43, v0
	v_mov_b32_e32 v44, v0
	v_mov_b32_e32 v45, v0
	v_mov_b32_e32 v46, v0
	v_mov_b32_e32 v47, v0
	v_mov_b32_e32 v56, v0
	v_mov_b32_e32 v57, v0
	v_mov_b32_e32 v58, v0
	v_mov_b32_e32 v59, v0
	v_mov_b32_e32 v60, v0
	v_mov_b32_e32 v61, v0
	v_mov_b32_e32 v62, v0
	v_mov_b32_e32 v63, v0
	v_mov_b32_e32 v64, v0
	v_mov_b32_e32 v65, v0
	v_mov_b32_e32 v66, v0
	v_mov_b32_e32 v67, v0
	v_mov_b32_e32 v68, v0
	v_mov_b32_e32 v69, v0
	v_mov_b32_e32 v70, v0
	v_mov_b32_e32 v71, v0
	v_mov_b32_e32 v104, v0
	v_mov_b32_e32 v105, v0
	v_mov_b32_e32 v106, v0
	v_mov_b32_e32 v107, v0
	v_mov_b32_e32 v112, v0
	v_mov_b32_e32 v113, v0
	v_mov_b32_e32 v114, v0
	v_mov_b32_e32 v115, v0
	v_mov_b32_e32 v116, v0
	v_mov_b32_e32 v117, v0
	v_mov_b32_e32 v118, v0
	v_mov_b32_e32 v119, v0
	v_mov_b32_e32 v108, v0
	v_mov_b32_e32 v109, v0
	v_mov_b32_e32 v110, v0
	v_mov_b32_e32 v111, v0
	v_mov_b32_e32 v88, v0
	v_mov_b32_e32 v89, v0
	v_mov_b32_e32 v90, v0
	v_mov_b32_e32 v91, v0
	v_mov_b32_e32 v80, v0
	v_mov_b32_e32 v81, v0
	v_mov_b32_e32 v82, v0
	v_mov_b32_e32 v83, v0
	v_mov_b32_e32 v84, v0
	v_mov_b32_e32 v85, v0
	v_mov_b32_e32 v86, v0
	v_mov_b32_e32 v87, v0
	v_mov_b32_e32 v92, v0
	v_mov_b32_e32 v93, v0
	v_mov_b32_e32 v94, v0
	v_mov_b32_e32 v95, v0
	v_mov_b32_e32 v120, v0
	v_mov_b32_e32 v121, v0
	v_mov_b32_e32 v122, v0
	v_mov_b32_e32 v123, v0
	v_mov_b32_e32 v124, v0
	v_mov_b32_e32 v125, v0
	v_mov_b32_e32 v126, v0
	v_mov_b32_e32 v127, v0
	v_mov_b32_e32 v96, v0
	v_mov_b32_e32 v97, v0
	v_mov_b32_e32 v98, v0
	v_mov_b32_e32 v99, v0
	v_mov_b32_e32 v100, v0
	v_mov_b32_e32 v101, v0
	v_mov_b32_e32 v102, v0
	v_mov_b32_e32 v103, v0
	v_mov_b32_e32 v72, v0
	v_mov_b32_e32 v73, v0
	v_mov_b32_e32 v74, v0
	v_mov_b32_e32 v75, v0
	v_mov_b32_e32 v76, v0
	v_mov_b32_e32 v77, v0
	v_mov_b32_e32 v78, v0
	v_mov_b32_e32 v79, v0
	s_load_dword s75, s[96:97], 0x0
	s_mov_b64 s[72:73], 0x20000
	s_andn2_b64 vcc, exec, s[6:7]
	s_cbranch_vccnz .LBB0_243
	s_branch .LBB0_244

; #define PG8_STAGE(bufoff, gbase, voff) do { _Pragma("unroll") for (int _i = 0; _i < 2; ++_i) \
;         __builtin_amdgcn_global_load_lds((const unsigned*)((const char*)(gbase) + (voff)[_i]), (PG8_LAS unsigned*)(lds + (bufoff) + ldsw + _i * 8192), 16, 0, 0); } while (0)
; #define PG8_LDA(dst, b, h) do { _Pragma("unroll") for (int m = 0; m < 4; ++m) _Pragma("unroll") for (int k = 0; k < 2; ++k) dst[m][k] = *(const PG8_LAS bf16x8*)(lds + PG8_SA(b, h) + aoff + m * 2048 + k * 1024); } while (0)
; #define PG8_LDB(dst, b, h) do { _Pragma("unroll") for (int n = 0; n < 2; ++n) _Pragma("unroll") for (int k = 0; k < 2; ++k) dst[n][k] = *(const PG8_LAS bf16x8*)(lds + PG8_SB(b, h) + boff + n * 2048 + k * 1024); } while (0)
; #define PG8_MMA(ai, bj, At, Bt) do { __builtin_amdgcn_s_setprio(1); _Pragma("unroll") for (int m = 0; m < 4; ++m) _Pragma("unroll") for (int n = 0; n < 2; ++n) _Pragma("unroll") for (int k = 0; k < 2; ++k) \
;         acc[ai][bj][m][n] = __builtin_amdgcn_mfma_f32_16x16x32_bf16(Bt[n][k], At[m][k], acc[ai][bj][m][n], 0, 0, 0); __builtin_amdgcn_s_setprio(0); } while (0)
; #define PG8_WAIT_V(n) asm volatile("s_waitcnt vmcnt(" #n ")" ::: "memory")
; #define PG8_BAR __builtin_amdgcn_s_barrier()
; template <class Epi, class Sched, bool ALIGN_EPI = false, bool SP2 = false>
; __device__ __forceinline__ void gemm_phase(PG8_LAS unsigned char* lds, const Gemm g, const Sched& S, const Epi& E, const int tid) {
;     ...
;         for (int t = 0; t < nt; t += 2) {
;             const bool last = (t == nt - 2);
;             const char* a1 = cA + (size_t)(t + 1) * kstep;
;             const char* a2 = last ? nA : cA + (size_t)(t + 2) * kstep; const char* b2 = last ? nB : cB + (size_t)(t + 2) * kstep;
;             const char* a3 = a2 + kstep; const char* b3 = b2 + kstep;
;             if (last && has_next) S.a_ready(nxt);
;             if constexpr (SP2) {
;             PG8_LDB(B0, 0, 0); PG8_LDB(B1, 0, 1); PG8_SCHED; PG8_LDA(At, 0, 0); PG8_STAGE(PG8_SA(1, 1), a1 + hstep, voffA);
;             PG8_WAIT_V(8); PG8_WAIT_L(0); PG8_BAR; PG8_MMA(0, 0, At, B0); PG8_MMA(0, 1, At, B1); PG8_BAR; PG8_SCHED;
;             PG8_LDA(At, 0, 1); PG8_STAGE(PG8_SB(0, 0), b2, voffB); PG8_STAGE(PG8_SB(0, 1), b2 + hstep, voffB); PG8_STAGE(PG8_SA(0, 0), a2, voffA);
;             PG8_WAIT_V(8); PG8_WAIT_L(0); PG8_BAR; PG8_MMA(1, 0, At, B0); PG8_MMA(1, 1, At, B1); PG8_BAR; PG8_SCHED;
.LBB0_324:
	v_add_u32_e32 v152, 0x10000, v142
	v_add_u32_e32 v168, 0x14000, v142
	ds_read_b128 v[138:141], v152
	ds_read_b128 v[144:147], v152 offset:1024
	ds_read_b128 v[148:151], v152 offset:2048
	ds_read_b128 v[152:155], v152 offset:3072
	ds_read_b128 v[156:159], v168
	ds_read_b128 v[160:163], v168 offset:1024
	ds_read_b128 v[164:167], v168 offset:2048
	ds_read_b128 v[168:171], v168 offset:3072
	s_add_u32 s28, s22, 0xfffc0080
	s_addc_u32 s29, s23, -1
	s_add_i32 s35, 0, 0x10000
	s_cmp_eq_u32 s34, 12
	s_cselect_b32 s45, s1, s29
	s_cselect_b32 s44, s2, s28
	s_cselect_b32 s29, s13, s26
	s_cselect_b32 s28, s15, s21
	s_add_i32 s38, 0, 0x14000
	v_lshl_add_u64 v[194:195], s[22:23], 0, v[134:135]
	s_add_i32 m0, s80, 0xc000
	ds_read_b128 v[172:175], v143
	ds_read_b128 v[176:179], v143 offset:1024
	ds_read_b128 v[180:183], v143 offset:2048
	ds_read_b128 v[184:187], v143 offset:3072
	ds_read_b128 v[188:191], v143 offset:4096
	ds_read_b128 v[212:215], v143 offset:5120
	ds_read_b128 v[216:219], v143 offset:6144
	ds_read_b128 v[232:235], v143 offset:7168
	global_load_lds_dwordx4 v[194:195], off
	v_lshl_add_u64 v[194:195], s[22:23], 0, v[136:137]
	s_add_i32 m0, s80, 0xe000
	s_nop 0
	global_load_lds_dwordx4 v[194:195], off
	s_waitcnt vmcnt(8)
	s_waitcnt lgkmcnt(0)
	s_barrier
	s_setprio 1
	s_waitcnt lgkmcnt(0)
	v_mfma_f32_16x16x32_bf16 v[124:127], v[138:141], v[172:175], v[124:127]
	v_mfma_f32_16x16x32_bf16 v[120:123], v[148:151], v[172:175], v[120:123]
	v_mfma_f32_16x16x32_bf16 v[108:111], v[138:141], v[180:183], v[108:111]
	v_mfma_f32_16x16x32_bf16 v[104:107], v[148:151], v[180:183], v[104:107]
	v_mfma_f32_16x16x32_bf16 v[92:95], v[138:141], v[188:191], v[92:95]
	v_mfma_f32_16x16x32_bf16 v[88:91], v[148:151], v[188:191], v[88:91]
	v_mfma_f32_16x16x32_bf16 v[76:79], v[138:141], v[216:219], v[76:79]
	v_mfma_f32_16x16x32_bf16 v[72:75], v[148:151], v[216:219], v[72:75]
	v_mfma_f32_16x16x32_bf16 v[124:127], v[144:147], v[176:179], v[124:127]
	v_mfma_f32_16x16x32_bf16 v[120:123], v[152:155], v[176:179], v[120:123]
	v_mfma_f32_16x16x32_bf16 v[108:111], v[144:147], v[184:187], v[108:111]
	v_mfma_f32_16x16x32_bf16 v[104:107], v[152:155], v[184:187], v[104:107]
	v_mfma_f32_16x16x32_bf16 v[92:95], v[144:147], v[212:215], v[92:95]
	v_mfma_f32_16x16x32_bf16 v[88:91], v[152:155], v[212:215], v[88:91]
	v_mfma_f32_16x16x32_bf16 v[76:79], v[144:147], v[232:235], v[76:79]
	v_mfma_f32_16x16x32_bf16 v[72:75], v[152:155], v[232:235], v[72:75]
	s_setprio 0
	s_setprio 1
	v_mfma_f32_16x16x32_bf16 v[116:119], v[156:159], v[172:175], v[116:119]
	v_mfma_f32_16x16x32_bf16 v[112:115], v[164:167], v[172:175], v[112:115]
	v_mfma_f32_16x16x32_bf16 v[100:103], v[156:159], v[180:183], v[100:103]
	v_mfma_f32_16x16x32_bf16 v[96:99], v[164:167], v[180:183], v[96:99]
	v_mfma_f32_16x16x32_bf16 v[84:87], v[156:159], v[188:191], v[84:87]
	v_mfma_f32_16x16x32_bf16 v[80:83], v[164:167], v[188:191], v[80:83]
	v_mfma_f32_16x16x32_bf16 v[68:71], v[156:159], v[216:219], v[68:71]
	v_mfma_f32_16x16x32_bf16 v[64:67], v[164:167], v[216:219], v[64:67]
	v_mfma_f32_16x16x32_bf16 v[116:119], v[160:163], v[176:179], v[116:119]
	v_mfma_f32_16x16x32_bf16 v[112:115], v[168:171], v[176:179], v[112:115]
	v_mfma_f32_16x16x32_bf16 v[100:103], v[160:163], v[184:187], v[100:103]
	v_mfma_f32_16x16x32_bf16 v[96:99], v[168:171], v[184:187], v[96:99]
	v_mfma_f32_16x16x32_bf16 v[84:87], v[160:163], v[212:215], v[84:87]
	v_mfma_f32_16x16x32_bf16 v[80:83], v[168:171], v[212:215], v[80:83]
	v_mfma_f32_16x16x32_bf16 v[68:71], v[160:163], v[232:235], v[68:71]
	v_mfma_f32_16x16x32_bf16 v[64:67], v[168:171], v[232:235], v[64:67]
	s_setprio 0
	s_barrier
	s_add_i32 s35, s35, s79
	v_lshl_add_u64 v[194:195], s[28:29], 0, v[192:193]
	s_mov_b32 m0, s35
	ds_read_b128 v[172:175], v143 offset:16384
	ds_read_b128 v[176:179], v143 offset:17408
	ds_read_b128 v[180:183], v143 offset:18432
	ds_read_b128 v[184:187], v143 offset:19456
	ds_read_b128 v[188:191], v143 offset:20480
	ds_read_b128 v[212:215], v143 offset:21504
	ds_read_b128 v[216:219], v143 offset:22528
	ds_read_b128 v[232:235], v143 offset:23552
	global_load_lds_dwordx4 v[194:195], off
	s_add_i32 m0, s35, 0x2000
	s_add_u32 s40, s28, 0x40000
	v_lshl_add_u64 v[196:197], s[28:29], 0, v[132:133]
	s_addc_u32 s41, s29, 0
	s_add_i32 s35, s38, s79
	global_load_lds_dwordx4 v[196:197], off
	v_lshl_add_u64 v[202:203], s[40:41], 0, v[192:193]
	s_mov_b32 m0, s35
	v_lshl_add_u64 v[204:205], s[44:45], 0, v[130:131]
	global_load_lds_dwordx4 v[202:203], off
	v_lshl_add_u64 v[202:203], s[40:41], 0, v[132:133]
	s_add_i32 m0, s35, 0x2000
	s_nop 0
	global_load_lds_dwordx4 v[202:203], off
	v_lshl_add_u64 v[202:203], s[44:45], 0, v[128:129]
	s_mov_b32 m0, s80
	s_nop 0
	global_load_lds_dwordx4 v[202:203], off
	s_mov_b32 m0, s81
	s_nop 0
	global_load_lds_dwordx4 v[204:205], off
	s_waitcnt vmcnt(8)
	s_waitcnt lgkmcnt(0)
	s_barrier
; #define PG8_STAGE(bufoff, gbase, voff) do { _Pragma("unroll") for (int _i = 0; _i < 2; ++_i) \
;         __builtin_amdgcn_global_load_lds((const unsigned*)((const char*)(gbase) + (voff)[_i]), (PG8_LAS unsigned*)(lds + (bufoff) + ldsw + _i * 8192), 16, 0, 0); } while (0)
; #define PG8_LDA(dst, b, h) do { _Pragma("unroll") for (int m = 0; m < 4; ++m) _Pragma("unroll") for (int k = 0; k < 2; ++k) dst[m][k] = *(const PG8_LAS bf16x8*)(lds + PG8_SA(b, h) + aoff + m * 2048 + k * 1024); } while (0)
; #define PG8_LDB(dst, b, h) do { _Pragma("unroll") for (int n = 0; n < 2; ++n) _Pragma("unroll") for (int k = 0; k < 2; ++k) dst[n][k] = *(const PG8_LAS bf16x8*)(lds + PG8_SB(b, h) + boff + n * 2048 + k * 1024); } while (0)
; #define PG8_MMA(ai, bj, At, Bt) do { __builtin_amdgcn_s_setprio(1); _Pragma("unroll") for (int m = 0; m < 4; ++m) _Pragma("unroll") for (int n = 0; n < 2; ++n) _Pragma("unroll") for (int k = 0; k < 2; ++k) \
;         acc[ai][bj][m][n] = __builtin_amdgcn_mfma_f32_16x16x32_bf16(Bt[n][k], At[m][k], acc[ai][bj][m][n], 0, 0, 0); __builtin_amdgcn_s_setprio(0); } while (0)
; #define PG8_WAIT_V(n) asm volatile("s_waitcnt vmcnt(" #n ")" ::: "memory")
; #define PG8_WAIT_L(n) asm volatile("s_waitcnt lgkmcnt(" #n ")" ::: "memory")
; #define PG8_BAR __builtin_amdgcn_s_barrier()
; #define PG8_SCHED __builtin_amdgcn_sched_barrier(0)
; template <class Epi, class Sched, bool ALIGN_EPI = false, bool SP2 = false>
; __device__ __forceinline__ void gemm_phase(PG8_LAS unsigned char* lds, const Gemm g, const Sched& S, const Epi& E, const int tid) {
;     ...
;             PG8_WAIT_V(8); PG8_WAIT_L(0); PG8_BAR; PG8_MMA(1, 0, At, B0); PG8_MMA(1, 1, At, B1); PG8_BAR; PG8_SCHED;
;             PG8_LDB(B0, 1, 0); PG8_LDB(B1, 1, 1); PG8_SCHED; PG8_LDA(At, 1, 0); PG8_STAGE(PG8_SA(0, 1), a2 + hstep, voffA);
;             PG8_WAIT_V(8); PG8_WAIT_L(0); PG8_BAR; PG8_MMA(0, 0, At, B0); PG8_MMA(0, 1, At, B1); PG8_BAR; PG8_SCHED;
	s_setprio 1
	s_waitcnt lgkmcnt(0)
	v_mfma_f32_16x16x32_bf16 v[60:63], v[138:141], v[172:175], v[60:63]
	v_mfma_f32_16x16x32_bf16 v[56:59], v[148:151], v[172:175], v[56:59]
	v_mfma_f32_16x16x32_bf16 v[44:47], v[138:141], v[180:183], v[44:47]
	v_mfma_f32_16x16x32_bf16 v[40:43], v[148:151], v[180:183], v[40:43]
	v_mfma_f32_16x16x32_bf16 v[28:31], v[138:141], v[188:191], v[28:31]
	v_mfma_f32_16x16x32_bf16 v[24:27], v[148:151], v[188:191], v[24:27]
	v_mfma_f32_16x16x32_bf16 v[12:15], v[138:141], v[216:219], v[12:15]
	v_mfma_f32_16x16x32_bf16 v[8:11], v[148:151], v[216:219], v[8:11]
	v_mfma_f32_16x16x32_bf16 v[60:63], v[144:147], v[176:179], v[60:63]
	v_mfma_f32_16x16x32_bf16 v[56:59], v[152:155], v[176:179], v[56:59]
	v_mfma_f32_16x16x32_bf16 v[44:47], v[144:147], v[184:187], v[44:47]
	v_mfma_f32_16x16x32_bf16 v[40:43], v[152:155], v[184:187], v[40:43]
	v_mfma_f32_16x16x32_bf16 v[28:31], v[144:147], v[212:215], v[28:31]
	v_mfma_f32_16x16x32_bf16 v[24:27], v[152:155], v[212:215], v[24:27]
	v_mfma_f32_16x16x32_bf16 v[12:15], v[144:147], v[232:235], v[12:15]
	v_mfma_f32_16x16x32_bf16 v[8:11], v[152:155], v[232:235], v[8:11]
	s_setprio 0
	s_setprio 1
	v_mfma_f32_16x16x32_bf16 v[52:55], v[156:159], v[172:175], v[52:55]
	v_mfma_f32_16x16x32_bf16 v[48:51], v[164:167], v[172:175], v[48:51]
	v_mfma_f32_16x16x32_bf16 v[36:39], v[156:159], v[180:183], v[36:39]
	v_mfma_f32_16x16x32_bf16 v[32:35], v[164:167], v[180:183], v[32:35]
	v_mfma_f32_16x16x32_bf16 v[20:23], v[156:159], v[188:191], v[20:23]
	v_mfma_f32_16x16x32_bf16 v[16:19], v[164:167], v[188:191], v[16:19]
	v_mfma_f32_16x16x32_bf16 v[4:7], v[156:159], v[216:219], v[4:7]
	v_mfma_f32_16x16x32_bf16 v[0:3], v[164:167], v[216:219], v[0:3]
	v_mfma_f32_16x16x32_bf16 v[52:55], v[160:163], v[176:179], v[52:55]
	v_mfma_f32_16x16x32_bf16 v[48:51], v[168:171], v[176:179], v[48:51]
	v_mfma_f32_16x16x32_bf16 v[36:39], v[160:163], v[184:187], v[36:39]
	v_mfma_f32_16x16x32_bf16 v[32:35], v[168:171], v[184:187], v[32:35]
	v_mfma_f32_16x16x32_bf16 v[20:23], v[160:163], v[212:215], v[20:23]
	v_mfma_f32_16x16x32_bf16 v[16:19], v[168:171], v[212:215], v[16:19]
	v_mfma_f32_16x16x32_bf16 v[4:7], v[160:163], v[232:235], v[4:7]
	v_mfma_f32_16x16x32_bf16 v[0:3], v[168:171], v[232:235], v[0:3]
	s_setprio 0
	s_barrier
	s_add_i32 s35, 0, 0x18000
	s_add_i32 s38, 0, 0x1c000
	v_add_u32_e32 v152, s35, v142
	v_add_u32_e32 v168, s38, v142
	ds_read_b128 v[138:141], v152
	ds_read_b128 v[144:147], v152 offset:1024
	ds_read_b128 v[148:151], v152 offset:2048
	ds_read_b128 v[152:155], v152 offset:3072
	ds_read_b128 v[156:159], v168
	ds_read_b128 v[160:163], v168 offset:1024
	ds_read_b128 v[164:167], v168 offset:2048
	ds_read_b128 v[168:171], v168 offset:3072
	s_add_u32 s40, s44, 0x40000
	s_addc_u32 s41, s45, 0
	s_mov_b32 m0, s82
	v_lshl_add_u64 v[206:207], s[40:41], 0, v[128:129]
	ds_read_b128 v[172:175], v143 offset:32768
	ds_read_b128 v[176:179], v143 offset:33792
	ds_read_b128 v[180:183], v143 offset:34816
	ds_read_b128 v[184:187], v143 offset:35840
	ds_read_b128 v[188:191], v143 offset:36864
	ds_read_b128 v[212:215], v143 offset:37888
	ds_read_b128 v[216:219], v143 offset:38912
	ds_read_b128 v[232:235], v143 offset:39936
	global_load_lds_dwordx4 v[206:207], off
	v_lshl_add_u64 v[206:207], s[40:41], 0, v[130:131]
	s_mov_b32 m0, s83
	s_nop 0
	global_load_lds_dwordx4 v[206:207], off
	s_waitcnt vmcnt(8)
	s_waitcnt lgkmcnt(0)
	s_barrier
	s_setprio 1
	s_waitcnt lgkmcnt(0)
	v_mfma_f32_16x16x32_bf16 v[124:127], v[138:141], v[172:175], v[124:127]
	v_mfma_f32_16x16x32_bf16 v[120:123], v[148:151], v[172:175], v[120:123]
	v_mfma_f32_16x16x32_bf16 v[108:111], v[138:141], v[180:183], v[108:111]
	v_mfma_f32_16x16x32_bf16 v[104:107], v[148:151], v[180:183], v[104:107]
	v_mfma_f32_16x16x32_bf16 v[92:95], v[138:141], v[188:191], v[92:95]
	v_mfma_f32_16x16x32_bf16 v[88:91], v[148:151], v[188:191], v[88:91]
	v_mfma_f32_16x16x32_bf16 v[76:79], v[138:141], v[216:219], v[76:79]
	v_mfma_f32_16x16x32_bf16 v[72:75], v[148:151], v[216:219], v[72:75]
	v_mfma_f32_16x16x32_bf16 v[124:127], v[144:147], v[176:179], v[124:127]
	v_mfma_f32_16x16x32_bf16 v[120:123], v[152:155], v[176:179], v[120:123]
	v_mfma_f32_16x16x32_bf16 v[108:111], v[144:147], v[184:187], v[108:111]
	v_mfma_f32_16x16x32_bf16 v[104:107], v[152:155], v[184:187], v[104:107]
	v_mfma_f32_16x16x32_bf16 v[92:95], v[144:147], v[212:215], v[92:95]
	v_mfma_f32_16x16x32_bf16 v[88:91], v[152:155], v[212:215], v[88:91]
	v_mfma_f32_16x16x32_bf16 v[76:79], v[144:147], v[232:235], v[76:79]
	v_mfma_f32_16x16x32_bf16 v[72:75], v[152:155], v[232:235], v[72:75]
	s_setprio 0
	s_setprio 1
	v_mfma_f32_16x16x32_bf16 v[116:119], v[156:159], v[172:175], v[116:119]
	v_mfma_f32_16x16x32_bf16 v[112:115], v[164:167], v[172:175], v[112:115]
	v_mfma_f32_16x16x32_bf16 v[100:103], v[156:159], v[180:183], v[100:103]
	v_mfma_f32_16x16x32_bf16 v[96:99], v[164:167], v[180:183], v[96:99]
	v_mfma_f32_16x16x32_bf16 v[84:87], v[156:159], v[188:191], v[84:87]
	v_mfma_f32_16x16x32_bf16 v[80:83], v[164:167], v[188:191], v[80:83]
	v_mfma_f32_16x16x32_bf16 v[68:71], v[156:159], v[216:219], v[68:71]
	v_mfma_f32_16x16x32_bf16 v[64:67], v[164:167], v[216:219], v[64:67]
	v_mfma_f32_16x16x32_bf16 v[116:119], v[160:163], v[176:179], v[116:119]
	v_mfma_f32_16x16x32_bf16 v[112:115], v[168:171], v[176:179], v[112:115]
	v_mfma_f32_16x16x32_bf16 v[100:103], v[160:163], v[184:187], v[100:103]
	v_mfma_f32_16x16x32_bf16 v[96:99], v[168:171], v[184:187], v[96:99]
	v_mfma_f32_16x16x32_bf16 v[84:87], v[160:163], v[212:215], v[84:87]
	v_mfma_f32_16x16x32_bf16 v[80:83], v[168:171], v[212:215], v[80:83]
	v_mfma_f32_16x16x32_bf16 v[68:71], v[160:163], v[232:235], v[68:71]
	v_mfma_f32_16x16x32_bf16 v[64:67], v[168:171], v[232:235], v[64:67]
	s_setprio 0
	s_barrier
; #define PG8_STAGE(bufoff, gbase, voff) do { _Pragma("unroll") for (int _i = 0; _i < 2; ++_i) \
;         __builtin_amdgcn_global_load_lds((const unsigned*)((const char*)(gbase) + (voff)[_i]), (PG8_LAS unsigned*)(lds + (bufoff) + ldsw + _i * 8192), 16, 0, 0); } while (0)
; #define PG8_LDA(dst, b, h) do { _Pragma("unroll") for (int m = 0; m < 4; ++m) _Pragma("unroll") for (int k = 0; k < 2; ++k) dst[m][k] = *(const PG8_LAS bf16x8*)(lds + PG8_SA(b, h) + aoff + m * 2048 + k * 1024); } while (0)
; #define PG8_MMA(ai, bj, At, Bt) do { __builtin_amdgcn_s_setprio(1); _Pragma("unroll") for (int m = 0; m < 4; ++m) _Pragma("unroll") for (int n = 0; n < 2; ++n) _Pragma("unroll") for (int k = 0; k < 2; ++k) \
;         acc[ai][bj][m][n] = __builtin_amdgcn_mfma_f32_16x16x32_bf16(Bt[n][k], At[m][k], acc[ai][bj][m][n], 0, 0, 0); __builtin_amdgcn_s_setprio(0); } while (0)
; #define PG8_WAIT_V(n) asm volatile("s_waitcnt vmcnt(" #n ")" ::: "memory")
; #define PG8_WAIT_L(n) asm volatile("s_waitcnt lgkmcnt(" #n ")" ::: "memory")
; #define PG8_BAR __builtin_amdgcn_s_barrier()
; #define PG8_SCHED __builtin_amdgcn_sched_barrier(0)
; template <class Epi, class Sched, bool ALIGN_EPI = false, bool SP2 = false>
; __device__ __forceinline__ void gemm_phase(PG8_LAS unsigned char* lds, const Gemm g, const Sched& S, const Epi& E, const int tid) {
;     ...
;             PG8_LDA(At, 1, 1); PG8_STAGE(PG8_SB(1, 0), b3, voffB); PG8_STAGE(PG8_SB(1, 1), b3 + hstep, voffB); PG8_STAGE(PG8_SA(1, 0), a3, voffA);
;             PG8_WAIT_V(8); PG8_WAIT_L(0); PG8_BAR; PG8_MMA(1, 0, At, B0); PG8_MMA(1, 1, At, B1); PG8_BAR; PG8_SCHED;
;     ...
;         if constexpr (ALIGN_EPI) { if (wr == 0) PG8_BAR; }
	s_add_i32 s35, s35, s79
	v_lshl_add_u64 v[194:195], v[194:195], 0, s[36:37]
	s_mov_b32 m0, s35
	ds_read_b128 v[172:175], v143 offset:49152
	ds_read_b128 v[176:179], v143 offset:50176
	ds_read_b128 v[180:183], v143 offset:51200
	ds_read_b128 v[184:187], v143 offset:52224
	ds_read_b128 v[188:191], v143 offset:53248
	ds_read_b128 v[212:215], v143 offset:54272
	ds_read_b128 v[216:219], v143 offset:55296
	ds_read_b128 v[232:235], v143 offset:56320
	global_load_lds_dwordx4 v[194:195], off
	s_add_i32 m0, s35, 0x2000
	s_add_u32 s28, s28, 0x40080
	v_lshl_add_u64 v[194:195], v[196:197], 0, s[36:37]
	s_addc_u32 s29, s29, 0
	s_add_i32 s35, s38, s79
	global_load_lds_dwordx4 v[194:195], off
	v_lshl_add_u64 v[194:195], s[28:29], 0, v[192:193]
	s_mov_b32 m0, s35
	s_nop 0
	global_load_lds_dwordx4 v[194:195], off
	v_lshl_add_u64 v[194:195], s[28:29], 0, v[132:133]
	s_add_i32 m0, s35, 0x2000
	s_nop 0
	global_load_lds_dwordx4 v[194:195], off
	v_lshl_add_u64 v[194:195], v[202:203], 0, s[36:37]
	s_mov_b32 m0, s84
	s_nop 0
	global_load_lds_dwordx4 v[194:195], off
	v_lshl_add_u64 v[194:195], v[204:205], 0, s[36:37]
	s_mov_b32 m0, s85
	s_nop 0
	global_load_lds_dwordx4 v[194:195], off
	s_add_i32 s34, s34, 2
	s_add_u32 s22, s22, 0x100
	s_addc_u32 s23, s23, 0
	s_add_u32 s21, s21, 0x100
	s_addc_u32 s26, s26, 0
	s_cmp_gt_u32 s34, 13
	s_waitcnt vmcnt(8)
	s_waitcnt lgkmcnt(0)
	s_barrier
	s_setprio 1
	s_waitcnt lgkmcnt(0)
	v_mfma_f32_16x16x32_bf16 v[60:63], v[138:141], v[172:175], v[60:63]
	v_mfma_f32_16x16x32_bf16 v[56:59], v[148:151], v[172:175], v[56:59]
	v_mfma_f32_16x16x32_bf16 v[44:47], v[138:141], v[180:183], v[44:47]
	v_mfma_f32_16x16x32_bf16 v[40:43], v[148:151], v[180:183], v[40:43]
	v_mfma_f32_16x16x32_bf16 v[28:31], v[138:141], v[188:191], v[28:31]
	v_mfma_f32_16x16x32_bf16 v[24:27], v[148:151], v[188:191], v[24:27]
	v_mfma_f32_16x16x32_bf16 v[12:15], v[138:141], v[216:219], v[12:15]
	v_mfma_f32_16x16x32_bf16 v[8:11], v[148:151], v[216:219], v[8:11]
	v_mfma_f32_16x16x32_bf16 v[60:63], v[144:147], v[176:179], v[60:63]
	v_mfma_f32_16x16x32_bf16 v[56:59], v[152:155], v[176:179], v[56:59]
	v_mfma_f32_16x16x32_bf16 v[44:47], v[144:147], v[184:187], v[44:47]
	v_mfma_f32_16x16x32_bf16 v[40:43], v[152:155], v[184:187], v[40:43]
	v_mfma_f32_16x16x32_bf16 v[28:31], v[144:147], v[212:215], v[28:31]
	v_mfma_f32_16x16x32_bf16 v[24:27], v[152:155], v[212:215], v[24:27]
	v_mfma_f32_16x16x32_bf16 v[12:15], v[144:147], v[232:235], v[12:15]
	v_mfma_f32_16x16x32_bf16 v[8:11], v[152:155], v[232:235], v[8:11]
	s_setprio 0
	s_setprio 1
	v_mfma_f32_16x16x32_bf16 v[52:55], v[156:159], v[172:175], v[52:55]
	v_mfma_f32_16x16x32_bf16 v[48:51], v[164:167], v[172:175], v[48:51]
	v_mfma_f32_16x16x32_bf16 v[36:39], v[156:159], v[180:183], v[36:39]
	v_mfma_f32_16x16x32_bf16 v[32:35], v[164:167], v[180:183], v[32:35]
	v_mfma_f32_16x16x32_bf16 v[20:23], v[156:159], v[188:191], v[20:23]
	v_mfma_f32_16x16x32_bf16 v[16:19], v[164:167], v[188:191], v[16:19]
	v_mfma_f32_16x16x32_bf16 v[4:7], v[156:159], v[216:219], v[4:7]
	v_mfma_f32_16x16x32_bf16 v[0:3], v[164:167], v[216:219], v[0:3]
	v_mfma_f32_16x16x32_bf16 v[52:55], v[160:163], v[176:179], v[52:55]
	v_mfma_f32_16x16x32_bf16 v[48:51], v[168:171], v[176:179], v[48:51]
	v_mfma_f32_16x16x32_bf16 v[36:39], v[160:163], v[184:187], v[36:39]
	v_mfma_f32_16x16x32_bf16 v[32:35], v[168:171], v[184:187], v[32:35]
	v_mfma_f32_16x16x32_bf16 v[20:23], v[160:163], v[212:215], v[20:23]
	v_mfma_f32_16x16x32_bf16 v[16:19], v[168:171], v[212:215], v[16:19]
	v_mfma_f32_16x16x32_bf16 v[4:7], v[160:163], v[232:235], v[4:7]
	v_mfma_f32_16x16x32_bf16 v[0:3], v[168:171], v[232:235], v[0:3]
	s_setprio 0
	s_barrier
	s_cbranch_scc0 .LBB0_324
	s_and_b64 vcc, exec, s[10:11]
	s_cbranch_vccz .LBB0_327
	s_barrier

; #define PG8_STAGE(bufoff, gbase, voff) do { _Pragma("unroll") for (int _i = 0; _i < 2; ++_i) \
;         __builtin_amdgcn_global_load_lds((const unsigned*)((const char*)(gbase) + (voff)[_i]), (PG8_LAS unsigned*)(lds + (bufoff) + ldsw + _i * 8192), 16, 0, 0); } while (0)
; #define PG8_LDA(dst, b, h) do { _Pragma("unroll") for (int m = 0; m < 4; ++m) _Pragma("unroll") for (int k = 0; k < 2; ++k) dst[m][k] = *(const PG8_LAS bf16x8*)(lds + PG8_SA(b, h) + aoff + m * 2048 + k * 1024); } while (0)
; #define PG8_LDB(dst, b, h) do { _Pragma("unroll") for (int n = 0; n < 2; ++n) _Pragma("unroll") for (int k = 0; k < 2; ++k) dst[n][k] = *(const PG8_LAS bf16x8*)(lds + PG8_SB(b, h) + boff + n * 2048 + k * 1024); } while (0)
; #define PG8_MMA(ai, bj, At, Bt) do { __builtin_amdgcn_s_setprio(1); _Pragma("unroll") for (int m = 0; m < 4; ++m) _Pragma("unroll") for (int n = 0; n < 2; ++n) _Pragma("unroll") for (int k = 0; k < 2; ++k) \
;         acc[ai][bj][m][n] = __builtin_amdgcn_mfma_f32_16x16x32_bf16(Bt[n][k], At[m][k], acc[ai][bj][m][n], 0, 0, 0); __builtin_amdgcn_s_setprio(0); } while (0)
; #define PG8_WAIT_V(n) asm volatile("s_waitcnt vmcnt(" #n ")" ::: "memory")
; #define PG8_BAR __builtin_amdgcn_s_barrier()
; template <class Epi, class Sched, bool ALIGN_EPI = false, bool SP2 = false>
; __device__ __forceinline__ void gemm_phase(PG8_LAS unsigned char* lds, const Gemm g, const Sched& S, const Epi& E, const int tid) {
;     ...
;         for (int t = 0; t < nt; t += 2) {
;             const bool last = (t == nt - 2);
;             const char* a1 = cA + (size_t)(t + 1) * kstep;
;             const char* a2 = last ? nA : cA + (size_t)(t + 2) * kstep; const char* b2 = last ? nB : cB + (size_t)(t + 2) * kstep;
;             const char* a3 = a2 + kstep; const char* b3 = b2 + kstep;
;             if (last && has_next) S.a_ready(nxt);
;             if constexpr (SP2) {
;             PG8_LDB(B0, 0, 0); PG8_LDB(B1, 0, 1); PG8_SCHED; PG8_LDA(At, 0, 0); PG8_STAGE(PG8_SA(1, 1), a1 + hstep, voffA);
;             PG8_WAIT_V(8); PG8_WAIT_L(0); PG8_BAR; PG8_MMA(0, 0, At, B0); PG8_MMA(0, 1, At, B1); PG8_BAR; PG8_SCHED;
;             PG8_LDA(At, 0, 1); PG8_STAGE(PG8_SB(0, 0), b2, voffB); PG8_STAGE(PG8_SB(0, 1), b2 + hstep, voffB); PG8_STAGE(PG8_SA(0, 0), a2, voffA);
;             PG8_WAIT_V(8); PG8_WAIT_L(0); PG8_BAR; PG8_MMA(1, 0, At, B0); PG8_MMA(1, 1, At, B1); PG8_BAR; PG8_SCHED;
.LBB0_348:
	v_add_u32_e32 v152, 0x10000, v142
	v_add_u32_e32 v168, 0x14000, v142
	ds_read_b128 v[138:141], v152
	ds_read_b128 v[144:147], v152 offset:1024
	ds_read_b128 v[148:151], v152 offset:2048
	ds_read_b128 v[152:155], v152 offset:3072
	ds_read_b128 v[156:159], v168
	ds_read_b128 v[160:163], v168 offset:1024
	ds_read_b128 v[164:167], v168 offset:2048
	ds_read_b128 v[168:171], v168 offset:3072
	s_add_u32 s35, s28, 0xfffe0080
	s_addc_u32 s38, s29, -1
	s_add_i32 s40, 0, 0x10000
	s_cmp_eq_u32 s34, 4
	s_cselect_b32 s59, s1, s38
	s_cselect_b32 s58, s2, s35
	s_cselect_b32 s45, s15, s26
	s_cselect_b32 s44, s17, s23
	s_add_i32 s35, 0, 0x14000
	v_lshl_add_u64 v[194:195], s[28:29], 0, v[134:135]
	s_add_i32 m0, s83, 0xc000
	ds_read_b128 v[172:175], v143
	ds_read_b128 v[176:179], v143 offset:1024
	ds_read_b128 v[180:183], v143 offset:2048
	ds_read_b128 v[184:187], v143 offset:3072
	ds_read_b128 v[188:191], v143 offset:4096
	ds_read_b128 v[212:215], v143 offset:5120
	ds_read_b128 v[216:219], v143 offset:6144
	ds_read_b128 v[232:235], v143 offset:7168
	global_load_lds_dwordx4 v[194:195], off
	v_lshl_add_u64 v[194:195], s[28:29], 0, v[136:137]
	s_add_i32 m0, s83, 0xe000
	s_nop 0
	global_load_lds_dwordx4 v[194:195], off
	s_waitcnt vmcnt(8)
	s_waitcnt lgkmcnt(0)
	s_barrier
	s_setprio 1
	s_waitcnt lgkmcnt(0)
	v_mfma_f32_16x16x32_bf16 v[124:127], v[138:141], v[172:175], v[124:127]
	v_mfma_f32_16x16x32_bf16 v[120:123], v[148:151], v[172:175], v[120:123]
	v_mfma_f32_16x16x32_bf16 v[108:111], v[138:141], v[180:183], v[108:111]
	v_mfma_f32_16x16x32_bf16 v[104:107], v[148:151], v[180:183], v[104:107]
	v_mfma_f32_16x16x32_bf16 v[92:95], v[138:141], v[188:191], v[92:95]
	v_mfma_f32_16x16x32_bf16 v[88:91], v[148:151], v[188:191], v[88:91]
	v_mfma_f32_16x16x32_bf16 v[76:79], v[138:141], v[216:219], v[76:79]
	v_mfma_f32_16x16x32_bf16 v[72:75], v[148:151], v[216:219], v[72:75]
	v_mfma_f32_16x16x32_bf16 v[124:127], v[144:147], v[176:179], v[124:127]
	v_mfma_f32_16x16x32_bf16 v[120:123], v[152:155], v[176:179], v[120:123]
	v_mfma_f32_16x16x32_bf16 v[108:111], v[144:147], v[184:187], v[108:111]
	v_mfma_f32_16x16x32_bf16 v[104:107], v[152:155], v[184:187], v[104:107]
	v_mfma_f32_16x16x32_bf16 v[92:95], v[144:147], v[212:215], v[92:95]
	v_mfma_f32_16x16x32_bf16 v[88:91], v[152:155], v[212:215], v[88:91]
	v_mfma_f32_16x16x32_bf16 v[76:79], v[144:147], v[232:235], v[76:79]
	v_mfma_f32_16x16x32_bf16 v[72:75], v[152:155], v[232:235], v[72:75]
	s_setprio 0
	s_setprio 1
	v_mfma_f32_16x16x32_bf16 v[116:119], v[156:159], v[172:175], v[116:119]
	v_mfma_f32_16x16x32_bf16 v[112:115], v[164:167], v[172:175], v[112:115]
	v_mfma_f32_16x16x32_bf16 v[100:103], v[156:159], v[180:183], v[100:103]
	v_mfma_f32_16x16x32_bf16 v[96:99], v[164:167], v[180:183], v[96:99]
	v_mfma_f32_16x16x32_bf16 v[84:87], v[156:159], v[188:191], v[84:87]
	v_mfma_f32_16x16x32_bf16 v[80:83], v[164:167], v[188:191], v[80:83]
	v_mfma_f32_16x16x32_bf16 v[68:71], v[156:159], v[216:219], v[68:71]
	v_mfma_f32_16x16x32_bf16 v[64:67], v[164:167], v[216:219], v[64:67]
	v_mfma_f32_16x16x32_bf16 v[116:119], v[160:163], v[176:179], v[116:119]
	v_mfma_f32_16x16x32_bf16 v[112:115], v[168:171], v[176:179], v[112:115]
	v_mfma_f32_16x16x32_bf16 v[100:103], v[160:163], v[184:187], v[100:103]
	v_mfma_f32_16x16x32_bf16 v[96:99], v[168:171], v[184:187], v[96:99]
	v_mfma_f32_16x16x32_bf16 v[84:87], v[160:163], v[212:215], v[84:87]
	v_mfma_f32_16x16x32_bf16 v[80:83], v[168:171], v[212:215], v[80:83]
	v_mfma_f32_16x16x32_bf16 v[68:71], v[160:163], v[232:235], v[68:71]
	v_mfma_f32_16x16x32_bf16 v[64:67], v[168:171], v[232:235], v[64:67]
	s_setprio 0
	s_barrier
	s_add_i32 s38, s40, s82
	v_lshl_add_u64 v[194:195], s[44:45], 0, v[192:193]
	s_mov_b32 m0, s38
	ds_read_b128 v[172:175], v143 offset:16384
	ds_read_b128 v[176:179], v143 offset:17408
	ds_read_b128 v[180:183], v143 offset:18432
	ds_read_b128 v[184:187], v143 offset:19456
	ds_read_b128 v[188:191], v143 offset:20480
	ds_read_b128 v[212:215], v143 offset:21504
	ds_read_b128 v[216:219], v143 offset:22528
	ds_read_b128 v[232:235], v143 offset:23552
	global_load_lds_dwordx4 v[194:195], off
	s_add_i32 m0, s38, 0x2000
	s_add_u32 s40, s44, 0x20000
	v_lshl_add_u64 v[196:197], s[44:45], 0, v[132:133]
	s_addc_u32 s41, s45, 0
	s_add_i32 s35, s35, s82
	global_load_lds_dwordx4 v[196:197], off
	v_lshl_add_u64 v[202:203], s[40:41], 0, v[192:193]
	s_mov_b32 m0, s35
	v_lshl_add_u64 v[204:205], s[58:59], 0, v[130:131]
	global_load_lds_dwordx4 v[202:203], off
	v_lshl_add_u64 v[202:203], s[40:41], 0, v[132:133]
	s_add_i32 m0, s35, 0x2000
	s_nop 0
	global_load_lds_dwordx4 v[202:203], off
	v_lshl_add_u64 v[202:203], s[58:59], 0, v[128:129]
	s_mov_b32 m0, s83
	s_nop 0
	global_load_lds_dwordx4 v[202:203], off
	s_mov_b32 m0, s84
	s_nop 0
	global_load_lds_dwordx4 v[204:205], off
	s_waitcnt vmcnt(8)
	s_waitcnt lgkmcnt(0)
	s_barrier
; #define PG8_STAGE(bufoff, gbase, voff) do { _Pragma("unroll") for (int _i = 0; _i < 2; ++_i) \
;         __builtin_amdgcn_global_load_lds((const unsigned*)((const char*)(gbase) + (voff)[_i]), (PG8_LAS unsigned*)(lds + (bufoff) + ldsw + _i * 8192), 16, 0, 0); } while (0)
; #define PG8_LDA(dst, b, h) do { _Pragma("unroll") for (int m = 0; m < 4; ++m) _Pragma("unroll") for (int k = 0; k < 2; ++k) dst[m][k] = *(const PG8_LAS bf16x8*)(lds + PG8_SA(b, h) + aoff + m * 2048 + k * 1024); } while (0)
; #define PG8_LDB(dst, b, h) do { _Pragma("unroll") for (int n = 0; n < 2; ++n) _Pragma("unroll") for (int k = 0; k < 2; ++k) dst[n][k] = *(const PG8_LAS bf16x8*)(lds + PG8_SB(b, h) + boff + n * 2048 + k * 1024); } while (0)
; #define PG8_MMA(ai, bj, At, Bt) do { __builtin_amdgcn_s_setprio(1); _Pragma("unroll") for (int m = 0; m < 4; ++m) _Pragma("unroll") for (int n = 0; n < 2; ++n) _Pragma("unroll") for (int k = 0; k < 2; ++k) \
;         acc[ai][bj][m][n] = __builtin_amdgcn_mfma_f32_16x16x32_bf16(Bt[n][k], At[m][k], acc[ai][bj][m][n], 0, 0, 0); __builtin_amdgcn_s_setprio(0); } while (0)
; #define PG8_WAIT_V(n) asm volatile("s_waitcnt vmcnt(" #n ")" ::: "memory")
; #define PG8_WAIT_L(n) asm volatile("s_waitcnt lgkmcnt(" #n ")" ::: "memory")
; #define PG8_BAR __builtin_amdgcn_s_barrier()
; #define PG8_SCHED __builtin_amdgcn_sched_barrier(0)
; template <class Epi, class Sched, bool ALIGN_EPI = false, bool SP2 = false>
; __device__ __forceinline__ void gemm_phase(PG8_LAS unsigned char* lds, const Gemm g, const Sched& S, const Epi& E, const int tid) {
;     ...
;             PG8_WAIT_V(8); PG8_WAIT_L(0); PG8_BAR; PG8_MMA(1, 0, At, B0); PG8_MMA(1, 1, At, B1); PG8_BAR; PG8_SCHED;
;             PG8_LDB(B0, 1, 0); PG8_LDB(B1, 1, 1); PG8_SCHED; PG8_LDA(At, 1, 0); PG8_STAGE(PG8_SA(0, 1), a2 + hstep, voffA);
;             PG8_WAIT_V(8); PG8_WAIT_L(0); PG8_BAR; PG8_MMA(0, 0, At, B0); PG8_MMA(0, 1, At, B1); PG8_BAR; PG8_SCHED;
	s_setprio 1
	s_waitcnt lgkmcnt(0)
	v_mfma_f32_16x16x32_bf16 v[60:63], v[138:141], v[172:175], v[60:63]
	v_mfma_f32_16x16x32_bf16 v[56:59], v[148:151], v[172:175], v[56:59]
	v_mfma_f32_16x16x32_bf16 v[44:47], v[138:141], v[180:183], v[44:47]
	v_mfma_f32_16x16x32_bf16 v[40:43], v[148:151], v[180:183], v[40:43]
	v_mfma_f32_16x16x32_bf16 v[28:31], v[138:141], v[188:191], v[28:31]
	v_mfma_f32_16x16x32_bf16 v[24:27], v[148:151], v[188:191], v[24:27]
	v_mfma_f32_16x16x32_bf16 v[12:15], v[138:141], v[216:219], v[12:15]
	v_mfma_f32_16x16x32_bf16 v[8:11], v[148:151], v[216:219], v[8:11]
	v_mfma_f32_16x16x32_bf16 v[60:63], v[144:147], v[176:179], v[60:63]
	v_mfma_f32_16x16x32_bf16 v[56:59], v[152:155], v[176:179], v[56:59]
	v_mfma_f32_16x16x32_bf16 v[44:47], v[144:147], v[184:187], v[44:47]
	v_mfma_f32_16x16x32_bf16 v[40:43], v[152:155], v[184:187], v[40:43]
	v_mfma_f32_16x16x32_bf16 v[28:31], v[144:147], v[212:215], v[28:31]
	v_mfma_f32_16x16x32_bf16 v[24:27], v[152:155], v[212:215], v[24:27]
	v_mfma_f32_16x16x32_bf16 v[12:15], v[144:147], v[232:235], v[12:15]
	v_mfma_f32_16x16x32_bf16 v[8:11], v[152:155], v[232:235], v[8:11]
	s_setprio 0
	s_setprio 1
	v_mfma_f32_16x16x32_bf16 v[52:55], v[156:159], v[172:175], v[52:55]
	v_mfma_f32_16x16x32_bf16 v[48:51], v[164:167], v[172:175], v[48:51]
	v_mfma_f32_16x16x32_bf16 v[36:39], v[156:159], v[180:183], v[36:39]
	v_mfma_f32_16x16x32_bf16 v[32:35], v[164:167], v[180:183], v[32:35]
	v_mfma_f32_16x16x32_bf16 v[20:23], v[156:159], v[188:191], v[20:23]
	v_mfma_f32_16x16x32_bf16 v[16:19], v[164:167], v[188:191], v[16:19]
	v_mfma_f32_16x16x32_bf16 v[4:7], v[156:159], v[216:219], v[4:7]
	v_mfma_f32_16x16x32_bf16 v[0:3], v[164:167], v[216:219], v[0:3]
	v_mfma_f32_16x16x32_bf16 v[52:55], v[160:163], v[176:179], v[52:55]
	v_mfma_f32_16x16x32_bf16 v[48:51], v[168:171], v[176:179], v[48:51]
	v_mfma_f32_16x16x32_bf16 v[36:39], v[160:163], v[184:187], v[36:39]
	v_mfma_f32_16x16x32_bf16 v[32:35], v[168:171], v[184:187], v[32:35]
	v_mfma_f32_16x16x32_bf16 v[20:23], v[160:163], v[212:215], v[20:23]
	v_mfma_f32_16x16x32_bf16 v[16:19], v[168:171], v[212:215], v[16:19]
	v_mfma_f32_16x16x32_bf16 v[4:7], v[160:163], v[232:235], v[4:7]
	v_mfma_f32_16x16x32_bf16 v[0:3], v[168:171], v[232:235], v[0:3]
	s_setprio 0
	s_barrier
	s_add_i32 s35, 0, 0x18000
	s_add_i32 s38, 0, 0x1c000
	v_add_u32_e32 v152, s35, v142
	v_add_u32_e32 v168, s38, v142
	ds_read_b128 v[138:141], v152
	ds_read_b128 v[144:147], v152 offset:1024
	ds_read_b128 v[148:151], v152 offset:2048
	ds_read_b128 v[152:155], v152 offset:3072
	ds_read_b128 v[156:159], v168
	ds_read_b128 v[160:163], v168 offset:1024
	ds_read_b128 v[164:167], v168 offset:2048
	ds_read_b128 v[168:171], v168 offset:3072
	s_add_u32 s40, s58, 0x20000
	s_addc_u32 s41, s59, 0
	s_mov_b32 m0, s85
	v_lshl_add_u64 v[206:207], s[40:41], 0, v[128:129]
	ds_read_b128 v[172:175], v143 offset:32768
	ds_read_b128 v[176:179], v143 offset:33792
	ds_read_b128 v[180:183], v143 offset:34816
	ds_read_b128 v[184:187], v143 offset:35840
	ds_read_b128 v[188:191], v143 offset:36864
	ds_read_b128 v[212:215], v143 offset:37888
	ds_read_b128 v[216:219], v143 offset:38912
	ds_read_b128 v[232:235], v143 offset:39936
	global_load_lds_dwordx4 v[206:207], off
	v_lshl_add_u64 v[206:207], s[40:41], 0, v[130:131]
	s_mov_b32 m0, s86
	s_nop 0
	global_load_lds_dwordx4 v[206:207], off
	s_waitcnt vmcnt(8)
	s_waitcnt lgkmcnt(0)
	s_barrier
	s_setprio 1
	s_waitcnt lgkmcnt(0)
	v_mfma_f32_16x16x32_bf16 v[124:127], v[138:141], v[172:175], v[124:127]
	v_mfma_f32_16x16x32_bf16 v[120:123], v[148:151], v[172:175], v[120:123]
	v_mfma_f32_16x16x32_bf16 v[108:111], v[138:141], v[180:183], v[108:111]
	v_mfma_f32_16x16x32_bf16 v[104:107], v[148:151], v[180:183], v[104:107]
	v_mfma_f32_16x16x32_bf16 v[92:95], v[138:141], v[188:191], v[92:95]
	v_mfma_f32_16x16x32_bf16 v[88:91], v[148:151], v[188:191], v[88:91]
	v_mfma_f32_16x16x32_bf16 v[76:79], v[138:141], v[216:219], v[76:79]
	v_mfma_f32_16x16x32_bf16 v[72:75], v[148:151], v[216:219], v[72:75]
	v_mfma_f32_16x16x32_bf16 v[124:127], v[144:147], v[176:179], v[124:127]
	v_mfma_f32_16x16x32_bf16 v[120:123], v[152:155], v[176:179], v[120:123]
	v_mfma_f32_16x16x32_bf16 v[108:111], v[144:147], v[184:187], v[108:111]
	v_mfma_f32_16x16x32_bf16 v[104:107], v[152:155], v[184:187], v[104:107]
	v_mfma_f32_16x16x32_bf16 v[92:95], v[144:147], v[212:215], v[92:95]
	v_mfma_f32_16x16x32_bf16 v[88:91], v[152:155], v[212:215], v[88:91]
	v_mfma_f32_16x16x32_bf16 v[76:79], v[144:147], v[232:235], v[76:79]
	v_mfma_f32_16x16x32_bf16 v[72:75], v[152:155], v[232:235], v[72:75]
	s_setprio 0
	s_setprio 1
	v_mfma_f32_16x16x32_bf16 v[116:119], v[156:159], v[172:175], v[116:119]
	v_mfma_f32_16x16x32_bf16 v[112:115], v[164:167], v[172:175], v[112:115]
	v_mfma_f32_16x16x32_bf16 v[100:103], v[156:159], v[180:183], v[100:103]
	v_mfma_f32_16x16x32_bf16 v[96:99], v[164:167], v[180:183], v[96:99]
	v_mfma_f32_16x16x32_bf16 v[84:87], v[156:159], v[188:191], v[84:87]
	v_mfma_f32_16x16x32_bf16 v[80:83], v[164:167], v[188:191], v[80:83]
	v_mfma_f32_16x16x32_bf16 v[68:71], v[156:159], v[216:219], v[68:71]
	v_mfma_f32_16x16x32_bf16 v[64:67], v[164:167], v[216:219], v[64:67]
	v_mfma_f32_16x16x32_bf16 v[116:119], v[160:163], v[176:179], v[116:119]
	v_mfma_f32_16x16x32_bf16 v[112:115], v[168:171], v[176:179], v[112:115]
	v_mfma_f32_16x16x32_bf16 v[100:103], v[160:163], v[184:187], v[100:103]
	v_mfma_f32_16x16x32_bf16 v[96:99], v[168:171], v[184:187], v[96:99]
	v_mfma_f32_16x16x32_bf16 v[84:87], v[160:163], v[212:215], v[84:87]
	v_mfma_f32_16x16x32_bf16 v[80:83], v[168:171], v[212:215], v[80:83]
	v_mfma_f32_16x16x32_bf16 v[68:71], v[160:163], v[232:235], v[68:71]
	v_mfma_f32_16x16x32_bf16 v[64:67], v[168:171], v[232:235], v[64:67]
	s_setprio 0
	s_barrier
; #define PG8_STAGE(bufoff, gbase, voff) do { _Pragma("unroll") for (int _i = 0; _i < 2; ++_i) \
;         __builtin_amdgcn_global_load_lds((const unsigned*)((const char*)(gbase) + (voff)[_i]), (PG8_LAS unsigned*)(lds + (bufoff) + ldsw + _i * 8192), 16, 0, 0); } while (0)
; #define PG8_LDA(dst, b, h) do { _Pragma("unroll") for (int m = 0; m < 4; ++m) _Pragma("unroll") for (int k = 0; k < 2; ++k) dst[m][k] = *(const PG8_LAS bf16x8*)(lds + PG8_SA(b, h) + aoff + m * 2048 + k * 1024); } while (0)
; #define PG8_MMA(ai, bj, At, Bt) do { __builtin_amdgcn_s_setprio(1); _Pragma("unroll") for (int m = 0; m < 4; ++m) _Pragma("unroll") for (int n = 0; n < 2; ++n) _Pragma("unroll") for (int k = 0; k < 2; ++k) \
;         acc[ai][bj][m][n] = __builtin_amdgcn_mfma_f32_16x16x32_bf16(Bt[n][k], At[m][k], acc[ai][bj][m][n], 0, 0, 0); __builtin_amdgcn_s_setprio(0); } while (0)
; #define PG8_WAIT_V(n) asm volatile("s_waitcnt vmcnt(" #n ")" ::: "memory")
; #define PG8_WAIT_L(n) asm volatile("s_waitcnt lgkmcnt(" #n ")" ::: "memory")
; #define PG8_BAR __builtin_amdgcn_s_barrier()
; #define PG8_SCHED __builtin_amdgcn_sched_barrier(0)
; template <class Epi, class Sched, bool ALIGN_EPI = false, bool SP2 = false>
; __device__ __forceinline__ void gemm_phase(PG8_LAS unsigned char* lds, const Gemm g, const Sched& S, const Epi& E, const int tid) {
;     ...
;             PG8_LDA(At, 1, 1); PG8_STAGE(PG8_SB(1, 0), b3, voffB); PG8_STAGE(PG8_SB(1, 1), b3 + hstep, voffB); PG8_STAGE(PG8_SA(1, 0), a3, voffA);
;             PG8_WAIT_V(8); PG8_WAIT_L(0); PG8_BAR; PG8_MMA(1, 0, At, B0); PG8_MMA(1, 1, At, B1); PG8_BAR; PG8_SCHED;
;     ...
;         if constexpr (ALIGN_EPI) { if (wr == 0) PG8_BAR; }
	s_add_i32 s35, s35, s82
	v_lshl_add_u64 v[194:195], v[194:195], 0, s[36:37]
	s_mov_b32 m0, s35
	ds_read_b128 v[172:175], v143 offset:49152
	ds_read_b128 v[176:179], v143 offset:50176
	ds_read_b128 v[180:183], v143 offset:51200
	ds_read_b128 v[184:187], v143 offset:52224
	ds_read_b128 v[188:191], v143 offset:53248
	ds_read_b128 v[212:215], v143 offset:54272
	ds_read_b128 v[216:219], v143 offset:55296
	ds_read_b128 v[232:235], v143 offset:56320
	global_load_lds_dwordx4 v[194:195], off
	s_add_i32 m0, s35, 0x2000
	s_add_u32 s40, s44, 0x20080
	v_lshl_add_u64 v[194:195], v[196:197], 0, s[36:37]
	s_addc_u32 s41, s45, 0
	s_add_i32 s35, s38, s82
	global_load_lds_dwordx4 v[194:195], off
	v_lshl_add_u64 v[194:195], s[40:41], 0, v[192:193]
	s_mov_b32 m0, s35
	s_nop 0
	global_load_lds_dwordx4 v[194:195], off
	v_lshl_add_u64 v[194:195], s[40:41], 0, v[132:133]
	s_add_i32 m0, s35, 0x2000
	s_nop 0
	global_load_lds_dwordx4 v[194:195], off
	v_lshl_add_u64 v[194:195], v[202:203], 0, s[36:37]
	s_mov_b32 m0, s87
	s_nop 0
	global_load_lds_dwordx4 v[194:195], off
	v_lshl_add_u64 v[194:195], v[204:205], 0, s[36:37]
	s_mov_b32 m0, s88
	s_nop 0
	global_load_lds_dwordx4 v[194:195], off
	s_add_i32 s34, s34, 2
	s_add_u32 s28, s28, 0x100
	s_addc_u32 s29, s29, 0
	s_add_u32 s23, s23, 0x100
	s_addc_u32 s26, s26, 0
	s_cmp_gt_u32 s34, 5
	s_waitcnt vmcnt(8)
	s_waitcnt lgkmcnt(0)
	s_barrier
	s_setprio 1
	s_waitcnt lgkmcnt(0)
	v_mfma_f32_16x16x32_bf16 v[60:63], v[138:141], v[172:175], v[60:63]
	v_mfma_f32_16x16x32_bf16 v[56:59], v[148:151], v[172:175], v[56:59]
	v_mfma_f32_16x16x32_bf16 v[44:47], v[138:141], v[180:183], v[44:47]
	v_mfma_f32_16x16x32_bf16 v[40:43], v[148:151], v[180:183], v[40:43]
	v_mfma_f32_16x16x32_bf16 v[28:31], v[138:141], v[188:191], v[28:31]
	v_mfma_f32_16x16x32_bf16 v[24:27], v[148:151], v[188:191], v[24:27]
	v_mfma_f32_16x16x32_bf16 v[12:15], v[138:141], v[216:219], v[12:15]
	v_mfma_f32_16x16x32_bf16 v[8:11], v[148:151], v[216:219], v[8:11]
	v_mfma_f32_16x16x32_bf16 v[60:63], v[144:147], v[176:179], v[60:63]
	v_mfma_f32_16x16x32_bf16 v[56:59], v[152:155], v[176:179], v[56:59]
	v_mfma_f32_16x16x32_bf16 v[44:47], v[144:147], v[184:187], v[44:47]
	v_mfma_f32_16x16x32_bf16 v[40:43], v[152:155], v[184:187], v[40:43]
	v_mfma_f32_16x16x32_bf16 v[28:31], v[144:147], v[212:215], v[28:31]
	v_mfma_f32_16x16x32_bf16 v[24:27], v[152:155], v[212:215], v[24:27]
	v_mfma_f32_16x16x32_bf16 v[12:15], v[144:147], v[232:235], v[12:15]
	v_mfma_f32_16x16x32_bf16 v[8:11], v[152:155], v[232:235], v[8:11]
	s_setprio 0
	s_setprio 1
	v_mfma_f32_16x16x32_bf16 v[52:55], v[156:159], v[172:175], v[52:55]
	v_mfma_f32_16x16x32_bf16 v[48:51], v[164:167], v[172:175], v[48:51]
	v_mfma_f32_16x16x32_bf16 v[36:39], v[156:159], v[180:183], v[36:39]
	v_mfma_f32_16x16x32_bf16 v[32:35], v[164:167], v[180:183], v[32:35]
	v_mfma_f32_16x16x32_bf16 v[20:23], v[156:159], v[188:191], v[20:23]
	v_mfma_f32_16x16x32_bf16 v[16:19], v[164:167], v[188:191], v[16:19]
	v_mfma_f32_16x16x32_bf16 v[4:7], v[156:159], v[216:219], v[4:7]
	v_mfma_f32_16x16x32_bf16 v[0:3], v[164:167], v[216:219], v[0:3]
	v_mfma_f32_16x16x32_bf16 v[52:55], v[160:163], v[176:179], v[52:55]
	v_mfma_f32_16x16x32_bf16 v[48:51], v[168:171], v[176:179], v[48:51]
	v_mfma_f32_16x16x32_bf16 v[36:39], v[160:163], v[184:187], v[36:39]
	v_mfma_f32_16x16x32_bf16 v[32:35], v[168:171], v[184:187], v[32:35]
	v_mfma_f32_16x16x32_bf16 v[20:23], v[160:163], v[212:215], v[20:23]
	v_mfma_f32_16x16x32_bf16 v[16:19], v[168:171], v[212:215], v[16:19]
	v_mfma_f32_16x16x32_bf16 v[4:7], v[160:163], v[232:235], v[4:7]
	v_mfma_f32_16x16x32_bf16 v[0:3], v[168:171], v[232:235], v[0:3]
	s_setprio 0
	s_barrier
	s_cbranch_scc0 .LBB0_348
	s_and_b64 vcc, exec, s[12:13]
	s_cbranch_vccz .LBB0_351
	s_barrier

; #define PG8_STAGE(bufoff, gbase, voff) do { _Pragma("unroll") for (int _i = 0; _i < 2; ++_i) \
;         __builtin_amdgcn_global_load_lds((const unsigned*)((const char*)(gbase) + (voff)[_i]), (PG8_LAS unsigned*)(lds + (bufoff) + ldsw + _i * 8192), 16, 0, 0); } while (0)
; #define PG8_LDA(dst, b, h) do { _Pragma("unroll") for (int m = 0; m < 4; ++m) _Pragma("unroll") for (int k = 0; k < 2; ++k) dst[m][k] = *(const PG8_LAS bf16x8*)(lds + PG8_SA(b, h) + aoff + m * 2048 + k * 1024); } while (0)
; #define PG8_LDB(dst, b, h) do { _Pragma("unroll") for (int n = 0; n < 2; ++n) _Pragma("unroll") for (int k = 0; k < 2; ++k) dst[n][k] = *(const PG8_LAS bf16x8*)(lds + PG8_SB(b, h) + boff + n * 2048 + k * 1024); } while (0)
; #define PG8_MMA(ai, bj, At, Bt) do { __builtin_amdgcn_s_setprio(1); _Pragma("unroll") for (int m = 0; m < 4; ++m) _Pragma("unroll") for (int n = 0; n < 2; ++n) _Pragma("unroll") for (int k = 0; k < 2; ++k) \
;         acc[ai][bj][m][n] = __builtin_amdgcn_mfma_f32_16x16x32_bf16(Bt[n][k], At[m][k], acc[ai][bj][m][n], 0, 0, 0); __builtin_amdgcn_s_setprio(0); } while (0)
; #define PG8_WAIT_V(n) asm volatile("s_waitcnt vmcnt(" #n ")" ::: "memory")
; #define PG8_BAR __builtin_amdgcn_s_barrier()
; template <class Epi, class Sched, bool ALIGN_EPI = false, bool SP2 = false>
; __device__ __forceinline__ void gemm_phase(PG8_LAS unsigned char* lds, const Gemm g, const Sched& S, const Epi& E, const int tid) {
;     ...
;         for (int t = 0; t < nt; t += 2) {
;             const bool last = (t == nt - 2);
;             const char* a1 = cA + (size_t)(t + 1) * kstep;
;             const char* a2 = last ? nA : cA + (size_t)(t + 2) * kstep; const char* b2 = last ? nB : cB + (size_t)(t + 2) * kstep;
;             const char* a3 = a2 + kstep; const char* b3 = b2 + kstep;
;             if (last && has_next) S.a_ready(nxt);
;             if constexpr (SP2) {
;             PG8_LDB(B0, 0, 0); PG8_LDB(B1, 0, 1); PG8_SCHED; PG8_LDA(At, 0, 0); PG8_STAGE(PG8_SA(1, 1), a1 + hstep, voffA);
;             PG8_WAIT_V(8); PG8_WAIT_L(0); PG8_BAR; PG8_MMA(0, 0, At, B0); PG8_MMA(0, 1, At, B1); PG8_BAR; PG8_SCHED;
;             PG8_LDA(At, 0, 1); PG8_STAGE(PG8_SB(0, 0), b2, voffB); PG8_STAGE(PG8_SB(0, 1), b2 + hstep, voffB); PG8_STAGE(PG8_SA(0, 0), a2, voffA);
;             PG8_WAIT_V(8); PG8_WAIT_L(0); PG8_BAR; PG8_MMA(1, 0, At, B0); PG8_MMA(1, 1, At, B1); PG8_BAR; PG8_SCHED;
.LBB0_485:
	v_add_u32_e32 v140, 0x10000, v184
	v_add_u32_e32 v168, 0x14000, v184
	ds_read_b128 v[128:131], v140
	ds_read_b128 v[132:135], v140 offset:1024
	ds_read_b128 v[136:139], v140 offset:2048
	ds_read_b128 v[140:143], v140 offset:3072
	ds_read_b128 v[144:147], v168
	ds_read_b128 v[148:151], v168 offset:1024
	ds_read_b128 v[164:167], v168 offset:2048
	ds_read_b128 v[168:171], v168 offset:3072
	s_add_u32 s38, s8, 0xfffc0080
	s_addc_u32 s40, s9, -1
	s_add_i32 s41, 0, 0x10000
	s_cmp_eq_u32 s35, 12
	s_cselect_b32 s59, s0, s40
	s_cselect_b32 s58, s1, s38
	s_cselect_b32 s45, s2, s34
	s_cselect_b32 s44, s15, s17
	s_add_i32 s38, 0, 0x14000
	v_lshl_add_u64 v[190:191], s[8:9], 0, v[160:161]
	s_add_i32 m0, s23, 0xc000
	ds_read_b128 v[172:175], v185
	ds_read_b128 v[176:179], v185 offset:1024
	ds_read_b128 v[180:183], v185 offset:2048
	ds_read_b128 v[186:189], v185 offset:3072
	ds_read_b128 v[212:215], v185 offset:4096
	ds_read_b128 v[216:219], v185 offset:5120
	ds_read_b128 v[232:235], v185 offset:6144
	ds_read_b128 v[236:239], v185 offset:7168
	global_load_lds_dwordx4 v[190:191], off
	v_lshl_add_u64 v[190:191], s[8:9], 0, v[162:163]
	s_add_i32 m0, s23, 0xe000
	s_nop 0
	global_load_lds_dwordx4 v[190:191], off
	s_waitcnt vmcnt(8)
	s_waitcnt lgkmcnt(0)
	s_barrier
	s_setprio 1
	s_waitcnt lgkmcnt(0)
	v_mfma_f32_16x16x32_bf16 v[124:127], v[128:131], v[172:175], v[124:127]
	v_mfma_f32_16x16x32_bf16 v[120:123], v[136:139], v[172:175], v[120:123]
	v_mfma_f32_16x16x32_bf16 v[108:111], v[128:131], v[180:183], v[108:111]
	v_mfma_f32_16x16x32_bf16 v[104:107], v[136:139], v[180:183], v[104:107]
	v_mfma_f32_16x16x32_bf16 v[92:95], v[128:131], v[212:215], v[92:95]
	v_mfma_f32_16x16x32_bf16 v[88:91], v[136:139], v[212:215], v[88:91]
	v_mfma_f32_16x16x32_bf16 v[76:79], v[128:131], v[232:235], v[76:79]
	v_mfma_f32_16x16x32_bf16 v[72:75], v[136:139], v[232:235], v[72:75]
	v_mfma_f32_16x16x32_bf16 v[124:127], v[132:135], v[176:179], v[124:127]
	v_mfma_f32_16x16x32_bf16 v[120:123], v[140:143], v[176:179], v[120:123]
	v_mfma_f32_16x16x32_bf16 v[108:111], v[132:135], v[186:189], v[108:111]
	v_mfma_f32_16x16x32_bf16 v[104:107], v[140:143], v[186:189], v[104:107]
	v_mfma_f32_16x16x32_bf16 v[92:95], v[132:135], v[216:219], v[92:95]
	v_mfma_f32_16x16x32_bf16 v[88:91], v[140:143], v[216:219], v[88:91]
	v_mfma_f32_16x16x32_bf16 v[76:79], v[132:135], v[236:239], v[76:79]
	v_mfma_f32_16x16x32_bf16 v[72:75], v[140:143], v[236:239], v[72:75]
	s_setprio 0
	s_setprio 1
	v_mfma_f32_16x16x32_bf16 v[116:119], v[144:147], v[172:175], v[116:119]
	v_mfma_f32_16x16x32_bf16 v[112:115], v[164:167], v[172:175], v[112:115]
	v_mfma_f32_16x16x32_bf16 v[100:103], v[144:147], v[180:183], v[100:103]
	v_mfma_f32_16x16x32_bf16 v[96:99], v[164:167], v[180:183], v[96:99]
	v_mfma_f32_16x16x32_bf16 v[84:87], v[144:147], v[212:215], v[84:87]
	v_mfma_f32_16x16x32_bf16 v[80:83], v[164:167], v[212:215], v[80:83]
	v_mfma_f32_16x16x32_bf16 v[68:71], v[144:147], v[232:235], v[68:71]
	v_mfma_f32_16x16x32_bf16 v[64:67], v[164:167], v[232:235], v[64:67]
	v_mfma_f32_16x16x32_bf16 v[116:119], v[148:151], v[176:179], v[116:119]
	v_mfma_f32_16x16x32_bf16 v[112:115], v[168:171], v[176:179], v[112:115]
	v_mfma_f32_16x16x32_bf16 v[100:103], v[148:151], v[186:189], v[100:103]
	v_mfma_f32_16x16x32_bf16 v[96:99], v[168:171], v[186:189], v[96:99]
	v_mfma_f32_16x16x32_bf16 v[84:87], v[148:151], v[216:219], v[84:87]
	v_mfma_f32_16x16x32_bf16 v[80:83], v[168:171], v[216:219], v[80:83]
	v_mfma_f32_16x16x32_bf16 v[68:71], v[148:151], v[236:239], v[68:71]
	v_mfma_f32_16x16x32_bf16 v[64:67], v[168:171], v[236:239], v[64:67]
	s_setprio 0
	s_barrier
	s_add_i32 s40, s41, s83
	v_lshl_add_u64 v[190:191], s[44:45], 0, v[154:155]
	s_mov_b32 m0, s40
	ds_read_b128 v[172:175], v185 offset:16384
	ds_read_b128 v[176:179], v185 offset:17408
	ds_read_b128 v[180:183], v185 offset:18432
	ds_read_b128 v[186:189], v185 offset:19456
	ds_read_b128 v[212:215], v185 offset:20480
	ds_read_b128 v[216:219], v185 offset:21504
	ds_read_b128 v[232:235], v185 offset:22528
	ds_read_b128 v[236:239], v185 offset:23552
	global_load_lds_dwordx4 v[190:191], off
	s_add_i32 m0, s40, 0x2000
	s_add_u32 s40, s44, 0x40000
	v_lshl_add_u64 v[194:195], s[44:45], 0, v[158:159]
	s_addc_u32 s41, s45, 0
	s_add_i32 s38, s38, s83
	global_load_lds_dwordx4 v[194:195], off
	v_lshl_add_u64 v[196:197], s[40:41], 0, v[154:155]
	s_mov_b32 m0, s38
	v_lshl_add_u64 v[202:203], s[58:59], 0, v[156:157]
	global_load_lds_dwordx4 v[196:197], off
	v_lshl_add_u64 v[196:197], s[40:41], 0, v[158:159]
	s_add_i32 m0, s38, 0x2000
	s_nop 0
	global_load_lds_dwordx4 v[196:197], off
	v_lshl_add_u64 v[196:197], s[58:59], 0, v[152:153]
	s_mov_b32 m0, s23
	s_nop 0
	global_load_lds_dwordx4 v[196:197], off
	s_mov_b32 m0, s29
	s_nop 0
	global_load_lds_dwordx4 v[202:203], off
	s_waitcnt vmcnt(8)
	s_waitcnt lgkmcnt(0)
	s_barrier
; #define PG8_STAGE(bufoff, gbase, voff) do { _Pragma("unroll") for (int _i = 0; _i < 2; ++_i) \
;         __builtin_amdgcn_global_load_lds((const unsigned*)((const char*)(gbase) + (voff)[_i]), (PG8_LAS unsigned*)(lds + (bufoff) + ldsw + _i * 8192), 16, 0, 0); } while (0)
; #define PG8_LDA(dst, b, h) do { _Pragma("unroll") for (int m = 0; m < 4; ++m) _Pragma("unroll") for (int k = 0; k < 2; ++k) dst[m][k] = *(const PG8_LAS bf16x8*)(lds + PG8_SA(b, h) + aoff + m * 2048 + k * 1024); } while (0)
; #define PG8_LDB(dst, b, h) do { _Pragma("unroll") for (int n = 0; n < 2; ++n) _Pragma("unroll") for (int k = 0; k < 2; ++k) dst[n][k] = *(const PG8_LAS bf16x8*)(lds + PG8_SB(b, h) + boff + n * 2048 + k * 1024); } while (0)
; #define PG8_MMA(ai, bj, At, Bt) do { __builtin_amdgcn_s_setprio(1); _Pragma("unroll") for (int m = 0; m < 4; ++m) _Pragma("unroll") for (int n = 0; n < 2; ++n) _Pragma("unroll") for (int k = 0; k < 2; ++k) \
;         acc[ai][bj][m][n] = __builtin_amdgcn_mfma_f32_16x16x32_bf16(Bt[n][k], At[m][k], acc[ai][bj][m][n], 0, 0, 0); __builtin_amdgcn_s_setprio(0); } while (0)
; #define PG8_WAIT_V(n) asm volatile("s_waitcnt vmcnt(" #n ")" ::: "memory")
; #define PG8_WAIT_L(n) asm volatile("s_waitcnt lgkmcnt(" #n ")" ::: "memory")
; #define PG8_BAR __builtin_amdgcn_s_barrier()
; #define PG8_SCHED __builtin_amdgcn_sched_barrier(0)
; template <class Epi, class Sched, bool ALIGN_EPI = false, bool SP2 = false>
; __device__ __forceinline__ void gemm_phase(PG8_LAS unsigned char* lds, const Gemm g, const Sched& S, const Epi& E, const int tid) {
;     ...
;             PG8_WAIT_V(8); PG8_WAIT_L(0); PG8_BAR; PG8_MMA(1, 0, At, B0); PG8_MMA(1, 1, At, B1); PG8_BAR; PG8_SCHED;
;             PG8_LDB(B0, 1, 0); PG8_LDB(B1, 1, 1); PG8_SCHED; PG8_LDA(At, 1, 0); PG8_STAGE(PG8_SA(0, 1), a2 + hstep, voffA);
;             PG8_WAIT_V(8); PG8_WAIT_L(0); PG8_BAR; PG8_MMA(0, 0, At, B0); PG8_MMA(0, 1, At, B1); PG8_BAR; PG8_SCHED;
	s_setprio 1
	s_waitcnt lgkmcnt(0)
	v_mfma_f32_16x16x32_bf16 v[60:63], v[128:131], v[172:175], v[60:63]
	v_mfma_f32_16x16x32_bf16 v[56:59], v[136:139], v[172:175], v[56:59]
	v_mfma_f32_16x16x32_bf16 v[44:47], v[128:131], v[180:183], v[44:47]
	v_mfma_f32_16x16x32_bf16 v[40:43], v[136:139], v[180:183], v[40:43]
	v_mfma_f32_16x16x32_bf16 v[28:31], v[128:131], v[212:215], v[28:31]
	v_mfma_f32_16x16x32_bf16 v[24:27], v[136:139], v[212:215], v[24:27]
	v_mfma_f32_16x16x32_bf16 v[12:15], v[128:131], v[232:235], v[12:15]
	v_mfma_f32_16x16x32_bf16 v[8:11], v[136:139], v[232:235], v[8:11]
	v_mfma_f32_16x16x32_bf16 v[60:63], v[132:135], v[176:179], v[60:63]
	v_mfma_f32_16x16x32_bf16 v[56:59], v[140:143], v[176:179], v[56:59]
	v_mfma_f32_16x16x32_bf16 v[44:47], v[132:135], v[186:189], v[44:47]
	v_mfma_f32_16x16x32_bf16 v[40:43], v[140:143], v[186:189], v[40:43]
	v_mfma_f32_16x16x32_bf16 v[28:31], v[132:135], v[216:219], v[28:31]
	v_mfma_f32_16x16x32_bf16 v[24:27], v[140:143], v[216:219], v[24:27]
	v_mfma_f32_16x16x32_bf16 v[12:15], v[132:135], v[236:239], v[12:15]
	v_mfma_f32_16x16x32_bf16 v[8:11], v[140:143], v[236:239], v[8:11]
	s_setprio 0
	s_setprio 1
	v_mfma_f32_16x16x32_bf16 v[52:55], v[144:147], v[172:175], v[52:55]
	v_mfma_f32_16x16x32_bf16 v[48:51], v[164:167], v[172:175], v[48:51]
	v_mfma_f32_16x16x32_bf16 v[36:39], v[144:147], v[180:183], v[36:39]
	v_mfma_f32_16x16x32_bf16 v[32:35], v[164:167], v[180:183], v[32:35]
	v_mfma_f32_16x16x32_bf16 v[20:23], v[144:147], v[212:215], v[20:23]
	v_mfma_f32_16x16x32_bf16 v[16:19], v[164:167], v[212:215], v[16:19]
	v_mfma_f32_16x16x32_bf16 v[4:7], v[144:147], v[232:235], v[4:7]
	v_mfma_f32_16x16x32_bf16 v[0:3], v[164:167], v[232:235], v[0:3]
	v_mfma_f32_16x16x32_bf16 v[52:55], v[148:151], v[176:179], v[52:55]
	v_mfma_f32_16x16x32_bf16 v[48:51], v[168:171], v[176:179], v[48:51]
	v_mfma_f32_16x16x32_bf16 v[36:39], v[148:151], v[186:189], v[36:39]
	v_mfma_f32_16x16x32_bf16 v[32:35], v[168:171], v[186:189], v[32:35]
	v_mfma_f32_16x16x32_bf16 v[20:23], v[148:151], v[216:219], v[20:23]
	v_mfma_f32_16x16x32_bf16 v[16:19], v[168:171], v[216:219], v[16:19]
	v_mfma_f32_16x16x32_bf16 v[4:7], v[148:151], v[236:239], v[4:7]
	v_mfma_f32_16x16x32_bf16 v[0:3], v[168:171], v[236:239], v[0:3]
	s_setprio 0
	s_barrier
	s_add_i32 s38, 0, 0x18000
	s_add_i32 s46, 0, 0x1c000
	v_add_u32_e32 v140, s38, v184
	v_add_u32_e32 v168, s46, v184
	ds_read_b128 v[128:131], v140
	ds_read_b128 v[132:135], v140 offset:1024
	ds_read_b128 v[136:139], v140 offset:2048
	ds_read_b128 v[140:143], v140 offset:3072
	ds_read_b128 v[144:147], v168
	ds_read_b128 v[148:151], v168 offset:1024
	ds_read_b128 v[164:167], v168 offset:2048
	ds_read_b128 v[168:171], v168 offset:3072
	s_add_u32 s40, s58, 0x40000
	s_addc_u32 s41, s59, 0
	s_mov_b32 m0, s84
	v_lshl_add_u64 v[204:205], s[40:41], 0, v[152:153]
	ds_read_b128 v[172:175], v185 offset:32768
	ds_read_b128 v[176:179], v185 offset:33792
	ds_read_b128 v[180:183], v185 offset:34816
	ds_read_b128 v[186:189], v185 offset:35840
	ds_read_b128 v[212:215], v185 offset:36864
	ds_read_b128 v[216:219], v185 offset:37888
	ds_read_b128 v[232:235], v185 offset:38912
	ds_read_b128 v[236:239], v185 offset:39936
	global_load_lds_dwordx4 v[204:205], off
	v_lshl_add_u64 v[204:205], s[40:41], 0, v[156:157]
	s_mov_b32 m0, s85
	s_nop 0
	global_load_lds_dwordx4 v[204:205], off
	s_waitcnt vmcnt(8)
	s_waitcnt lgkmcnt(0)
	s_barrier
	s_setprio 1
	s_waitcnt lgkmcnt(0)
	v_mfma_f32_16x16x32_bf16 v[124:127], v[128:131], v[172:175], v[124:127]
	v_mfma_f32_16x16x32_bf16 v[120:123], v[136:139], v[172:175], v[120:123]
	v_mfma_f32_16x16x32_bf16 v[108:111], v[128:131], v[180:183], v[108:111]
	v_mfma_f32_16x16x32_bf16 v[104:107], v[136:139], v[180:183], v[104:107]
	v_mfma_f32_16x16x32_bf16 v[92:95], v[128:131], v[212:215], v[92:95]
	v_mfma_f32_16x16x32_bf16 v[88:91], v[136:139], v[212:215], v[88:91]
	v_mfma_f32_16x16x32_bf16 v[76:79], v[128:131], v[232:235], v[76:79]
	v_mfma_f32_16x16x32_bf16 v[72:75], v[136:139], v[232:235], v[72:75]
	v_mfma_f32_16x16x32_bf16 v[124:127], v[132:135], v[176:179], v[124:127]
	v_mfma_f32_16x16x32_bf16 v[120:123], v[140:143], v[176:179], v[120:123]
	v_mfma_f32_16x16x32_bf16 v[108:111], v[132:135], v[186:189], v[108:111]
	v_mfma_f32_16x16x32_bf16 v[104:107], v[140:143], v[186:189], v[104:107]
	v_mfma_f32_16x16x32_bf16 v[92:95], v[132:135], v[216:219], v[92:95]
	v_mfma_f32_16x16x32_bf16 v[88:91], v[140:143], v[216:219], v[88:91]
	v_mfma_f32_16x16x32_bf16 v[76:79], v[132:135], v[236:239], v[76:79]
	v_mfma_f32_16x16x32_bf16 v[72:75], v[140:143], v[236:239], v[72:75]
	s_setprio 0
	s_setprio 1
	v_mfma_f32_16x16x32_bf16 v[116:119], v[144:147], v[172:175], v[116:119]
	v_mfma_f32_16x16x32_bf16 v[112:115], v[164:167], v[172:175], v[112:115]
	v_mfma_f32_16x16x32_bf16 v[100:103], v[144:147], v[180:183], v[100:103]
	v_mfma_f32_16x16x32_bf16 v[96:99], v[164:167], v[180:183], v[96:99]
	v_mfma_f32_16x16x32_bf16 v[84:87], v[144:147], v[212:215], v[84:87]
	v_mfma_f32_16x16x32_bf16 v[80:83], v[164:167], v[212:215], v[80:83]
	v_mfma_f32_16x16x32_bf16 v[68:71], v[144:147], v[232:235], v[68:71]
	v_mfma_f32_16x16x32_bf16 v[64:67], v[164:167], v[232:235], v[64:67]
	v_mfma_f32_16x16x32_bf16 v[116:119], v[148:151], v[176:179], v[116:119]
	v_mfma_f32_16x16x32_bf16 v[112:115], v[168:171], v[176:179], v[112:115]
	v_mfma_f32_16x16x32_bf16 v[100:103], v[148:151], v[186:189], v[100:103]
	v_mfma_f32_16x16x32_bf16 v[96:99], v[168:171], v[186:189], v[96:99]
	v_mfma_f32_16x16x32_bf16 v[84:87], v[148:151], v[216:219], v[84:87]
	v_mfma_f32_16x16x32_bf16 v[80:83], v[168:171], v[216:219], v[80:83]
	v_mfma_f32_16x16x32_bf16 v[68:71], v[148:151], v[236:239], v[68:71]
	v_mfma_f32_16x16x32_bf16 v[64:67], v[168:171], v[236:239], v[64:67]
	s_setprio 0
	s_barrier
; #define PG8_STAGE(bufoff, gbase, voff) do { _Pragma("unroll") for (int _i = 0; _i < 2; ++_i) \
;         __builtin_amdgcn_global_load_lds((const unsigned*)((const char*)(gbase) + (voff)[_i]), (PG8_LAS unsigned*)(lds + (bufoff) + ldsw + _i * 8192), 16, 0, 0); } while (0)
; #define PG8_LDA(dst, b, h) do { _Pragma("unroll") for (int m = 0; m < 4; ++m) _Pragma("unroll") for (int k = 0; k < 2; ++k) dst[m][k] = *(const PG8_LAS bf16x8*)(lds + PG8_SA(b, h) + aoff + m * 2048 + k * 1024); } while (0)
; #define PG8_MMA(ai, bj, At, Bt) do { __builtin_amdgcn_s_setprio(1); _Pragma("unroll") for (int m = 0; m < 4; ++m) _Pragma("unroll") for (int n = 0; n < 2; ++n) _Pragma("unroll") for (int k = 0; k < 2; ++k) \
;         acc[ai][bj][m][n] = __builtin_amdgcn_mfma_f32_16x16x32_bf16(Bt[n][k], At[m][k], acc[ai][bj][m][n], 0, 0, 0); __builtin_amdgcn_s_setprio(0); } while (0)
; #define PG8_WAIT_V(n) asm volatile("s_waitcnt vmcnt(" #n ")" ::: "memory")
; #define PG8_WAIT_L(n) asm volatile("s_waitcnt lgkmcnt(" #n ")" ::: "memory")
; #define PG8_BAR __builtin_amdgcn_s_barrier()
; #define PG8_SCHED __builtin_amdgcn_sched_barrier(0)
; template <class Epi, class Sched, bool ALIGN_EPI = false, bool SP2 = false>
; __device__ __forceinline__ void gemm_phase(PG8_LAS unsigned char* lds, const Gemm g, const Sched& S, const Epi& E, const int tid) {
;     ...
;             PG8_LDA(At, 1, 1); PG8_STAGE(PG8_SB(1, 0), b3, voffB); PG8_STAGE(PG8_SB(1, 1), b3 + hstep, voffB); PG8_STAGE(PG8_SA(1, 0), a3, voffA);
;             PG8_WAIT_V(8); PG8_WAIT_L(0); PG8_BAR; PG8_MMA(1, 0, At, B0); PG8_MMA(1, 1, At, B1); PG8_BAR; PG8_SCHED;
;     ...
;         if constexpr (ALIGN_EPI) { if (wr == 0) PG8_BAR; }
	s_add_i32 s38, s38, s83
	v_lshl_add_u64 v[190:191], v[190:191], 0, s[36:37]
	s_mov_b32 m0, s38
	ds_read_b128 v[172:175], v185 offset:49152
	ds_read_b128 v[176:179], v185 offset:50176
	ds_read_b128 v[180:183], v185 offset:51200
	ds_read_b128 v[186:189], v185 offset:52224
	ds_read_b128 v[212:215], v185 offset:53248
	ds_read_b128 v[216:219], v185 offset:54272
	ds_read_b128 v[232:235], v185 offset:55296
	ds_read_b128 v[236:239], v185 offset:56320
	global_load_lds_dwordx4 v[190:191], off
	s_add_i32 m0, s38, 0x2000
	s_add_u32 s40, s44, 0x40080
	v_lshl_add_u64 v[190:191], v[194:195], 0, s[36:37]
	s_addc_u32 s41, s45, 0
	s_add_i32 s38, s46, s83
	global_load_lds_dwordx4 v[190:191], off
	v_lshl_add_u64 v[190:191], s[40:41], 0, v[154:155]
	s_mov_b32 m0, s38
	s_nop 0
	global_load_lds_dwordx4 v[190:191], off
	v_lshl_add_u64 v[190:191], s[40:41], 0, v[158:159]
	s_add_i32 m0, s38, 0x2000
	s_nop 0
	global_load_lds_dwordx4 v[190:191], off
	v_lshl_add_u64 v[190:191], v[196:197], 0, s[36:37]
	s_mov_b32 m0, s86
	s_nop 0
	global_load_lds_dwordx4 v[190:191], off
	v_lshl_add_u64 v[190:191], v[202:203], 0, s[36:37]
	s_mov_b32 m0, s87
	s_nop 0
	global_load_lds_dwordx4 v[190:191], off
	s_add_i32 s35, s35, 2
	s_add_u32 s8, s8, 0x100
	s_addc_u32 s9, s9, 0
	s_add_u32 s17, s17, 0x100
	s_addc_u32 s34, s34, 0
	s_cmp_gt_u32 s35, 13
	s_waitcnt vmcnt(8)
	s_waitcnt lgkmcnt(0)
	s_barrier
	s_setprio 1
	s_waitcnt lgkmcnt(0)
	v_mfma_f32_16x16x32_bf16 v[60:63], v[128:131], v[172:175], v[60:63]
	v_mfma_f32_16x16x32_bf16 v[56:59], v[136:139], v[172:175], v[56:59]
	v_mfma_f32_16x16x32_bf16 v[44:47], v[128:131], v[180:183], v[44:47]
	v_mfma_f32_16x16x32_bf16 v[40:43], v[136:139], v[180:183], v[40:43]
	v_mfma_f32_16x16x32_bf16 v[28:31], v[128:131], v[212:215], v[28:31]
	v_mfma_f32_16x16x32_bf16 v[24:27], v[136:139], v[212:215], v[24:27]
	v_mfma_f32_16x16x32_bf16 v[12:15], v[128:131], v[232:235], v[12:15]
	v_mfma_f32_16x16x32_bf16 v[8:11], v[136:139], v[232:235], v[8:11]
	v_mfma_f32_16x16x32_bf16 v[60:63], v[132:135], v[176:179], v[60:63]
	v_mfma_f32_16x16x32_bf16 v[56:59], v[140:143], v[176:179], v[56:59]
	v_mfma_f32_16x16x32_bf16 v[44:47], v[132:135], v[186:189], v[44:47]
	v_mfma_f32_16x16x32_bf16 v[40:43], v[140:143], v[186:189], v[40:43]
	v_mfma_f32_16x16x32_bf16 v[28:31], v[132:135], v[216:219], v[28:31]
	v_mfma_f32_16x16x32_bf16 v[24:27], v[140:143], v[216:219], v[24:27]
	v_mfma_f32_16x16x32_bf16 v[12:15], v[132:135], v[236:239], v[12:15]
	v_mfma_f32_16x16x32_bf16 v[8:11], v[140:143], v[236:239], v[8:11]
	s_setprio 0
	s_setprio 1
	v_mfma_f32_16x16x32_bf16 v[52:55], v[144:147], v[172:175], v[52:55]
	v_mfma_f32_16x16x32_bf16 v[48:51], v[164:167], v[172:175], v[48:51]
	v_mfma_f32_16x16x32_bf16 v[36:39], v[144:147], v[180:183], v[36:39]
	v_mfma_f32_16x16x32_bf16 v[32:35], v[164:167], v[180:183], v[32:35]
	v_mfma_f32_16x16x32_bf16 v[20:23], v[144:147], v[212:215], v[20:23]
	v_mfma_f32_16x16x32_bf16 v[16:19], v[164:167], v[212:215], v[16:19]
	v_mfma_f32_16x16x32_bf16 v[4:7], v[144:147], v[232:235], v[4:7]
	v_mfma_f32_16x16x32_bf16 v[0:3], v[164:167], v[232:235], v[0:3]
	v_mfma_f32_16x16x32_bf16 v[52:55], v[148:151], v[176:179], v[52:55]
	v_mfma_f32_16x16x32_bf16 v[48:51], v[168:171], v[176:179], v[48:51]
	v_mfma_f32_16x16x32_bf16 v[36:39], v[148:151], v[186:189], v[36:39]
	v_mfma_f32_16x16x32_bf16 v[32:35], v[168:171], v[186:189], v[32:35]
	v_mfma_f32_16x16x32_bf16 v[20:23], v[148:151], v[216:219], v[20:23]
	v_mfma_f32_16x16x32_bf16 v[16:19], v[168:171], v[216:219], v[16:19]
	v_mfma_f32_16x16x32_bf16 v[4:7], v[148:151], v[236:239], v[4:7]
	v_mfma_f32_16x16x32_bf16 v[0:3], v[168:171], v[236:239], v[0:3]
	s_setprio 0
	s_barrier
	s_cbranch_scc0 .LBB0_485
	s_and_b64 vcc, exec, s[12:13]
	s_cbranch_vccz .LBB0_488
	s_barrier
